# v12 + MFMA order inside each 32-MFMA block changed so the two k-steps of one accumulator issue back-to-back (accumulate chain forwarding, same per-accumulator order, bit-identical sums)
# speedup vs baseline: 1.0138x; 1.0079x over previous
; #define PG8_STAGE(bufoff, gbase, voff) do { _Pragma("unroll") for (int _i = 0; _i < 2; ++_i) \
;         __builtin_amdgcn_global_load_lds((const unsigned*)((const char*)(gbase) + (voff)[_i]), (PG8_LAS unsigned*)(lds + (bufoff) + ldsw + _i * 8192), 16, 0, 0); } while (0)
; #define PG8_LDA(dst, b, h) do { _Pragma("unroll") for (int m = 0; m < 4; ++m) _Pragma("unroll") for (int k = 0; k < 2; ++k) dst[m][k] = *(const PG8_LAS bf16x8*)(lds + PG8_SA(b, h) + aoff + m * 2048 + k * 1024); } while (0)
; #define PG8_LDB(dst, b, h) do { _Pragma("unroll") for (int n = 0; n < 2; ++n) _Pragma("unroll") for (int k = 0; k < 2; ++k) dst[n][k] = *(const PG8_LAS bf16x8*)(lds + PG8_SB(b, h) + boff + n * 2048 + k * 1024); } while (0)
; #define PG8_MMA(ai, bj, At, Bt) do { __builtin_amdgcn_s_setprio(1); _Pragma("unroll") for (int m = 0; m < 4; ++m) _Pragma("unroll") for (int n = 0; n < 2; ++n) _Pragma("unroll") for (int k = 0; k < 2; ++k) \
;         acc[ai][bj][m][n] = __builtin_amdgcn_mfma_f32_16x16x32_bf16(Bt[n][k], At[m][k], acc[ai][bj][m][n], 0, 0, 0); __builtin_amdgcn_s_setprio(0); } while (0)
; #define PG8_WAIT_V(n) asm volatile("s_waitcnt vmcnt(" #n ")" ::: "memory")
; #define PG8_WAIT_L(n) asm volatile("s_waitcnt lgkmcnt(" #n ")" ::: "memory")
; #define PG8_BAR __builtin_amdgcn_s_barrier()
; #define PG8_SCHED __builtin_amdgcn_sched_barrier(0)
; template <class Epi, class Sched, bool ALIGN_EPI = false, bool SP2 = false>
; __device__ __forceinline__ void gemm_phase(PG8_LAS unsigned char* lds, const Gemm g, const Sched& S, const Epi& E) {
;     ...
;             if constexpr (SP2) {
;             PG8_LDB(B0, 0, 0); PG8_LDB(B1, 0, 1); PG8_SCHED; PG8_LDA(At, 0, 0); PG8_STAGE(PG8_SA(1, 1), a1 + hstep, voffA);
;             PG8_WAIT_V(8); PG8_WAIT_L(0); PG8_BAR; PG8_MMA(0, 0, At, B0); PG8_MMA(0, 1, At, B1); PG8_BAR; PG8_SCHED;
;             PG8_LDA(At, 0, 1); PG8_STAGE(PG8_SB(0, 0), b2, voffB); PG8_STAGE(PG8_SB(0, 1), b2 + hstep, voffB); PG8_STAGE(PG8_SA(0, 0), a2, voffA);
;             PG8_WAIT_V(8); PG8_WAIT_L(0); PG8_BAR; PG8_MMA(1, 0, At, B0); PG8_MMA(1, 1, At, B1); PG8_BAR; PG8_SCHED;
.LBB0_673:
	ds_read_b128 v[148:151], v241 offset:0
	ds_read_b128 v[156:159], v241 offset:1024
	ds_read_b128 v[166:169], v241 offset:2048
	ds_read_b128 v[170:173], v241 offset:3072
	ds_read_b128 v[174:177], v241 offset:16384
	ds_read_b128 v[178:181], v241 offset:17408
	ds_read_b128 v[182:185], v241 offset:18432
	ds_read_b128 v[186:189], v241 offset:19456
	s_add_u32 s20, s22, 0xfff00080
	s_addc_u32 s21, s23, -1
	s_cmp_eq_u32 s35, 60
	s_cselect_b32 s25, s11, s21
	s_cselect_b32 s24, s52, s20
	s_cselect_b32 s21, s13, s34
	s_cselect_b32 s20, s53, s62
	s_add_i32 m0, s19, 0xc000
	ds_read_b128 v[190:193], v161
	ds_read_b128 v[194:197], v161 offset:1024
	ds_read_b128 v[198:201], v161 offset:2048
	ds_read_b128 v[202:205], v161 offset:3072
	ds_read_b128 v[206:209], v161 offset:4096
	ds_read_b128 v[210:213], v161 offset:5120
	ds_read_b128 v[214:217], v161 offset:6144
	ds_read_b128 v[218:221], v161 offset:7168
	global_load_lds_dwordx4 v138, s[22:23]
	s_add_i32 m0, s19, 0xe000
	s_nop 0
	global_load_lds_dwordx4 v140, s[22:23]
	s_waitcnt vmcnt(8)
	s_waitcnt lgkmcnt(0)
	s_barrier
	s_waitcnt lgkmcnt(0)
	v_mfma_f32_16x16x32_bf16 v[118:121], v[148:151], v[190:193], v[118:121]
	v_mfma_f32_16x16x32_bf16 v[118:121], v[156:159], v[194:197], v[118:121]
	v_mfma_f32_16x16x32_bf16 v[114:117], v[166:169], v[190:193], v[114:117]
	v_mfma_f32_16x16x32_bf16 v[114:117], v[170:173], v[194:197], v[114:117]
	v_mfma_f32_16x16x32_bf16 v[102:105], v[148:151], v[198:201], v[102:105]
	v_mfma_f32_16x16x32_bf16 v[102:105], v[156:159], v[202:205], v[102:105]
	v_mfma_f32_16x16x32_bf16 v[98:101], v[166:169], v[198:201], v[98:101]
	v_mfma_f32_16x16x32_bf16 v[98:101], v[170:173], v[202:205], v[98:101]
	v_mfma_f32_16x16x32_bf16 v[86:89], v[148:151], v[206:209], v[86:89]
	v_mfma_f32_16x16x32_bf16 v[86:89], v[156:159], v[210:213], v[86:89]
	v_mfma_f32_16x16x32_bf16 v[82:85], v[166:169], v[206:209], v[82:85]
	v_mfma_f32_16x16x32_bf16 v[82:85], v[170:173], v[210:213], v[82:85]
	v_mfma_f32_16x16x32_bf16 v[70:73], v[148:151], v[214:217], v[70:73]
	v_mfma_f32_16x16x32_bf16 v[70:73], v[156:159], v[218:221], v[70:73]
	v_mfma_f32_16x16x32_bf16 v[66:69], v[166:169], v[214:217], v[66:69]
	v_mfma_f32_16x16x32_bf16 v[66:69], v[170:173], v[218:221], v[66:69]
	v_mfma_f32_16x16x32_bf16 v[126:129], v[174:177], v[190:193], v[126:129]
	v_mfma_f32_16x16x32_bf16 v[126:129], v[178:181], v[194:197], v[126:129]
	v_mfma_f32_16x16x32_bf16 v[122:125], v[182:185], v[190:193], v[122:125]
	v_mfma_f32_16x16x32_bf16 v[122:125], v[186:189], v[194:197], v[122:125]
	v_mfma_f32_16x16x32_bf16 v[110:113], v[174:177], v[198:201], v[110:113]
	v_mfma_f32_16x16x32_bf16 v[110:113], v[178:181], v[202:205], v[110:113]
	v_mfma_f32_16x16x32_bf16 v[106:109], v[182:185], v[198:201], v[106:109]
	v_mfma_f32_16x16x32_bf16 v[106:109], v[186:189], v[202:205], v[106:109]
	v_mfma_f32_16x16x32_bf16 v[94:97], v[174:177], v[206:209], v[94:97]
	v_mfma_f32_16x16x32_bf16 v[94:97], v[178:181], v[210:213], v[94:97]
	v_mfma_f32_16x16x32_bf16 v[90:93], v[182:185], v[206:209], v[90:93]
	v_mfma_f32_16x16x32_bf16 v[90:93], v[186:189], v[210:213], v[90:93]
	v_mfma_f32_16x16x32_bf16 v[78:81], v[174:177], v[214:217], v[78:81]
	v_mfma_f32_16x16x32_bf16 v[78:81], v[178:181], v[218:221], v[78:81]
	v_mfma_f32_16x16x32_bf16 v[74:77], v[182:185], v[214:217], v[74:77]
	v_mfma_f32_16x16x32_bf16 v[74:77], v[186:189], v[218:221], v[74:77]
	s_barrier
	s_add_i32 s63, s43, s26
	s_mov_b32 m0, s63
	ds_read_b128 v[190:193], v161 offset:16384
	ds_read_b128 v[194:197], v161 offset:17408
	ds_read_b128 v[198:201], v161 offset:18432
	ds_read_b128 v[202:205], v161 offset:19456
	ds_read_b128 v[206:209], v161 offset:20480
	ds_read_b128 v[210:213], v161 offset:21504
	ds_read_b128 v[214:217], v161 offset:22528
	ds_read_b128 v[218:221], v161 offset:23552
	global_load_lds_dwordx4 v132, s[20:21]
	s_add_i32 m0, s63, 0x2000
	s_add_u32 s64, s20, 0x100000
	s_addc_u32 s65, s21, 0
	s_add_i32 s63, s46, s26
	global_load_lds_dwordx4 v136, s[20:21]
	s_mov_b32 m0, s63
	s_add_u32 s100, s24, 0x80
	s_addc_u32 s101, s25, 0
	global_load_lds_dwordx4 v132, s[64:65]
	s_add_i32 m0, s63, 0x2000
	s_nop 0
	global_load_lds_dwordx4 v136, s[64:65]
	s_mov_b32 m0, s19
	s_nop 0
	global_load_lds_dwordx4 v130, s[24:25]
	s_mov_b32 m0, s29
	s_nop 0
	global_load_lds_dwordx4 v134, s[24:25]
	s_waitcnt vmcnt(8)
	s_waitcnt lgkmcnt(0)
	s_barrier
	s_waitcnt lgkmcnt(0)
	v_mfma_f32_16x16x32_bf16 v[54:57], v[148:151], v[190:193], v[54:57]
	v_mfma_f32_16x16x32_bf16 v[54:57], v[156:159], v[194:197], v[54:57]
	v_mfma_f32_16x16x32_bf16 v[50:53], v[166:169], v[190:193], v[50:53]
	v_mfma_f32_16x16x32_bf16 v[50:53], v[170:173], v[194:197], v[50:53]
	v_mfma_f32_16x16x32_bf16 v[38:41], v[148:151], v[198:201], v[38:41]
	v_mfma_f32_16x16x32_bf16 v[38:41], v[156:159], v[202:205], v[38:41]
	v_mfma_f32_16x16x32_bf16 v[34:37], v[166:169], v[198:201], v[34:37]
	v_mfma_f32_16x16x32_bf16 v[34:37], v[170:173], v[202:205], v[34:37]
	v_mfma_f32_16x16x32_bf16 v[22:25], v[148:151], v[206:209], v[22:25]
	v_mfma_f32_16x16x32_bf16 v[22:25], v[156:159], v[210:213], v[22:25]
	v_mfma_f32_16x16x32_bf16 v[18:21], v[166:169], v[206:209], v[18:21]
	v_mfma_f32_16x16x32_bf16 v[18:21], v[170:173], v[210:213], v[18:21]
	v_mfma_f32_16x16x32_bf16 v[6:9], v[148:151], v[214:217], v[6:9]
	v_mfma_f32_16x16x32_bf16 v[6:9], v[156:159], v[218:221], v[6:9]
	v_mfma_f32_16x16x32_bf16 v[2:5], v[166:169], v[214:217], v[2:5]
	v_mfma_f32_16x16x32_bf16 v[2:5], v[170:173], v[218:221], v[2:5]
	v_mfma_f32_16x16x32_bf16 v[62:65], v[174:177], v[190:193], v[62:65]
	v_mfma_f32_16x16x32_bf16 v[62:65], v[178:181], v[194:197], v[62:65]
	v_mfma_f32_16x16x32_bf16 v[58:61], v[182:185], v[190:193], v[58:61]
	v_mfma_f32_16x16x32_bf16 v[58:61], v[186:189], v[194:197], v[58:61]
	v_mfma_f32_16x16x32_bf16 v[46:49], v[174:177], v[198:201], v[46:49]
	v_mfma_f32_16x16x32_bf16 v[46:49], v[178:181], v[202:205], v[46:49]
	v_mfma_f32_16x16x32_bf16 v[42:45], v[182:185], v[198:201], v[42:45]
	v_mfma_f32_16x16x32_bf16 v[42:45], v[186:189], v[202:205], v[42:45]
	v_mfma_f32_16x16x32_bf16 v[30:33], v[174:177], v[206:209], v[30:33]
	v_mfma_f32_16x16x32_bf16 v[30:33], v[178:181], v[210:213], v[30:33]
	v_mfma_f32_16x16x32_bf16 v[26:29], v[182:185], v[206:209], v[26:29]
	v_mfma_f32_16x16x32_bf16 v[26:29], v[186:189], v[210:213], v[26:29]
	v_mfma_f32_16x16x32_bf16 v[10:13], v[174:177], v[214:217], v[10:13]
	v_mfma_f32_16x16x32_bf16 v[10:13], v[178:181], v[218:221], v[10:13]
	v_mfma_f32_16x16x32_bf16 v[14:17], v[182:185], v[214:217], v[14:17]
	v_mfma_f32_16x16x32_bf16 v[14:17], v[186:189], v[218:221], v[14:17]
	s_barrier
; #define PG8_STAGE(bufoff, gbase, voff) do { _Pragma("unroll") for (int _i = 0; _i < 2; ++_i) \
;         __builtin_amdgcn_global_load_lds((const unsigned*)((const char*)(gbase) + (voff)[_i]), (PG8_LAS unsigned*)(lds + (bufoff) + ldsw + _i * 8192), 16, 0, 0); } while (0)
; #define PG8_LDA(dst, b, h) do { _Pragma("unroll") for (int m = 0; m < 4; ++m) _Pragma("unroll") for (int k = 0; k < 2; ++k) dst[m][k] = *(const PG8_LAS bf16x8*)(lds + PG8_SA(b, h) + aoff + m * 2048 + k * 1024); } while (0)
; #define PG8_LDB(dst, b, h) do { _Pragma("unroll") for (int n = 0; n < 2; ++n) _Pragma("unroll") for (int k = 0; k < 2; ++k) dst[n][k] = *(const PG8_LAS bf16x8*)(lds + PG8_SB(b, h) + boff + n * 2048 + k * 1024); } while (0)
; template <class Epi, class Sched, bool ALIGN_EPI = false, bool SP2 = false>
; __device__ __forceinline__ void gemm_phase(PG8_LAS unsigned char* lds, const Gemm g, const Sched& S, const Epi& E) {
;     ...
;         for (int t = 0; t < nt; t += 2) {
;             const bool last = (t == nt - 2);
;             const char* a1 = cA + (size_t)(t + 1) * kstep;
;             const char* a2 = last ? nA : cA + (size_t)(t + 2) * kstep; const char* b2 = last ? nB : cB + (size_t)(t + 2) * kstep;
;             const char* a3 = a2 + kstep; const char* b3 = b2 + kstep;
;             if (last && has_next) S.a_ready(nxt);
;             if constexpr (SP2) {
;             PG8_LDB(B0, 0, 0); PG8_LDB(B1, 0, 1); PG8_SCHED; PG8_LDA(At, 0, 0); PG8_STAGE(PG8_SA(1, 1), a1 + hstep, voffA);
;             PG8_WAIT_V(8); PG8_WAIT_L(0); PG8_BAR; PG8_MMA(0, 0, At, B0); PG8_MMA(0, 1, At, B1); PG8_BAR; PG8_SCHED;
;             PG8_LDA(At, 0, 1); PG8_STAGE(PG8_SB(0, 0), b2, voffB); PG8_STAGE(PG8_SB(0, 1), b2 + hstep, voffB); PG8_STAGE(PG8_SA(0, 0), a2, voffA);
;             PG8_WAIT_V(8); PG8_WAIT_L(0); PG8_BAR; PG8_MMA(1, 0, At, B0); PG8_MMA(1, 1, At, B1); PG8_BAR; PG8_SCHED;
;             PG8_LDB(B0, 1, 0); PG8_LDB(B1, 1, 1); PG8_SCHED; PG8_LDA(At, 1, 0); PG8_STAGE(PG8_SA(0, 1), a2 + hstep, voffA);
;             PG8_WAIT_V(8); PG8_WAIT_L(0); PG8_BAR; PG8_MMA(0, 0, At, B0); PG8_MMA(0, 1, At, B1); PG8_BAR; PG8_SCHED;
;             PG8_LDA(At, 1, 1); PG8_STAGE(PG8_SB(1, 0), b3, voffB); PG8_STAGE(PG8_SB(1, 1), b3 + hstep, voffB); PG8_STAGE(PG8_SA(1, 0), a3, voffA);
;             PG8_WAIT_V(8); PG8_WAIT_L(0); PG8_BAR; PG8_MMA(1, 0, At, B0); PG8_MMA(1, 1, At, B1); PG8_BAR; PG8_SCHED;
	s_add_i32 s63, 0, 0x18000
	s_add_i32 s64, 0, 0x1c000
	ds_read_b128 v[148:151], v241 offset:32768
	ds_read_b128 v[156:159], v241 offset:33792
	ds_read_b128 v[166:169], v241 offset:34816
	ds_read_b128 v[170:173], v241 offset:35840
	ds_read_b128 v[174:177], v241 offset:49152
	ds_read_b128 v[178:181], v241 offset:50176
	ds_read_b128 v[182:185], v241 offset:51200
	ds_read_b128 v[186:189], v241 offset:52224
	s_add_u32 s24, s24, 0x100000
	s_addc_u32 s25, s25, 0
	s_mov_b32 m0, s30
	ds_read_b128 v[190:193], v161 offset:32768
	ds_read_b128 v[194:197], v161 offset:33792
	ds_read_b128 v[198:201], v161 offset:34816
	ds_read_b128 v[202:205], v161 offset:35840
	ds_read_b128 v[206:209], v161 offset:36864
	ds_read_b128 v[210:213], v161 offset:37888
	ds_read_b128 v[214:217], v161 offset:38912
	ds_read_b128 v[218:221], v161 offset:39936
	global_load_lds_dwordx4 v130, s[24:25]
	s_mov_b32 m0, s31
	s_nop 0
	global_load_lds_dwordx4 v134, s[24:25]
	s_waitcnt vmcnt(8)
	s_waitcnt lgkmcnt(0)
	s_barrier
	s_waitcnt lgkmcnt(0)
	v_mfma_f32_16x16x32_bf16 v[118:121], v[148:151], v[190:193], v[118:121]
	v_mfma_f32_16x16x32_bf16 v[118:121], v[156:159], v[194:197], v[118:121]
	v_mfma_f32_16x16x32_bf16 v[114:117], v[166:169], v[190:193], v[114:117]
	v_mfma_f32_16x16x32_bf16 v[114:117], v[170:173], v[194:197], v[114:117]
	v_mfma_f32_16x16x32_bf16 v[102:105], v[148:151], v[198:201], v[102:105]
	v_mfma_f32_16x16x32_bf16 v[102:105], v[156:159], v[202:205], v[102:105]
	v_mfma_f32_16x16x32_bf16 v[98:101], v[166:169], v[198:201], v[98:101]
	v_mfma_f32_16x16x32_bf16 v[98:101], v[170:173], v[202:205], v[98:101]
	v_mfma_f32_16x16x32_bf16 v[86:89], v[148:151], v[206:209], v[86:89]
	v_mfma_f32_16x16x32_bf16 v[86:89], v[156:159], v[210:213], v[86:89]
	v_mfma_f32_16x16x32_bf16 v[82:85], v[166:169], v[206:209], v[82:85]
	v_mfma_f32_16x16x32_bf16 v[82:85], v[170:173], v[210:213], v[82:85]
	v_mfma_f32_16x16x32_bf16 v[70:73], v[148:151], v[214:217], v[70:73]
	v_mfma_f32_16x16x32_bf16 v[70:73], v[156:159], v[218:221], v[70:73]
	v_mfma_f32_16x16x32_bf16 v[66:69], v[166:169], v[214:217], v[66:69]
	v_mfma_f32_16x16x32_bf16 v[66:69], v[170:173], v[218:221], v[66:69]
	v_mfma_f32_16x16x32_bf16 v[126:129], v[174:177], v[190:193], v[126:129]
	v_mfma_f32_16x16x32_bf16 v[126:129], v[178:181], v[194:197], v[126:129]
	v_mfma_f32_16x16x32_bf16 v[122:125], v[182:185], v[190:193], v[122:125]
	v_mfma_f32_16x16x32_bf16 v[122:125], v[186:189], v[194:197], v[122:125]
	v_mfma_f32_16x16x32_bf16 v[110:113], v[174:177], v[198:201], v[110:113]
	v_mfma_f32_16x16x32_bf16 v[110:113], v[178:181], v[202:205], v[110:113]
	v_mfma_f32_16x16x32_bf16 v[106:109], v[182:185], v[198:201], v[106:109]
	v_mfma_f32_16x16x32_bf16 v[106:109], v[186:189], v[202:205], v[106:109]
	v_mfma_f32_16x16x32_bf16 v[94:97], v[174:177], v[206:209], v[94:97]
	v_mfma_f32_16x16x32_bf16 v[94:97], v[178:181], v[210:213], v[94:97]
	v_mfma_f32_16x16x32_bf16 v[90:93], v[182:185], v[206:209], v[90:93]
	v_mfma_f32_16x16x32_bf16 v[90:93], v[186:189], v[210:213], v[90:93]
	v_mfma_f32_16x16x32_bf16 v[78:81], v[174:177], v[214:217], v[78:81]
	v_mfma_f32_16x16x32_bf16 v[78:81], v[178:181], v[218:221], v[78:81]
	v_mfma_f32_16x16x32_bf16 v[74:77], v[182:185], v[214:217], v[74:77]
	v_mfma_f32_16x16x32_bf16 v[74:77], v[186:189], v[218:221], v[74:77]
	s_barrier
	s_add_i32 s24, s63, s26
	s_add_i32 m0, s24, 0xffffff80
	ds_read_b128 v[190:193], v161 offset:49152
	ds_read_b128 v[194:197], v161 offset:50176
	ds_read_b128 v[198:201], v161 offset:51200
	ds_read_b128 v[202:205], v161 offset:52224
	ds_read_b128 v[206:209], v161 offset:53248
	ds_read_b128 v[210:213], v161 offset:54272
	ds_read_b128 v[214:217], v161 offset:55296
	ds_read_b128 v[218:221], v161 offset:56320
	global_load_lds_dwordx4 v132, s[20:21] offset:128
	s_add_i32 m0, s24, 0x1f80
	s_add_i32 s24, s64, s26
	global_load_lds_dwordx4 v136, s[20:21] offset:128
	s_add_u32 s20, s20, 0x100080
	s_addc_u32 s21, s21, 0
	s_mov_b32 m0, s24
	s_nop 0
	global_load_lds_dwordx4 v132, s[20:21]
	s_add_i32 m0, s24, 0x2000
	s_nop 0
	global_load_lds_dwordx4 v136, s[20:21]
	s_mov_b32 m0, s40
	s_nop 0
	global_load_lds_dwordx4 v130, s[100:101]
	s_mov_b32 m0, s41
	s_nop 0
	global_load_lds_dwordx4 v134, s[100:101]
	s_waitcnt vmcnt(8)
	s_waitcnt lgkmcnt(0)
	s_barrier
	s_waitcnt lgkmcnt(0)
	v_mfma_f32_16x16x32_bf16 v[54:57], v[148:151], v[190:193], v[54:57]
	v_mfma_f32_16x16x32_bf16 v[54:57], v[156:159], v[194:197], v[54:57]
	v_mfma_f32_16x16x32_bf16 v[50:53], v[166:169], v[190:193], v[50:53]
	v_mfma_f32_16x16x32_bf16 v[50:53], v[170:173], v[194:197], v[50:53]
	v_mfma_f32_16x16x32_bf16 v[38:41], v[148:151], v[198:201], v[38:41]
	v_mfma_f32_16x16x32_bf16 v[38:41], v[156:159], v[202:205], v[38:41]
	v_mfma_f32_16x16x32_bf16 v[34:37], v[166:169], v[198:201], v[34:37]
	v_mfma_f32_16x16x32_bf16 v[34:37], v[170:173], v[202:205], v[34:37]
	v_mfma_f32_16x16x32_bf16 v[22:25], v[148:151], v[206:209], v[22:25]
	v_mfma_f32_16x16x32_bf16 v[22:25], v[156:159], v[210:213], v[22:25]
	v_mfma_f32_16x16x32_bf16 v[18:21], v[166:169], v[206:209], v[18:21]
	v_mfma_f32_16x16x32_bf16 v[18:21], v[170:173], v[210:213], v[18:21]
	v_mfma_f32_16x16x32_bf16 v[6:9], v[148:151], v[214:217], v[6:9]
	v_mfma_f32_16x16x32_bf16 v[6:9], v[156:159], v[218:221], v[6:9]
	v_mfma_f32_16x16x32_bf16 v[2:5], v[166:169], v[214:217], v[2:5]
	v_mfma_f32_16x16x32_bf16 v[2:5], v[170:173], v[218:221], v[2:5]
	v_mfma_f32_16x16x32_bf16 v[62:65], v[174:177], v[190:193], v[62:65]
	v_mfma_f32_16x16x32_bf16 v[62:65], v[178:181], v[194:197], v[62:65]
	v_mfma_f32_16x16x32_bf16 v[58:61], v[182:185], v[190:193], v[58:61]
	v_mfma_f32_16x16x32_bf16 v[58:61], v[186:189], v[194:197], v[58:61]
	v_mfma_f32_16x16x32_bf16 v[46:49], v[174:177], v[198:201], v[46:49]
	v_mfma_f32_16x16x32_bf16 v[46:49], v[178:181], v[202:205], v[46:49]
	v_mfma_f32_16x16x32_bf16 v[42:45], v[182:185], v[198:201], v[42:45]
	v_mfma_f32_16x16x32_bf16 v[42:45], v[186:189], v[202:205], v[42:45]
	v_mfma_f32_16x16x32_bf16 v[30:33], v[174:177], v[206:209], v[30:33]
	v_mfma_f32_16x16x32_bf16 v[30:33], v[178:181], v[210:213], v[30:33]
	v_mfma_f32_16x16x32_bf16 v[26:29], v[182:185], v[206:209], v[26:29]
	v_mfma_f32_16x16x32_bf16 v[26:29], v[186:189], v[210:213], v[26:29]
	v_mfma_f32_16x16x32_bf16 v[10:13], v[174:177], v[214:217], v[10:13]
	v_mfma_f32_16x16x32_bf16 v[10:13], v[178:181], v[218:221], v[10:13]
	v_mfma_f32_16x16x32_bf16 v[14:17], v[182:185], v[214:217], v[14:17]
	v_mfma_f32_16x16x32_bf16 v[14:17], v[186:189], v[218:221], v[14:17]
	s_barrier
	s_add_i32 s35, s35, 2
	s_add_u32 s22, s22, 0x100
	s_addc_u32 s23, s23, 0
	s_add_u32 s62, s62, 0x100
	s_addc_u32 s34, s34, 0
	s_cmp_gt_u32 s35, 61
	s_cbranch_scc0 .LBB0_673
	s_and_b64 vcc, exec, s[8:9]
	s_cbranch_vccz .LBB0_676
	s_barrier

; #define PG8_STAGE(bufoff, gbase, voff) do { _Pragma("unroll") for (int _i = 0; _i < 2; ++_i) \
;         __builtin_amdgcn_global_load_lds((const unsigned*)((const char*)(gbase) + (voff)[_i]), (PG8_LAS unsigned*)(lds + (bufoff) + ldsw + _i * 8192), 16, 0, 0); } while (0)
; #define PG8_LDA(dst, b, h) do { _Pragma("unroll") for (int m = 0; m < 4; ++m) _Pragma("unroll") for (int k = 0; k < 2; ++k) dst[m][k] = *(const PG8_LAS bf16x8*)(lds + PG8_SA(b, h) + aoff + m * 2048 + k * 1024); } while (0)
; #define PG8_LDB(dst, b, h) do { _Pragma("unroll") for (int n = 0; n < 2; ++n) _Pragma("unroll") for (int k = 0; k < 2; ++k) dst[n][k] = *(const PG8_LAS bf16x8*)(lds + PG8_SB(b, h) + boff + n * 2048 + k * 1024); } while (0)
; #define PG8_MMA(ai, bj, At, Bt) do { __builtin_amdgcn_s_setprio(1); _Pragma("unroll") for (int m = 0; m < 4; ++m) _Pragma("unroll") for (int n = 0; n < 2; ++n) _Pragma("unroll") for (int k = 0; k < 2; ++k) \
;         acc[ai][bj][m][n] = __builtin_amdgcn_mfma_f32_16x16x32_bf16(Bt[n][k], At[m][k], acc[ai][bj][m][n], 0, 0, 0); __builtin_amdgcn_s_setprio(0); } while (0)
; #define PG8_WAIT_V(n) asm volatile("s_waitcnt vmcnt(" #n ")" ::: "memory")
; #define PG8_WAIT_L(n) asm volatile("s_waitcnt lgkmcnt(" #n ")" ::: "memory")
; #define PG8_BAR __builtin_amdgcn_s_barrier()
; #define PG8_SCHED __builtin_amdgcn_sched_barrier(0)
; template <class Epi, class Sched, bool ALIGN_EPI = false, bool SP2 = false>
; __device__ __forceinline__ void gemm_phase(PG8_LAS unsigned char* lds, const Gemm g, const Sched& S, const Epi& E) {
;     ...
;             if constexpr (SP2) {
;             PG8_LDB(B0, 0, 0); PG8_LDB(B1, 0, 1); PG8_SCHED; PG8_LDA(At, 0, 0); PG8_STAGE(PG8_SA(1, 1), a1 + hstep, voffA);
;             PG8_WAIT_V(8); PG8_WAIT_L(0); PG8_BAR; PG8_MMA(0, 0, At, B0); PG8_MMA(0, 1, At, B1); PG8_BAR; PG8_SCHED;
;             PG8_LDA(At, 0, 1); PG8_STAGE(PG8_SB(0, 0), b2, voffB); PG8_STAGE(PG8_SB(0, 1), b2 + hstep, voffB); PG8_STAGE(PG8_SA(0, 0), a2, voffA);
;             PG8_WAIT_V(8); PG8_WAIT_L(0); PG8_BAR; PG8_MMA(1, 0, At, B0); PG8_MMA(1, 1, At, B1); PG8_BAR; PG8_SCHED;
.LBB0_1039:
	ds_read_b128 v[130:133], v241 offset:0
	ds_read_b128 v[134:137], v241 offset:1024
	ds_read_b128 v[138:141], v241 offset:2048
	ds_read_b128 v[142:145], v241 offset:3072
	ds_read_b128 v[146:149], v241 offset:16384
	ds_read_b128 v[150:153], v241 offset:17408
	ds_read_b128 v[172:175], v241 offset:18432
	ds_read_b128 v[176:179], v241 offset:19456
	s_add_u32 s24, s26, 0xfff00080
	s_addc_u32 s25, s27, -1
	s_cmp_eq_u32 s68, 60
	s_cselect_b32 s29, s15, s25
	s_cselect_b32 s28, s21, s24
	s_cselect_b32 s25, s13, s67
	s_cselect_b32 s24, s65, s66
	s_add_i32 m0, s23, 0xc000
	ds_read_b128 v[180:183], v185
	ds_read_b128 v[188:191], v185 offset:1024
	ds_read_b128 v[192:195], v185 offset:2048
	ds_read_b128 v[196:199], v185 offset:3072
	ds_read_b128 v[200:203], v185 offset:4096
	ds_read_b128 v[204:207], v185 offset:5120
	ds_read_b128 v[208:211], v185 offset:6144
	ds_read_b128 v[212:215], v185 offset:7168
	global_load_lds_dwordx4 v162, s[26:27]
	s_add_i32 m0, s23, 0xe000
	s_nop 0
	global_load_lds_dwordx4 v166, s[26:27]
	s_waitcnt vmcnt(8)
	s_waitcnt lgkmcnt(0)
	s_barrier
	s_waitcnt lgkmcnt(0)
	v_mfma_f32_16x16x32_bf16 v[114:117], v[130:133], v[180:183], v[114:117]
	v_mfma_f32_16x16x32_bf16 v[114:117], v[134:137], v[188:191], v[114:117]
	v_mfma_f32_16x16x32_bf16 v[118:121], v[138:141], v[180:183], v[118:121]
	v_mfma_f32_16x16x32_bf16 v[118:121], v[142:145], v[188:191], v[118:121]
	v_mfma_f32_16x16x32_bf16 v[106:109], v[130:133], v[192:195], v[106:109]
	v_mfma_f32_16x16x32_bf16 v[106:109], v[134:137], v[196:199], v[106:109]
	v_mfma_f32_16x16x32_bf16 v[98:101], v[138:141], v[192:195], v[98:101]
	v_mfma_f32_16x16x32_bf16 v[98:101], v[142:145], v[196:199], v[98:101]
	v_mfma_f32_16x16x32_bf16 v[90:93], v[130:133], v[200:203], v[90:93]
	v_mfma_f32_16x16x32_bf16 v[90:93], v[134:137], v[204:207], v[90:93]
	v_mfma_f32_16x16x32_bf16 v[82:85], v[138:141], v[200:203], v[82:85]
	v_mfma_f32_16x16x32_bf16 v[82:85], v[142:145], v[204:207], v[82:85]
	v_mfma_f32_16x16x32_bf16 v[74:77], v[130:133], v[208:211], v[74:77]
	v_mfma_f32_16x16x32_bf16 v[74:77], v[134:137], v[212:215], v[74:77]
	v_mfma_f32_16x16x32_bf16 v[66:69], v[138:141], v[208:211], v[66:69]
	v_mfma_f32_16x16x32_bf16 v[66:69], v[142:145], v[212:215], v[66:69]
	v_mfma_f32_16x16x32_bf16 v[122:125], v[146:149], v[180:183], v[122:125]
	v_mfma_f32_16x16x32_bf16 v[122:125], v[150:153], v[188:191], v[122:125]
	v_mfma_f32_16x16x32_bf16 v[126:129], v[172:175], v[180:183], v[126:129]
	v_mfma_f32_16x16x32_bf16 v[126:129], v[176:179], v[188:191], v[126:129]
	v_mfma_f32_16x16x32_bf16 v[110:113], v[146:149], v[192:195], v[110:113]
	v_mfma_f32_16x16x32_bf16 v[110:113], v[150:153], v[196:199], v[110:113]
	v_mfma_f32_16x16x32_bf16 v[102:105], v[172:175], v[192:195], v[102:105]
	v_mfma_f32_16x16x32_bf16 v[102:105], v[176:179], v[196:199], v[102:105]
	v_mfma_f32_16x16x32_bf16 v[94:97], v[146:149], v[200:203], v[94:97]
	v_mfma_f32_16x16x32_bf16 v[94:97], v[150:153], v[204:207], v[94:97]
	v_mfma_f32_16x16x32_bf16 v[86:89], v[172:175], v[200:203], v[86:89]
	v_mfma_f32_16x16x32_bf16 v[86:89], v[176:179], v[204:207], v[86:89]
	v_mfma_f32_16x16x32_bf16 v[78:81], v[146:149], v[208:211], v[78:81]
	v_mfma_f32_16x16x32_bf16 v[78:81], v[150:153], v[212:215], v[78:81]
	v_mfma_f32_16x16x32_bf16 v[70:73], v[172:175], v[208:211], v[70:73]
	v_mfma_f32_16x16x32_bf16 v[70:73], v[176:179], v[212:215], v[70:73]
	s_barrier
	s_add_i32 s33, s62, s36
	s_mov_b32 m0, s33
	ds_read_b128 v[180:183], v185 offset:16384
	ds_read_b128 v[188:191], v185 offset:17408
	ds_read_b128 v[192:195], v185 offset:18432
	ds_read_b128 v[196:199], v185 offset:19456
	ds_read_b128 v[200:203], v185 offset:20480
	ds_read_b128 v[204:207], v185 offset:21504
	ds_read_b128 v[208:211], v185 offset:22528
	ds_read_b128 v[212:215], v185 offset:23552
	global_load_lds_dwordx4 v156, s[24:25]
	s_add_i32 m0, s33, 0x2000
	s_add_u32 s72, s24, 0x100000
	s_addc_u32 s73, s25, 0
	s_add_i32 s33, s63, s36
	global_load_lds_dwordx4 v160, s[24:25]
	s_mov_b32 m0, s33
	s_add_u32 s100, s28, 0x80
	s_addc_u32 s101, s29, 0
	global_load_lds_dwordx4 v156, s[72:73]
	s_add_i32 m0, s33, 0x2000
	s_nop 0
	global_load_lds_dwordx4 v160, s[72:73]
	s_mov_b32 m0, s23
	s_nop 0
	global_load_lds_dwordx4 v154, s[28:29]
	s_mov_b32 m0, s37
	s_nop 0
	global_load_lds_dwordx4 v158, s[28:29]
	s_waitcnt vmcnt(8)
	s_waitcnt lgkmcnt(0)
	s_barrier
	s_waitcnt lgkmcnt(0)
	v_mfma_f32_16x16x32_bf16 v[58:61], v[130:133], v[180:183], v[58:61]
	v_mfma_f32_16x16x32_bf16 v[58:61], v[134:137], v[188:191], v[58:61]
	v_mfma_f32_16x16x32_bf16 v[54:57], v[138:141], v[180:183], v[54:57]
	v_mfma_f32_16x16x32_bf16 v[54:57], v[142:145], v[188:191], v[54:57]
	v_mfma_f32_16x16x32_bf16 v[42:45], v[130:133], v[192:195], v[42:45]
	v_mfma_f32_16x16x32_bf16 v[42:45], v[134:137], v[196:199], v[42:45]
	v_mfma_f32_16x16x32_bf16 v[34:37], v[138:141], v[192:195], v[34:37]
	v_mfma_f32_16x16x32_bf16 v[34:37], v[142:145], v[196:199], v[34:37]
	v_mfma_f32_16x16x32_bf16 v[26:29], v[130:133], v[200:203], v[26:29]
	v_mfma_f32_16x16x32_bf16 v[26:29], v[134:137], v[204:207], v[26:29]
	v_mfma_f32_16x16x32_bf16 v[18:21], v[138:141], v[200:203], v[18:21]
	v_mfma_f32_16x16x32_bf16 v[18:21], v[142:145], v[204:207], v[18:21]
	v_mfma_f32_16x16x32_bf16 v[6:9], v[130:133], v[208:211], v[6:9]
	v_mfma_f32_16x16x32_bf16 v[6:9], v[134:137], v[212:215], v[6:9]
	v_mfma_f32_16x16x32_bf16 v[2:5], v[138:141], v[208:211], v[2:5]
	v_mfma_f32_16x16x32_bf16 v[2:5], v[142:145], v[212:215], v[2:5]
	v_mfma_f32_16x16x32_bf16 v[62:65], v[146:149], v[180:183], v[62:65]
	v_mfma_f32_16x16x32_bf16 v[62:65], v[150:153], v[188:191], v[62:65]
	v_mfma_f32_16x16x32_bf16 v[50:53], v[172:175], v[180:183], v[50:53]
	v_mfma_f32_16x16x32_bf16 v[50:53], v[176:179], v[188:191], v[50:53]
	v_mfma_f32_16x16x32_bf16 v[46:49], v[146:149], v[192:195], v[46:49]
	v_mfma_f32_16x16x32_bf16 v[46:49], v[150:153], v[196:199], v[46:49]
	v_mfma_f32_16x16x32_bf16 v[38:41], v[172:175], v[192:195], v[38:41]
	v_mfma_f32_16x16x32_bf16 v[38:41], v[176:179], v[196:199], v[38:41]
	v_mfma_f32_16x16x32_bf16 v[30:33], v[146:149], v[200:203], v[30:33]
	v_mfma_f32_16x16x32_bf16 v[30:33], v[150:153], v[204:207], v[30:33]
	v_mfma_f32_16x16x32_bf16 v[22:25], v[172:175], v[200:203], v[22:25]
	v_mfma_f32_16x16x32_bf16 v[22:25], v[176:179], v[204:207], v[22:25]
	v_mfma_f32_16x16x32_bf16 v[10:13], v[146:149], v[208:211], v[10:13]
	v_mfma_f32_16x16x32_bf16 v[10:13], v[150:153], v[212:215], v[10:13]
	v_mfma_f32_16x16x32_bf16 v[14:17], v[172:175], v[208:211], v[14:17]
	v_mfma_f32_16x16x32_bf16 v[14:17], v[176:179], v[212:215], v[14:17]
	s_barrier
; #define PG8_STAGE(bufoff, gbase, voff) do { _Pragma("unroll") for (int _i = 0; _i < 2; ++_i) \
;         __builtin_amdgcn_global_load_lds((const unsigned*)((const char*)(gbase) + (voff)[_i]), (PG8_LAS unsigned*)(lds + (bufoff) + ldsw + _i * 8192), 16, 0, 0); } while (0)
; #define PG8_LDA(dst, b, h) do { _Pragma("unroll") for (int m = 0; m < 4; ++m) _Pragma("unroll") for (int k = 0; k < 2; ++k) dst[m][k] = *(const PG8_LAS bf16x8*)(lds + PG8_SA(b, h) + aoff + m * 2048 + k * 1024); } while (0)
; #define PG8_LDB(dst, b, h) do { _Pragma("unroll") for (int n = 0; n < 2; ++n) _Pragma("unroll") for (int k = 0; k < 2; ++k) dst[n][k] = *(const PG8_LAS bf16x8*)(lds + PG8_SB(b, h) + boff + n * 2048 + k * 1024); } while (0)
; template <class Epi, class Sched, bool ALIGN_EPI = false, bool SP2 = false>
; __device__ __forceinline__ void gemm_phase(PG8_LAS unsigned char* lds, const Gemm g, const Sched& S, const Epi& E) {
;     ...
;         for (int t = 0; t < nt; t += 2) {
;             const bool last = (t == nt - 2);
;             const char* a1 = cA + (size_t)(t + 1) * kstep;
;             const char* a2 = last ? nA : cA + (size_t)(t + 2) * kstep; const char* b2 = last ? nB : cB + (size_t)(t + 2) * kstep;
;             const char* a3 = a2 + kstep; const char* b3 = b2 + kstep;
;             if (last && has_next) S.a_ready(nxt);
;             if constexpr (SP2) {
;             PG8_LDB(B0, 0, 0); PG8_LDB(B1, 0, 1); PG8_SCHED; PG8_LDA(At, 0, 0); PG8_STAGE(PG8_SA(1, 1), a1 + hstep, voffA);
;             PG8_WAIT_V(8); PG8_WAIT_L(0); PG8_BAR; PG8_MMA(0, 0, At, B0); PG8_MMA(0, 1, At, B1); PG8_BAR; PG8_SCHED;
;             PG8_LDA(At, 0, 1); PG8_STAGE(PG8_SB(0, 0), b2, voffB); PG8_STAGE(PG8_SB(0, 1), b2 + hstep, voffB); PG8_STAGE(PG8_SA(0, 0), a2, voffA);
;             PG8_WAIT_V(8); PG8_WAIT_L(0); PG8_BAR; PG8_MMA(1, 0, At, B0); PG8_MMA(1, 1, At, B1); PG8_BAR; PG8_SCHED;
;             PG8_LDB(B0, 1, 0); PG8_LDB(B1, 1, 1); PG8_SCHED; PG8_LDA(At, 1, 0); PG8_STAGE(PG8_SA(0, 1), a2 + hstep, voffA);
;             PG8_WAIT_V(8); PG8_WAIT_L(0); PG8_BAR; PG8_MMA(0, 0, At, B0); PG8_MMA(0, 1, At, B1); PG8_BAR; PG8_SCHED;
;             PG8_LDA(At, 1, 1); PG8_STAGE(PG8_SB(1, 0), b3, voffB); PG8_STAGE(PG8_SB(1, 1), b3 + hstep, voffB); PG8_STAGE(PG8_SA(1, 0), a3, voffA);
;             PG8_WAIT_V(8); PG8_WAIT_L(0); PG8_BAR; PG8_MMA(1, 0, At, B0); PG8_MMA(1, 1, At, B1); PG8_BAR; PG8_SCHED;
	s_add_i32 s33, 0, 0x18000
	s_add_i32 s42, 0, 0x1c000
	ds_read_b128 v[130:133], v241 offset:32768
	ds_read_b128 v[134:137], v241 offset:33792
	ds_read_b128 v[138:141], v241 offset:34816
	ds_read_b128 v[142:145], v241 offset:35840
	ds_read_b128 v[146:149], v241 offset:49152
	ds_read_b128 v[150:153], v241 offset:50176
	ds_read_b128 v[172:175], v241 offset:51200
	ds_read_b128 v[176:179], v241 offset:52224
	s_add_u32 s28, s28, 0x100000
	s_addc_u32 s29, s29, 0
	s_mov_b32 m0, s40
	ds_read_b128 v[180:183], v185 offset:32768
	ds_read_b128 v[188:191], v185 offset:33792
	ds_read_b128 v[192:195], v185 offset:34816
	ds_read_b128 v[196:199], v185 offset:35840
	ds_read_b128 v[200:203], v185 offset:36864
	ds_read_b128 v[204:207], v185 offset:37888
	ds_read_b128 v[208:211], v185 offset:38912
	ds_read_b128 v[212:215], v185 offset:39936
	global_load_lds_dwordx4 v154, s[28:29]
	s_mov_b32 m0, s41
	s_nop 0
	global_load_lds_dwordx4 v158, s[28:29]
	s_waitcnt vmcnt(8)
	s_waitcnt lgkmcnt(0)
	s_barrier
	s_waitcnt lgkmcnt(0)
	v_mfma_f32_16x16x32_bf16 v[114:117], v[130:133], v[180:183], v[114:117]
	v_mfma_f32_16x16x32_bf16 v[114:117], v[134:137], v[188:191], v[114:117]
	v_mfma_f32_16x16x32_bf16 v[118:121], v[138:141], v[180:183], v[118:121]
	v_mfma_f32_16x16x32_bf16 v[118:121], v[142:145], v[188:191], v[118:121]
	v_mfma_f32_16x16x32_bf16 v[106:109], v[130:133], v[192:195], v[106:109]
	v_mfma_f32_16x16x32_bf16 v[106:109], v[134:137], v[196:199], v[106:109]
	v_mfma_f32_16x16x32_bf16 v[98:101], v[138:141], v[192:195], v[98:101]
	v_mfma_f32_16x16x32_bf16 v[98:101], v[142:145], v[196:199], v[98:101]
	v_mfma_f32_16x16x32_bf16 v[90:93], v[130:133], v[200:203], v[90:93]
	v_mfma_f32_16x16x32_bf16 v[90:93], v[134:137], v[204:207], v[90:93]
	v_mfma_f32_16x16x32_bf16 v[82:85], v[138:141], v[200:203], v[82:85]
	v_mfma_f32_16x16x32_bf16 v[82:85], v[142:145], v[204:207], v[82:85]
	v_mfma_f32_16x16x32_bf16 v[74:77], v[130:133], v[208:211], v[74:77]
	v_mfma_f32_16x16x32_bf16 v[74:77], v[134:137], v[212:215], v[74:77]
	v_mfma_f32_16x16x32_bf16 v[66:69], v[138:141], v[208:211], v[66:69]
	v_mfma_f32_16x16x32_bf16 v[66:69], v[142:145], v[212:215], v[66:69]
	v_mfma_f32_16x16x32_bf16 v[122:125], v[146:149], v[180:183], v[122:125]
	v_mfma_f32_16x16x32_bf16 v[122:125], v[150:153], v[188:191], v[122:125]
	v_mfma_f32_16x16x32_bf16 v[126:129], v[172:175], v[180:183], v[126:129]
	v_mfma_f32_16x16x32_bf16 v[126:129], v[176:179], v[188:191], v[126:129]
	v_mfma_f32_16x16x32_bf16 v[110:113], v[146:149], v[192:195], v[110:113]
	v_mfma_f32_16x16x32_bf16 v[110:113], v[150:153], v[196:199], v[110:113]
	v_mfma_f32_16x16x32_bf16 v[102:105], v[172:175], v[192:195], v[102:105]
	v_mfma_f32_16x16x32_bf16 v[102:105], v[176:179], v[196:199], v[102:105]
	v_mfma_f32_16x16x32_bf16 v[94:97], v[146:149], v[200:203], v[94:97]
	v_mfma_f32_16x16x32_bf16 v[94:97], v[150:153], v[204:207], v[94:97]
	v_mfma_f32_16x16x32_bf16 v[86:89], v[172:175], v[200:203], v[86:89]
	v_mfma_f32_16x16x32_bf16 v[86:89], v[176:179], v[204:207], v[86:89]
	v_mfma_f32_16x16x32_bf16 v[78:81], v[146:149], v[208:211], v[78:81]
	v_mfma_f32_16x16x32_bf16 v[78:81], v[150:153], v[212:215], v[78:81]
	v_mfma_f32_16x16x32_bf16 v[70:73], v[172:175], v[208:211], v[70:73]
	v_mfma_f32_16x16x32_bf16 v[70:73], v[176:179], v[212:215], v[70:73]
	s_barrier
	s_add_i32 s28, s33, s36
	s_add_i32 m0, s28, 0xffffff80
	ds_read_b128 v[180:183], v185 offset:49152
	ds_read_b128 v[188:191], v185 offset:50176
	ds_read_b128 v[192:195], v185 offset:51200
	ds_read_b128 v[196:199], v185 offset:52224
	ds_read_b128 v[200:203], v185 offset:53248
	ds_read_b128 v[204:207], v185 offset:54272
	ds_read_b128 v[208:211], v185 offset:55296
	ds_read_b128 v[212:215], v185 offset:56320
	global_load_lds_dwordx4 v156, s[24:25] offset:128
	s_add_i32 m0, s28, 0x1f80
	s_add_i32 s28, s42, s36
	global_load_lds_dwordx4 v160, s[24:25] offset:128
	s_add_u32 s24, s24, 0x100080
	s_addc_u32 s25, s25, 0
	s_mov_b32 m0, s28
	s_nop 0
	global_load_lds_dwordx4 v156, s[24:25]
	s_add_i32 m0, s28, 0x2000
	s_nop 0
	global_load_lds_dwordx4 v160, s[24:25]
	s_mov_b32 m0, s46
	s_nop 0
	global_load_lds_dwordx4 v154, s[100:101]
	s_mov_b32 m0, s47
	s_nop 0
	global_load_lds_dwordx4 v158, s[100:101]
	s_waitcnt vmcnt(8)
	s_waitcnt lgkmcnt(0)
	s_barrier
	s_waitcnt lgkmcnt(0)
	v_mfma_f32_16x16x32_bf16 v[58:61], v[130:133], v[180:183], v[58:61]
	v_mfma_f32_16x16x32_bf16 v[58:61], v[134:137], v[188:191], v[58:61]
	v_mfma_f32_16x16x32_bf16 v[54:57], v[138:141], v[180:183], v[54:57]
	v_mfma_f32_16x16x32_bf16 v[54:57], v[142:145], v[188:191], v[54:57]
	v_mfma_f32_16x16x32_bf16 v[42:45], v[130:133], v[192:195], v[42:45]
	v_mfma_f32_16x16x32_bf16 v[42:45], v[134:137], v[196:199], v[42:45]
	v_mfma_f32_16x16x32_bf16 v[34:37], v[138:141], v[192:195], v[34:37]
	v_mfma_f32_16x16x32_bf16 v[34:37], v[142:145], v[196:199], v[34:37]
	v_mfma_f32_16x16x32_bf16 v[26:29], v[130:133], v[200:203], v[26:29]
	v_mfma_f32_16x16x32_bf16 v[26:29], v[134:137], v[204:207], v[26:29]
	v_mfma_f32_16x16x32_bf16 v[18:21], v[138:141], v[200:203], v[18:21]
	v_mfma_f32_16x16x32_bf16 v[18:21], v[142:145], v[204:207], v[18:21]
	v_mfma_f32_16x16x32_bf16 v[6:9], v[130:133], v[208:211], v[6:9]
	v_mfma_f32_16x16x32_bf16 v[6:9], v[134:137], v[212:215], v[6:9]
	v_mfma_f32_16x16x32_bf16 v[2:5], v[138:141], v[208:211], v[2:5]
	v_mfma_f32_16x16x32_bf16 v[2:5], v[142:145], v[212:215], v[2:5]
	v_mfma_f32_16x16x32_bf16 v[62:65], v[146:149], v[180:183], v[62:65]
	v_mfma_f32_16x16x32_bf16 v[62:65], v[150:153], v[188:191], v[62:65]
	v_mfma_f32_16x16x32_bf16 v[50:53], v[172:175], v[180:183], v[50:53]
	v_mfma_f32_16x16x32_bf16 v[50:53], v[176:179], v[188:191], v[50:53]
	v_mfma_f32_16x16x32_bf16 v[46:49], v[146:149], v[192:195], v[46:49]
	v_mfma_f32_16x16x32_bf16 v[46:49], v[150:153], v[196:199], v[46:49]
	v_mfma_f32_16x16x32_bf16 v[38:41], v[172:175], v[192:195], v[38:41]
	v_mfma_f32_16x16x32_bf16 v[38:41], v[176:179], v[196:199], v[38:41]
	v_mfma_f32_16x16x32_bf16 v[30:33], v[146:149], v[200:203], v[30:33]
	v_mfma_f32_16x16x32_bf16 v[30:33], v[150:153], v[204:207], v[30:33]
	v_mfma_f32_16x16x32_bf16 v[22:25], v[172:175], v[200:203], v[22:25]
	v_mfma_f32_16x16x32_bf16 v[22:25], v[176:179], v[204:207], v[22:25]
	v_mfma_f32_16x16x32_bf16 v[10:13], v[146:149], v[208:211], v[10:13]
	v_mfma_f32_16x16x32_bf16 v[10:13], v[150:153], v[212:215], v[10:13]
	v_mfma_f32_16x16x32_bf16 v[14:17], v[172:175], v[208:211], v[14:17]
	v_mfma_f32_16x16x32_bf16 v[14:17], v[176:179], v[212:215], v[14:17]
	s_barrier
	s_add_i32 s68, s68, 2
	s_add_u32 s26, s26, 0x100
	s_addc_u32 s27, s27, 0
	s_add_u32 s66, s66, 0x100
	s_addc_u32 s67, s67, 0
	s_cmp_gt_u32 s68, 61
	s_cbranch_scc0 .LBB0_1039
	s_and_b64 vcc, exec, s[10:11]
	s_cbranch_vccz .LBB0_1042
	s_barrier

; #define PG8_STAGE(bufoff, gbase, voff) do { _Pragma("unroll") for (int _i = 0; _i < 2; ++_i) \
;         __builtin_amdgcn_global_load_lds((const unsigned*)((const char*)(gbase) + (voff)[_i]), (PG8_LAS unsigned*)(lds + (bufoff) + ldsw + _i * 8192), 16, 0, 0); } while (0)
; #define PG8_LDA(dst, b, h) do { _Pragma("unroll") for (int m = 0; m < 4; ++m) _Pragma("unroll") for (int k = 0; k < 2; ++k) dst[m][k] = *(const PG8_LAS bf16x8*)(lds + PG8_SA(b, h) + aoff + m * 2048 + k * 1024); } while (0)
; #define PG8_LDB(dst, b, h) do { _Pragma("unroll") for (int n = 0; n < 2; ++n) _Pragma("unroll") for (int k = 0; k < 2; ++k) dst[n][k] = *(const PG8_LAS bf16x8*)(lds + PG8_SB(b, h) + boff + n * 2048 + k * 1024); } while (0)
; #define PG8_MMA(ai, bj, At, Bt) do { __builtin_amdgcn_s_setprio(1); _Pragma("unroll") for (int m = 0; m < 4; ++m) _Pragma("unroll") for (int n = 0; n < 2; ++n) _Pragma("unroll") for (int k = 0; k < 2; ++k) \
;         acc[ai][bj][m][n] = __builtin_amdgcn_mfma_f32_16x16x32_bf16(Bt[n][k], At[m][k], acc[ai][bj][m][n], 0, 0, 0); __builtin_amdgcn_s_setprio(0); } while (0)
; #define PG8_WAIT_V(n) asm volatile("s_waitcnt vmcnt(" #n ")" ::: "memory")
; #define PG8_WAIT_L(n) asm volatile("s_waitcnt lgkmcnt(" #n ")" ::: "memory")
; #define PG8_BAR __builtin_amdgcn_s_barrier()
; #define PG8_SCHED __builtin_amdgcn_sched_barrier(0)
; template <class Epi, class Sched, bool ALIGN_EPI = false, bool SP2 = false>
; __device__ __forceinline__ void gemm_phase(PG8_LAS unsigned char* lds, const Gemm g, const Sched& S, const Epi& E) {
;     ...
;             if constexpr (SP2) {
;             PG8_LDB(B0, 0, 0); PG8_LDB(B1, 0, 1); PG8_SCHED; PG8_LDA(At, 0, 0); PG8_STAGE(PG8_SA(1, 1), a1 + hstep, voffA);
;             PG8_WAIT_V(8); PG8_WAIT_L(0); PG8_BAR; PG8_MMA(0, 0, At, B0); PG8_MMA(0, 1, At, B1); PG8_BAR; PG8_SCHED;
;             PG8_LDA(At, 0, 1); PG8_STAGE(PG8_SB(0, 0), b2, voffB); PG8_STAGE(PG8_SB(0, 1), b2 + hstep, voffB); PG8_STAGE(PG8_SA(0, 0), a2, voffA);
;             PG8_WAIT_V(8); PG8_WAIT_L(0); PG8_BAR; PG8_MMA(1, 0, At, B0); PG8_MMA(1, 1, At, B1); PG8_BAR; PG8_SCHED;
.LBB0_1126:
	ds_read_b128 v[160:163], v241 offset:0
	ds_read_b128 v[166:169], v241 offset:1024
	ds_read_b128 v[170:173], v241 offset:2048
	ds_read_b128 v[174:177], v241 offset:3072
	ds_read_b128 v[178:181], v241 offset:16384
	ds_read_b128 v[182:185], v241 offset:17408
	ds_read_b128 v[186:189], v241 offset:18432
	ds_read_b128 v[190:193], v241 offset:19456
	s_add_u32 s22, s24, 0xfff00080
	s_addc_u32 s23, s25, -1
	s_cmp_eq_u32 s68, 60
	s_cselect_b32 s27, s15, s23
	s_cselect_b32 s26, s64, s22
	s_cselect_b32 s23, s13, s67
	s_cselect_b32 s22, s65, s66
	s_add_i32 m0, s21, 0xc000
	ds_read_b128 v[194:197], v155
	ds_read_b128 v[198:201], v155 offset:1024
	ds_read_b128 v[202:205], v155 offset:2048
	ds_read_b128 v[206:209], v155 offset:3072
	ds_read_b128 v[210:213], v155 offset:4096
	ds_read_b128 v[214:217], v155 offset:5120
	ds_read_b128 v[218:221], v155 offset:6144
	ds_read_b128 v[222:225], v155 offset:7168
	global_load_lds_dwordx4 v138, s[24:25]
	s_add_i32 m0, s21, 0xe000
	s_nop 0
	global_load_lds_dwordx4 v140, s[24:25]
	s_waitcnt vmcnt(8)
	s_waitcnt lgkmcnt(0)
	s_barrier
	s_waitcnt lgkmcnt(0)
	v_mfma_f32_16x16x32_bf16 v[122:125], v[160:163], v[194:197], v[122:125]
	v_mfma_f32_16x16x32_bf16 v[122:125], v[166:169], v[198:201], v[122:125]
	v_mfma_f32_16x16x32_bf16 v[114:117], v[170:173], v[194:197], v[114:117]
	v_mfma_f32_16x16x32_bf16 v[114:117], v[174:177], v[198:201], v[114:117]
	v_mfma_f32_16x16x32_bf16 v[106:109], v[160:163], v[202:205], v[106:109]
	v_mfma_f32_16x16x32_bf16 v[106:109], v[166:169], v[206:209], v[106:109]
	v_mfma_f32_16x16x32_bf16 v[98:101], v[170:173], v[202:205], v[98:101]
	v_mfma_f32_16x16x32_bf16 v[98:101], v[174:177], v[206:209], v[98:101]
	v_mfma_f32_16x16x32_bf16 v[90:93], v[160:163], v[210:213], v[90:93]
	v_mfma_f32_16x16x32_bf16 v[90:93], v[166:169], v[214:217], v[90:93]
	v_mfma_f32_16x16x32_bf16 v[82:85], v[170:173], v[210:213], v[82:85]
	v_mfma_f32_16x16x32_bf16 v[82:85], v[174:177], v[214:217], v[82:85]
	v_mfma_f32_16x16x32_bf16 v[74:77], v[160:163], v[218:221], v[74:77]
	v_mfma_f32_16x16x32_bf16 v[74:77], v[166:169], v[222:225], v[74:77]
	v_mfma_f32_16x16x32_bf16 v[62:65], v[170:173], v[218:221], v[62:65]
	v_mfma_f32_16x16x32_bf16 v[62:65], v[174:177], v[222:225], v[62:65]
	v_mfma_f32_16x16x32_bf16 v[126:129], v[178:181], v[194:197], v[126:129]
	v_mfma_f32_16x16x32_bf16 v[126:129], v[182:185], v[198:201], v[126:129]
	v_mfma_f32_16x16x32_bf16 v[118:121], v[186:189], v[194:197], v[118:121]
	v_mfma_f32_16x16x32_bf16 v[118:121], v[190:193], v[198:201], v[118:121]
	v_mfma_f32_16x16x32_bf16 v[110:113], v[178:181], v[202:205], v[110:113]
	v_mfma_f32_16x16x32_bf16 v[110:113], v[182:185], v[206:209], v[110:113]
	v_mfma_f32_16x16x32_bf16 v[102:105], v[186:189], v[202:205], v[102:105]
	v_mfma_f32_16x16x32_bf16 v[102:105], v[190:193], v[206:209], v[102:105]
	v_mfma_f32_16x16x32_bf16 v[94:97], v[178:181], v[210:213], v[94:97]
	v_mfma_f32_16x16x32_bf16 v[94:97], v[182:185], v[214:217], v[94:97]
	v_mfma_f32_16x16x32_bf16 v[86:89], v[186:189], v[210:213], v[86:89]
	v_mfma_f32_16x16x32_bf16 v[86:89], v[190:193], v[214:217], v[86:89]
	v_mfma_f32_16x16x32_bf16 v[78:81], v[178:181], v[218:221], v[78:81]
	v_mfma_f32_16x16x32_bf16 v[78:81], v[182:185], v[222:225], v[78:81]
	v_mfma_f32_16x16x32_bf16 v[70:73], v[186:189], v[218:221], v[70:73]
	v_mfma_f32_16x16x32_bf16 v[70:73], v[190:193], v[222:225], v[70:73]
	s_barrier
	s_add_i32 s33, s52, s29
	s_mov_b32 m0, s33
	ds_read_b128 v[194:197], v155 offset:16384
	ds_read_b128 v[198:201], v155 offset:17408
	ds_read_b128 v[202:205], v155 offset:18432
	ds_read_b128 v[206:209], v155 offset:19456
	ds_read_b128 v[210:213], v155 offset:20480
	ds_read_b128 v[214:217], v155 offset:21504
	ds_read_b128 v[218:221], v155 offset:22528
	ds_read_b128 v[222:225], v155 offset:23552
	global_load_lds_dwordx4 v132, s[22:23]
	s_add_i32 m0, s33, 0x2000
	s_add_u32 s72, s22, 0x100000
	s_addc_u32 s73, s23, 0
	s_add_i32 s33, s53, s29
	global_load_lds_dwordx4 v136, s[22:23]
	s_mov_b32 m0, s33
	s_add_u32 s100, s26, 0x80
	s_addc_u32 s101, s27, 0
	global_load_lds_dwordx4 v132, s[72:73]
	s_add_i32 m0, s33, 0x2000
	s_nop 0
	global_load_lds_dwordx4 v136, s[72:73]
	s_mov_b32 m0, s21
	s_nop 0
	global_load_lds_dwordx4 v130, s[26:27]
	s_mov_b32 m0, s36
	s_nop 0
	global_load_lds_dwordx4 v134, s[26:27]
	s_waitcnt vmcnt(8)
	s_waitcnt lgkmcnt(0)
	s_barrier
	s_waitcnt lgkmcnt(0)
	v_mfma_f32_16x16x32_bf16 v[58:61], v[160:163], v[194:197], v[58:61]
	v_mfma_f32_16x16x32_bf16 v[58:61], v[166:169], v[198:201], v[58:61]
	v_mfma_f32_16x16x32_bf16 v[50:53], v[170:173], v[194:197], v[50:53]
	v_mfma_f32_16x16x32_bf16 v[50:53], v[174:177], v[198:201], v[50:53]
	v_mfma_f32_16x16x32_bf16 v[42:45], v[160:163], v[202:205], v[42:45]
	v_mfma_f32_16x16x32_bf16 v[42:45], v[166:169], v[206:209], v[42:45]
	v_mfma_f32_16x16x32_bf16 v[34:37], v[170:173], v[202:205], v[34:37]
	v_mfma_f32_16x16x32_bf16 v[34:37], v[174:177], v[206:209], v[34:37]
	v_mfma_f32_16x16x32_bf16 v[26:29], v[160:163], v[210:213], v[26:29]
	v_mfma_f32_16x16x32_bf16 v[26:29], v[166:169], v[214:217], v[26:29]
	v_mfma_f32_16x16x32_bf16 v[18:21], v[170:173], v[210:213], v[18:21]
	v_mfma_f32_16x16x32_bf16 v[18:21], v[174:177], v[214:217], v[18:21]
	v_mfma_f32_16x16x32_bf16 v[10:13], v[160:163], v[218:221], v[10:13]
	v_mfma_f32_16x16x32_bf16 v[10:13], v[166:169], v[222:225], v[10:13]
	v_mfma_f32_16x16x32_bf16 v[2:5], v[170:173], v[218:221], v[2:5]
	v_mfma_f32_16x16x32_bf16 v[2:5], v[174:177], v[222:225], v[2:5]
	v_mfma_f32_16x16x32_bf16 v[66:69], v[178:181], v[194:197], v[66:69]
	v_mfma_f32_16x16x32_bf16 v[66:69], v[182:185], v[198:201], v[66:69]
	v_mfma_f32_16x16x32_bf16 v[54:57], v[186:189], v[194:197], v[54:57]
	v_mfma_f32_16x16x32_bf16 v[54:57], v[190:193], v[198:201], v[54:57]
	v_mfma_f32_16x16x32_bf16 v[46:49], v[178:181], v[202:205], v[46:49]
	v_mfma_f32_16x16x32_bf16 v[46:49], v[182:185], v[206:209], v[46:49]
	v_mfma_f32_16x16x32_bf16 v[38:41], v[186:189], v[202:205], v[38:41]
	v_mfma_f32_16x16x32_bf16 v[38:41], v[190:193], v[206:209], v[38:41]
	v_mfma_f32_16x16x32_bf16 v[30:33], v[178:181], v[210:213], v[30:33]
	v_mfma_f32_16x16x32_bf16 v[30:33], v[182:185], v[214:217], v[30:33]
	v_mfma_f32_16x16x32_bf16 v[22:25], v[186:189], v[210:213], v[22:25]
	v_mfma_f32_16x16x32_bf16 v[22:25], v[190:193], v[214:217], v[22:25]
	v_mfma_f32_16x16x32_bf16 v[14:17], v[178:181], v[218:221], v[14:17]
	v_mfma_f32_16x16x32_bf16 v[14:17], v[182:185], v[222:225], v[14:17]
	v_mfma_f32_16x16x32_bf16 v[6:9], v[186:189], v[218:221], v[6:9]
	v_mfma_f32_16x16x32_bf16 v[6:9], v[190:193], v[222:225], v[6:9]
	s_barrier
; #define PG8_STAGE(bufoff, gbase, voff) do { _Pragma("unroll") for (int _i = 0; _i < 2; ++_i) \
;         __builtin_amdgcn_global_load_lds((const unsigned*)((const char*)(gbase) + (voff)[_i]), (PG8_LAS unsigned*)(lds + (bufoff) + ldsw + _i * 8192), 16, 0, 0); } while (0)
; #define PG8_LDA(dst, b, h) do { _Pragma("unroll") for (int m = 0; m < 4; ++m) _Pragma("unroll") for (int k = 0; k < 2; ++k) dst[m][k] = *(const PG8_LAS bf16x8*)(lds + PG8_SA(b, h) + aoff + m * 2048 + k * 1024); } while (0)
; #define PG8_LDB(dst, b, h) do { _Pragma("unroll") for (int n = 0; n < 2; ++n) _Pragma("unroll") for (int k = 0; k < 2; ++k) dst[n][k] = *(const PG8_LAS bf16x8*)(lds + PG8_SB(b, h) + boff + n * 2048 + k * 1024); } while (0)
; template <class Epi, class Sched, bool ALIGN_EPI = false, bool SP2 = false>
; __device__ __forceinline__ void gemm_phase(PG8_LAS unsigned char* lds, const Gemm g, const Sched& S, const Epi& E) {
;     ...
;         for (int t = 0; t < nt; t += 2) {
;             const bool last = (t == nt - 2);
;             const char* a1 = cA + (size_t)(t + 1) * kstep;
;             const char* a2 = last ? nA : cA + (size_t)(t + 2) * kstep; const char* b2 = last ? nB : cB + (size_t)(t + 2) * kstep;
;             const char* a3 = a2 + kstep; const char* b3 = b2 + kstep;
;             if (last && has_next) S.a_ready(nxt);
;             if constexpr (SP2) {
;             PG8_LDB(B0, 0, 0); PG8_LDB(B1, 0, 1); PG8_SCHED; PG8_LDA(At, 0, 0); PG8_STAGE(PG8_SA(1, 1), a1 + hstep, voffA);
;             PG8_WAIT_V(8); PG8_WAIT_L(0); PG8_BAR; PG8_MMA(0, 0, At, B0); PG8_MMA(0, 1, At, B1); PG8_BAR; PG8_SCHED;
;             PG8_LDA(At, 0, 1); PG8_STAGE(PG8_SB(0, 0), b2, voffB); PG8_STAGE(PG8_SB(0, 1), b2 + hstep, voffB); PG8_STAGE(PG8_SA(0, 0), a2, voffA);
;             PG8_WAIT_V(8); PG8_WAIT_L(0); PG8_BAR; PG8_MMA(1, 0, At, B0); PG8_MMA(1, 1, At, B1); PG8_BAR; PG8_SCHED;
;             PG8_LDB(B0, 1, 0); PG8_LDB(B1, 1, 1); PG8_SCHED; PG8_LDA(At, 1, 0); PG8_STAGE(PG8_SA(0, 1), a2 + hstep, voffA);
;             PG8_WAIT_V(8); PG8_WAIT_L(0); PG8_BAR; PG8_MMA(0, 0, At, B0); PG8_MMA(0, 1, At, B1); PG8_BAR; PG8_SCHED;
;             PG8_LDA(At, 1, 1); PG8_STAGE(PG8_SB(1, 0), b3, voffB); PG8_STAGE(PG8_SB(1, 1), b3 + hstep, voffB); PG8_STAGE(PG8_SA(1, 0), a3, voffA);
;             PG8_WAIT_V(8); PG8_WAIT_L(0); PG8_BAR; PG8_MMA(1, 0, At, B0); PG8_MMA(1, 1, At, B1); PG8_BAR; PG8_SCHED;
	s_add_i32 s33, 0, 0x18000
	s_add_i32 s42, 0, 0x1c000
	ds_read_b128 v[160:163], v241 offset:32768
	ds_read_b128 v[166:169], v241 offset:33792
	ds_read_b128 v[170:173], v241 offset:34816
	ds_read_b128 v[174:177], v241 offset:35840
	ds_read_b128 v[178:181], v241 offset:49152
	ds_read_b128 v[182:185], v241 offset:50176
	ds_read_b128 v[186:189], v241 offset:51200
	ds_read_b128 v[190:193], v241 offset:52224
	s_add_u32 s26, s26, 0x100000
	s_addc_u32 s27, s27, 0
	s_mov_b32 m0, s37
	ds_read_b128 v[194:197], v155 offset:32768
	ds_read_b128 v[198:201], v155 offset:33792
	ds_read_b128 v[202:205], v155 offset:34816
	ds_read_b128 v[206:209], v155 offset:35840
	ds_read_b128 v[210:213], v155 offset:36864
	ds_read_b128 v[214:217], v155 offset:37888
	ds_read_b128 v[218:221], v155 offset:38912
	ds_read_b128 v[222:225], v155 offset:39936
	global_load_lds_dwordx4 v130, s[26:27]
	s_mov_b32 m0, s40
	s_nop 0
	global_load_lds_dwordx4 v134, s[26:27]
	s_waitcnt vmcnt(8)
	s_waitcnt lgkmcnt(0)
	s_barrier
	s_waitcnt lgkmcnt(0)
	v_mfma_f32_16x16x32_bf16 v[122:125], v[160:163], v[194:197], v[122:125]
	v_mfma_f32_16x16x32_bf16 v[122:125], v[166:169], v[198:201], v[122:125]
	v_mfma_f32_16x16x32_bf16 v[114:117], v[170:173], v[194:197], v[114:117]
	v_mfma_f32_16x16x32_bf16 v[114:117], v[174:177], v[198:201], v[114:117]
	v_mfma_f32_16x16x32_bf16 v[106:109], v[160:163], v[202:205], v[106:109]
	v_mfma_f32_16x16x32_bf16 v[106:109], v[166:169], v[206:209], v[106:109]
	v_mfma_f32_16x16x32_bf16 v[98:101], v[170:173], v[202:205], v[98:101]
	v_mfma_f32_16x16x32_bf16 v[98:101], v[174:177], v[206:209], v[98:101]
	v_mfma_f32_16x16x32_bf16 v[90:93], v[160:163], v[210:213], v[90:93]
	v_mfma_f32_16x16x32_bf16 v[90:93], v[166:169], v[214:217], v[90:93]
	v_mfma_f32_16x16x32_bf16 v[82:85], v[170:173], v[210:213], v[82:85]
	v_mfma_f32_16x16x32_bf16 v[82:85], v[174:177], v[214:217], v[82:85]
	v_mfma_f32_16x16x32_bf16 v[74:77], v[160:163], v[218:221], v[74:77]
	v_mfma_f32_16x16x32_bf16 v[74:77], v[166:169], v[222:225], v[74:77]
	v_mfma_f32_16x16x32_bf16 v[62:65], v[170:173], v[218:221], v[62:65]
	v_mfma_f32_16x16x32_bf16 v[62:65], v[174:177], v[222:225], v[62:65]
	v_mfma_f32_16x16x32_bf16 v[126:129], v[178:181], v[194:197], v[126:129]
	v_mfma_f32_16x16x32_bf16 v[126:129], v[182:185], v[198:201], v[126:129]
	v_mfma_f32_16x16x32_bf16 v[118:121], v[186:189], v[194:197], v[118:121]
	v_mfma_f32_16x16x32_bf16 v[118:121], v[190:193], v[198:201], v[118:121]
	v_mfma_f32_16x16x32_bf16 v[110:113], v[178:181], v[202:205], v[110:113]
	v_mfma_f32_16x16x32_bf16 v[110:113], v[182:185], v[206:209], v[110:113]
	v_mfma_f32_16x16x32_bf16 v[102:105], v[186:189], v[202:205], v[102:105]
	v_mfma_f32_16x16x32_bf16 v[102:105], v[190:193], v[206:209], v[102:105]
	v_mfma_f32_16x16x32_bf16 v[94:97], v[178:181], v[210:213], v[94:97]
	v_mfma_f32_16x16x32_bf16 v[94:97], v[182:185], v[214:217], v[94:97]
	v_mfma_f32_16x16x32_bf16 v[86:89], v[186:189], v[210:213], v[86:89]
	v_mfma_f32_16x16x32_bf16 v[86:89], v[190:193], v[214:217], v[86:89]
	v_mfma_f32_16x16x32_bf16 v[78:81], v[178:181], v[218:221], v[78:81]
	v_mfma_f32_16x16x32_bf16 v[78:81], v[182:185], v[222:225], v[78:81]
	v_mfma_f32_16x16x32_bf16 v[70:73], v[186:189], v[218:221], v[70:73]
	v_mfma_f32_16x16x32_bf16 v[70:73], v[190:193], v[222:225], v[70:73]
	s_barrier
	s_add_i32 s26, s33, s29
	s_add_i32 m0, s26, 0xffffff80
	ds_read_b128 v[194:197], v155 offset:49152
	ds_read_b128 v[198:201], v155 offset:50176
	ds_read_b128 v[202:205], v155 offset:51200
	ds_read_b128 v[206:209], v155 offset:52224
	ds_read_b128 v[210:213], v155 offset:53248
	ds_read_b128 v[214:217], v155 offset:54272
	ds_read_b128 v[218:221], v155 offset:55296
	ds_read_b128 v[222:225], v155 offset:56320
	global_load_lds_dwordx4 v132, s[22:23] offset:128
	s_add_i32 m0, s26, 0x1f80
	s_add_i32 s26, s42, s29
	global_load_lds_dwordx4 v136, s[22:23] offset:128
	s_add_u32 s22, s22, 0x100080
	s_addc_u32 s23, s23, 0
	s_mov_b32 m0, s26
	s_nop 0
	global_load_lds_dwordx4 v132, s[22:23]
	s_add_i32 m0, s26, 0x2000
	s_nop 0
	global_load_lds_dwordx4 v136, s[22:23]
	s_mov_b32 m0, s46
	s_nop 0
	global_load_lds_dwordx4 v130, s[100:101]
	s_mov_b32 m0, s47
	s_nop 0
	global_load_lds_dwordx4 v134, s[100:101]
	s_waitcnt vmcnt(8)
	s_waitcnt lgkmcnt(0)
	s_barrier
	s_waitcnt lgkmcnt(0)
	v_mfma_f32_16x16x32_bf16 v[58:61], v[160:163], v[194:197], v[58:61]
	v_mfma_f32_16x16x32_bf16 v[58:61], v[166:169], v[198:201], v[58:61]
	v_mfma_f32_16x16x32_bf16 v[50:53], v[170:173], v[194:197], v[50:53]
	v_mfma_f32_16x16x32_bf16 v[50:53], v[174:177], v[198:201], v[50:53]
	v_mfma_f32_16x16x32_bf16 v[42:45], v[160:163], v[202:205], v[42:45]
	v_mfma_f32_16x16x32_bf16 v[42:45], v[166:169], v[206:209], v[42:45]
	v_mfma_f32_16x16x32_bf16 v[34:37], v[170:173], v[202:205], v[34:37]
	v_mfma_f32_16x16x32_bf16 v[34:37], v[174:177], v[206:209], v[34:37]
	v_mfma_f32_16x16x32_bf16 v[26:29], v[160:163], v[210:213], v[26:29]
	v_mfma_f32_16x16x32_bf16 v[26:29], v[166:169], v[214:217], v[26:29]
	v_mfma_f32_16x16x32_bf16 v[18:21], v[170:173], v[210:213], v[18:21]
	v_mfma_f32_16x16x32_bf16 v[18:21], v[174:177], v[214:217], v[18:21]
	v_mfma_f32_16x16x32_bf16 v[10:13], v[160:163], v[218:221], v[10:13]
	v_mfma_f32_16x16x32_bf16 v[10:13], v[166:169], v[222:225], v[10:13]
	v_mfma_f32_16x16x32_bf16 v[2:5], v[170:173], v[218:221], v[2:5]
	v_mfma_f32_16x16x32_bf16 v[2:5], v[174:177], v[222:225], v[2:5]
	v_mfma_f32_16x16x32_bf16 v[66:69], v[178:181], v[194:197], v[66:69]
	v_mfma_f32_16x16x32_bf16 v[66:69], v[182:185], v[198:201], v[66:69]
	v_mfma_f32_16x16x32_bf16 v[54:57], v[186:189], v[194:197], v[54:57]
	v_mfma_f32_16x16x32_bf16 v[54:57], v[190:193], v[198:201], v[54:57]
	v_mfma_f32_16x16x32_bf16 v[46:49], v[178:181], v[202:205], v[46:49]
	v_mfma_f32_16x16x32_bf16 v[46:49], v[182:185], v[206:209], v[46:49]
	v_mfma_f32_16x16x32_bf16 v[38:41], v[186:189], v[202:205], v[38:41]
	v_mfma_f32_16x16x32_bf16 v[38:41], v[190:193], v[206:209], v[38:41]
	v_mfma_f32_16x16x32_bf16 v[30:33], v[178:181], v[210:213], v[30:33]
	v_mfma_f32_16x16x32_bf16 v[30:33], v[182:185], v[214:217], v[30:33]
	v_mfma_f32_16x16x32_bf16 v[22:25], v[186:189], v[210:213], v[22:25]
	v_mfma_f32_16x16x32_bf16 v[22:25], v[190:193], v[214:217], v[22:25]
	v_mfma_f32_16x16x32_bf16 v[14:17], v[178:181], v[218:221], v[14:17]
	v_mfma_f32_16x16x32_bf16 v[14:17], v[182:185], v[222:225], v[14:17]
	v_mfma_f32_16x16x32_bf16 v[6:9], v[186:189], v[218:221], v[6:9]
	v_mfma_f32_16x16x32_bf16 v[6:9], v[190:193], v[222:225], v[6:9]
	s_barrier
	s_add_i32 s68, s68, 2
	s_add_u32 s24, s24, 0x100
	s_addc_u32 s25, s25, 0
	s_add_u32 s66, s66, 0x100
	s_addc_u32 s67, s67, 0
	s_cmp_gt_u32 s68, 61
	s_cbranch_scc0 .LBB0_1126
	s_and_b64 vcc, exec, s[8:9]
	s_cbranch_vccz .LBB0_1129
	s_barrier

; #define PG8_STAGE(bufoff, gbase, voff) do { _Pragma("unroll") for (int _i = 0; _i < 2; ++_i) \
;         __builtin_amdgcn_global_load_lds((const unsigned*)((const char*)(gbase) + (voff)[_i]), (PG8_LAS unsigned*)(lds + (bufoff) + ldsw + _i * 8192), 16, 0, 0); } while (0)
; #define PG8_LDA(dst, b, h) do { _Pragma("unroll") for (int m = 0; m < 4; ++m) _Pragma("unroll") for (int k = 0; k < 2; ++k) dst[m][k] = *(const PG8_LAS bf16x8*)(lds + PG8_SA(b, h) + aoff + m * 2048 + k * 1024); } while (0)
; #define PG8_LDB(dst, b, h) do { _Pragma("unroll") for (int n = 0; n < 2; ++n) _Pragma("unroll") for (int k = 0; k < 2; ++k) dst[n][k] = *(const PG8_LAS bf16x8*)(lds + PG8_SB(b, h) + boff + n * 2048 + k * 1024); } while (0)
; #define PG8_MMA(ai, bj, At, Bt) do { __builtin_amdgcn_s_setprio(1); _Pragma("unroll") for (int m = 0; m < 4; ++m) _Pragma("unroll") for (int n = 0; n < 2; ++n) _Pragma("unroll") for (int k = 0; k < 2; ++k) \
;         acc[ai][bj][m][n] = __builtin_amdgcn_mfma_f32_16x16x32_bf16(Bt[n][k], At[m][k], acc[ai][bj][m][n], 0, 0, 0); __builtin_amdgcn_s_setprio(0); } while (0)
; #define PG8_WAIT_V(n) asm volatile("s_waitcnt vmcnt(" #n ")" ::: "memory")
; #define PG8_WAIT_L(n) asm volatile("s_waitcnt lgkmcnt(" #n ")" ::: "memory")
; #define PG8_BAR __builtin_amdgcn_s_barrier()
; #define PG8_SCHED __builtin_amdgcn_sched_barrier(0)
; template <class Epi, class Sched, bool ALIGN_EPI = false, bool SP2 = false>
; __device__ __forceinline__ void gemm_phase(PG8_LAS unsigned char* lds, const Gemm g, const Sched& S, const Epi& E) {
;     ...
;             if constexpr (SP2) {
;             PG8_LDB(B0, 0, 0); PG8_LDB(B1, 0, 1); PG8_SCHED; PG8_LDA(At, 0, 0); PG8_STAGE(PG8_SA(1, 1), a1 + hstep, voffA);
;             PG8_WAIT_V(8); PG8_WAIT_L(0); PG8_BAR; PG8_MMA(0, 0, At, B0); PG8_MMA(0, 1, At, B1); PG8_BAR; PG8_SCHED;
;             PG8_LDA(At, 0, 1); PG8_STAGE(PG8_SB(0, 0), b2, voffB); PG8_STAGE(PG8_SB(0, 1), b2 + hstep, voffB); PG8_STAGE(PG8_SA(0, 0), a2, voffA);
;             PG8_WAIT_V(8); PG8_WAIT_L(0); PG8_BAR; PG8_MMA(1, 0, At, B0); PG8_MMA(1, 1, At, B1); PG8_BAR; PG8_SCHED;
.LBB0_1245:
	ds_read_b128 v[130:133], v241 offset:0
	ds_read_b128 v[134:137], v241 offset:1024
	ds_read_b128 v[138:141], v241 offset:2048
	ds_read_b128 v[142:145], v241 offset:3072
	ds_read_b128 v[146:149], v241 offset:16384
	ds_read_b128 v[150:153], v241 offset:17408
	ds_read_b128 v[172:175], v241 offset:18432
	ds_read_b128 v[176:179], v241 offset:19456
	s_add_u32 s16, s18, 0xffd50080
	s_addc_u32 s17, s19, -1
	s_cmpk_eq_i32 s64, 0xa8
	s_cselect_b32 s21, s5, s17
	s_cselect_b32 s20, s4, s16
	s_cselect_b32 s17, s15, s63
	s_cselect_b32 s16, s14, s62
	s_add_i32 m0, s25, 0xc000
	ds_read_b128 v[180:183], v185
	ds_read_b128 v[188:191], v185 offset:1024
	ds_read_b128 v[192:195], v185 offset:2048
	ds_read_b128 v[196:199], v185 offset:3072
	ds_read_b128 v[200:203], v185 offset:4096
	ds_read_b128 v[204:207], v185 offset:5120
	ds_read_b128 v[208:211], v185 offset:6144
	ds_read_b128 v[212:215], v185 offset:7168
	global_load_lds_dwordx4 v162, s[18:19]
	s_add_i32 m0, s25, 0xe000
	s_nop 0
	global_load_lds_dwordx4 v166, s[18:19]
	s_waitcnt vmcnt(8)
	s_waitcnt lgkmcnt(0)
	s_barrier
	s_waitcnt lgkmcnt(0)
	v_mfma_f32_16x16x32_bf16 v[114:117], v[130:133], v[180:183], v[114:117]
	v_mfma_f32_16x16x32_bf16 v[114:117], v[134:137], v[188:191], v[114:117]
	v_mfma_f32_16x16x32_bf16 v[118:121], v[138:141], v[180:183], v[118:121]
	v_mfma_f32_16x16x32_bf16 v[118:121], v[142:145], v[188:191], v[118:121]
	v_mfma_f32_16x16x32_bf16 v[106:109], v[130:133], v[192:195], v[106:109]
	v_mfma_f32_16x16x32_bf16 v[106:109], v[134:137], v[196:199], v[106:109]
	v_mfma_f32_16x16x32_bf16 v[98:101], v[138:141], v[192:195], v[98:101]
	v_mfma_f32_16x16x32_bf16 v[98:101], v[142:145], v[196:199], v[98:101]
	v_mfma_f32_16x16x32_bf16 v[90:93], v[130:133], v[200:203], v[90:93]
	v_mfma_f32_16x16x32_bf16 v[90:93], v[134:137], v[204:207], v[90:93]
	v_mfma_f32_16x16x32_bf16 v[82:85], v[138:141], v[200:203], v[82:85]
	v_mfma_f32_16x16x32_bf16 v[82:85], v[142:145], v[204:207], v[82:85]
	v_mfma_f32_16x16x32_bf16 v[74:77], v[130:133], v[208:211], v[74:77]
	v_mfma_f32_16x16x32_bf16 v[74:77], v[134:137], v[212:215], v[74:77]
	v_mfma_f32_16x16x32_bf16 v[66:69], v[138:141], v[208:211], v[66:69]
	v_mfma_f32_16x16x32_bf16 v[66:69], v[142:145], v[212:215], v[66:69]
	v_mfma_f32_16x16x32_bf16 v[122:125], v[146:149], v[180:183], v[122:125]
	v_mfma_f32_16x16x32_bf16 v[122:125], v[150:153], v[188:191], v[122:125]
	v_mfma_f32_16x16x32_bf16 v[126:129], v[172:175], v[180:183], v[126:129]
	v_mfma_f32_16x16x32_bf16 v[126:129], v[176:179], v[188:191], v[126:129]
	v_mfma_f32_16x16x32_bf16 v[110:113], v[146:149], v[192:195], v[110:113]
	v_mfma_f32_16x16x32_bf16 v[110:113], v[150:153], v[196:199], v[110:113]
	v_mfma_f32_16x16x32_bf16 v[102:105], v[172:175], v[192:195], v[102:105]
	v_mfma_f32_16x16x32_bf16 v[102:105], v[176:179], v[196:199], v[102:105]
	v_mfma_f32_16x16x32_bf16 v[94:97], v[146:149], v[200:203], v[94:97]
	v_mfma_f32_16x16x32_bf16 v[94:97], v[150:153], v[204:207], v[94:97]
	v_mfma_f32_16x16x32_bf16 v[86:89], v[172:175], v[200:203], v[86:89]
	v_mfma_f32_16x16x32_bf16 v[86:89], v[176:179], v[204:207], v[86:89]
	v_mfma_f32_16x16x32_bf16 v[78:81], v[146:149], v[208:211], v[78:81]
	v_mfma_f32_16x16x32_bf16 v[78:81], v[150:153], v[212:215], v[78:81]
	v_mfma_f32_16x16x32_bf16 v[70:73], v[172:175], v[208:211], v[70:73]
	v_mfma_f32_16x16x32_bf16 v[70:73], v[176:179], v[212:215], v[70:73]
	s_barrier
	s_add_i32 s33, s40, s24
	s_mov_b32 m0, s33
	ds_read_b128 v[180:183], v185 offset:16384
	ds_read_b128 v[188:191], v185 offset:17408
	ds_read_b128 v[192:195], v185 offset:18432
	ds_read_b128 v[196:199], v185 offset:19456
	ds_read_b128 v[200:203], v185 offset:20480
	ds_read_b128 v[204:207], v185 offset:21504
	ds_read_b128 v[208:211], v185 offset:22528
	ds_read_b128 v[212:215], v185 offset:23552
	global_load_lds_dwordx4 v156, s[16:17]
	s_add_i32 m0, s33, 0x2000
	s_add_u32 s66, s16, 0x2b0000
	s_addc_u32 s67, s17, 0
	s_add_i32 s33, s41, s24
	global_load_lds_dwordx4 v160, s[16:17]
	s_mov_b32 m0, s33
	s_add_u32 s100, s20, 0x80
	s_addc_u32 s101, s21, 0
	global_load_lds_dwordx4 v156, s[66:67]
	s_add_i32 m0, s33, 0x2000
	s_nop 0
	global_load_lds_dwordx4 v160, s[66:67]
	s_mov_b32 m0, s25
	s_nop 0
	global_load_lds_dwordx4 v154, s[20:21]
	s_mov_b32 m0, s26
	s_nop 0
	global_load_lds_dwordx4 v158, s[20:21]
	s_waitcnt vmcnt(8)
	s_waitcnt lgkmcnt(0)
	s_barrier
	s_waitcnt lgkmcnt(0)
	v_mfma_f32_16x16x32_bf16 v[58:61], v[130:133], v[180:183], v[58:61]
	v_mfma_f32_16x16x32_bf16 v[58:61], v[134:137], v[188:191], v[58:61]
	v_mfma_f32_16x16x32_bf16 v[54:57], v[138:141], v[180:183], v[54:57]
	v_mfma_f32_16x16x32_bf16 v[54:57], v[142:145], v[188:191], v[54:57]
	v_mfma_f32_16x16x32_bf16 v[42:45], v[130:133], v[192:195], v[42:45]
	v_mfma_f32_16x16x32_bf16 v[42:45], v[134:137], v[196:199], v[42:45]
	v_mfma_f32_16x16x32_bf16 v[34:37], v[138:141], v[192:195], v[34:37]
	v_mfma_f32_16x16x32_bf16 v[34:37], v[142:145], v[196:199], v[34:37]
	v_mfma_f32_16x16x32_bf16 v[26:29], v[130:133], v[200:203], v[26:29]
	v_mfma_f32_16x16x32_bf16 v[26:29], v[134:137], v[204:207], v[26:29]
	v_mfma_f32_16x16x32_bf16 v[18:21], v[138:141], v[200:203], v[18:21]
	v_mfma_f32_16x16x32_bf16 v[18:21], v[142:145], v[204:207], v[18:21]
	v_mfma_f32_16x16x32_bf16 v[6:9], v[130:133], v[208:211], v[6:9]
	v_mfma_f32_16x16x32_bf16 v[6:9], v[134:137], v[212:215], v[6:9]
	v_mfma_f32_16x16x32_bf16 v[2:5], v[138:141], v[208:211], v[2:5]
	v_mfma_f32_16x16x32_bf16 v[2:5], v[142:145], v[212:215], v[2:5]
	v_mfma_f32_16x16x32_bf16 v[62:65], v[146:149], v[180:183], v[62:65]
	v_mfma_f32_16x16x32_bf16 v[62:65], v[150:153], v[188:191], v[62:65]
	v_mfma_f32_16x16x32_bf16 v[50:53], v[172:175], v[180:183], v[50:53]
	v_mfma_f32_16x16x32_bf16 v[50:53], v[176:179], v[188:191], v[50:53]
	v_mfma_f32_16x16x32_bf16 v[46:49], v[146:149], v[192:195], v[46:49]
	v_mfma_f32_16x16x32_bf16 v[46:49], v[150:153], v[196:199], v[46:49]
	v_mfma_f32_16x16x32_bf16 v[38:41], v[172:175], v[192:195], v[38:41]
	v_mfma_f32_16x16x32_bf16 v[38:41], v[176:179], v[196:199], v[38:41]
	v_mfma_f32_16x16x32_bf16 v[30:33], v[146:149], v[200:203], v[30:33]
	v_mfma_f32_16x16x32_bf16 v[30:33], v[150:153], v[204:207], v[30:33]
	v_mfma_f32_16x16x32_bf16 v[22:25], v[172:175], v[200:203], v[22:25]
	v_mfma_f32_16x16x32_bf16 v[22:25], v[176:179], v[204:207], v[22:25]
	v_mfma_f32_16x16x32_bf16 v[10:13], v[146:149], v[208:211], v[10:13]
	v_mfma_f32_16x16x32_bf16 v[10:13], v[150:153], v[212:215], v[10:13]
	v_mfma_f32_16x16x32_bf16 v[14:17], v[172:175], v[208:211], v[14:17]
	v_mfma_f32_16x16x32_bf16 v[14:17], v[176:179], v[212:215], v[14:17]
	s_barrier
; #define PG8_STAGE(bufoff, gbase, voff) do { _Pragma("unroll") for (int _i = 0; _i < 2; ++_i) \
;         __builtin_amdgcn_global_load_lds((const unsigned*)((const char*)(gbase) + (voff)[_i]), (PG8_LAS unsigned*)(lds + (bufoff) + ldsw + _i * 8192), 16, 0, 0); } while (0)
; #define PG8_LDA(dst, b, h) do { _Pragma("unroll") for (int m = 0; m < 4; ++m) _Pragma("unroll") for (int k = 0; k < 2; ++k) dst[m][k] = *(const PG8_LAS bf16x8*)(lds + PG8_SA(b, h) + aoff + m * 2048 + k * 1024); } while (0)
; #define PG8_LDB(dst, b, h) do { _Pragma("unroll") for (int n = 0; n < 2; ++n) _Pragma("unroll") for (int k = 0; k < 2; ++k) dst[n][k] = *(const PG8_LAS bf16x8*)(lds + PG8_SB(b, h) + boff + n * 2048 + k * 1024); } while (0)
; #define PG8_MMA(ai, bj, At, Bt) do { __builtin_amdgcn_s_setprio(1); _Pragma("unroll") for (int m = 0; m < 4; ++m) _Pragma("unroll") for (int n = 0; n < 2; ++n) _Pragma("unroll") for (int k = 0; k < 2; ++k) \
;         acc[ai][bj][m][n] = __builtin_amdgcn_mfma_f32_16x16x32_bf16(Bt[n][k], At[m][k], acc[ai][bj][m][n], 0, 0, 0); __builtin_amdgcn_s_setprio(0); } while (0)
; #define PG8_WAIT_V(n) asm volatile("s_waitcnt vmcnt(" #n ")" ::: "memory")
; #define PG8_WAIT_L(n) asm volatile("s_waitcnt lgkmcnt(" #n ")" ::: "memory")
; #define PG8_BAR __builtin_amdgcn_s_barrier()
; #define PG8_SCHED __builtin_amdgcn_sched_barrier(0)
; template <class Epi, class Sched, bool ALIGN_EPI = false, bool SP2 = false>
; __device__ __forceinline__ void gemm_phase(PG8_LAS unsigned char* lds, const Gemm g, const Sched& S, const Epi& E) {
;     ...
;             PG8_LDB(B0, 1, 0); PG8_LDB(B1, 1, 1); PG8_SCHED; PG8_LDA(At, 1, 0); PG8_STAGE(PG8_SA(0, 1), a2 + hstep, voffA);
;             PG8_WAIT_V(8); PG8_WAIT_L(0); PG8_BAR; PG8_MMA(0, 0, At, B0); PG8_MMA(0, 1, At, B1); PG8_BAR; PG8_SCHED;
;             PG8_LDA(At, 1, 1); PG8_STAGE(PG8_SB(1, 0), b3, voffB); PG8_STAGE(PG8_SB(1, 1), b3 + hstep, voffB); PG8_STAGE(PG8_SA(1, 0), a3, voffA);
;             PG8_WAIT_V(8); PG8_WAIT_L(0); PG8_BAR; PG8_MMA(1, 0, At, B0); PG8_MMA(1, 1, At, B1); PG8_BAR; PG8_SCHED;
	s_add_i32 s33, 0, 0x18000
	s_add_i32 s42, 0, 0x1c000
	ds_read_b128 v[130:133], v241 offset:32768
	ds_read_b128 v[134:137], v241 offset:33792
	ds_read_b128 v[138:141], v241 offset:34816
	ds_read_b128 v[142:145], v241 offset:35840
	ds_read_b128 v[146:149], v241 offset:49152
	ds_read_b128 v[150:153], v241 offset:50176
	ds_read_b128 v[172:175], v241 offset:51200
	ds_read_b128 v[176:179], v241 offset:52224
	s_add_u32 s20, s20, 0x2b0000
	s_addc_u32 s21, s21, 0
	s_mov_b32 m0, s27
	ds_read_b128 v[180:183], v185 offset:32768
	ds_read_b128 v[188:191], v185 offset:33792
	ds_read_b128 v[192:195], v185 offset:34816
	ds_read_b128 v[196:199], v185 offset:35840
	ds_read_b128 v[200:203], v185 offset:36864
	ds_read_b128 v[204:207], v185 offset:37888
	ds_read_b128 v[208:211], v185 offset:38912
	ds_read_b128 v[212:215], v185 offset:39936
	global_load_lds_dwordx4 v154, s[20:21]
	s_mov_b32 m0, s28
	s_nop 0
	global_load_lds_dwordx4 v158, s[20:21]
	s_waitcnt vmcnt(8)
	s_waitcnt lgkmcnt(0)
	s_barrier
	s_waitcnt lgkmcnt(0)
	v_mfma_f32_16x16x32_bf16 v[114:117], v[130:133], v[180:183], v[114:117]
	v_mfma_f32_16x16x32_bf16 v[114:117], v[134:137], v[188:191], v[114:117]
	v_mfma_f32_16x16x32_bf16 v[118:121], v[138:141], v[180:183], v[118:121]
	v_mfma_f32_16x16x32_bf16 v[118:121], v[142:145], v[188:191], v[118:121]
	v_mfma_f32_16x16x32_bf16 v[106:109], v[130:133], v[192:195], v[106:109]
	v_mfma_f32_16x16x32_bf16 v[106:109], v[134:137], v[196:199], v[106:109]
	v_mfma_f32_16x16x32_bf16 v[98:101], v[138:141], v[192:195], v[98:101]
	v_mfma_f32_16x16x32_bf16 v[98:101], v[142:145], v[196:199], v[98:101]
	v_mfma_f32_16x16x32_bf16 v[90:93], v[130:133], v[200:203], v[90:93]
	v_mfma_f32_16x16x32_bf16 v[90:93], v[134:137], v[204:207], v[90:93]
	v_mfma_f32_16x16x32_bf16 v[82:85], v[138:141], v[200:203], v[82:85]
	v_mfma_f32_16x16x32_bf16 v[82:85], v[142:145], v[204:207], v[82:85]
	v_mfma_f32_16x16x32_bf16 v[74:77], v[130:133], v[208:211], v[74:77]
	v_mfma_f32_16x16x32_bf16 v[74:77], v[134:137], v[212:215], v[74:77]
	v_mfma_f32_16x16x32_bf16 v[66:69], v[138:141], v[208:211], v[66:69]
	v_mfma_f32_16x16x32_bf16 v[66:69], v[142:145], v[212:215], v[66:69]
	v_mfma_f32_16x16x32_bf16 v[122:125], v[146:149], v[180:183], v[122:125]
	v_mfma_f32_16x16x32_bf16 v[122:125], v[150:153], v[188:191], v[122:125]
	v_mfma_f32_16x16x32_bf16 v[126:129], v[172:175], v[180:183], v[126:129]
	v_mfma_f32_16x16x32_bf16 v[126:129], v[176:179], v[188:191], v[126:129]
	v_mfma_f32_16x16x32_bf16 v[110:113], v[146:149], v[192:195], v[110:113]
	v_mfma_f32_16x16x32_bf16 v[110:113], v[150:153], v[196:199], v[110:113]
	v_mfma_f32_16x16x32_bf16 v[102:105], v[172:175], v[192:195], v[102:105]
	v_mfma_f32_16x16x32_bf16 v[102:105], v[176:179], v[196:199], v[102:105]
	v_mfma_f32_16x16x32_bf16 v[94:97], v[146:149], v[200:203], v[94:97]
	v_mfma_f32_16x16x32_bf16 v[94:97], v[150:153], v[204:207], v[94:97]
	v_mfma_f32_16x16x32_bf16 v[86:89], v[172:175], v[200:203], v[86:89]
	v_mfma_f32_16x16x32_bf16 v[86:89], v[176:179], v[204:207], v[86:89]
	v_mfma_f32_16x16x32_bf16 v[78:81], v[146:149], v[208:211], v[78:81]
	v_mfma_f32_16x16x32_bf16 v[78:81], v[150:153], v[212:215], v[78:81]
	v_mfma_f32_16x16x32_bf16 v[70:73], v[172:175], v[208:211], v[70:73]
	v_mfma_f32_16x16x32_bf16 v[70:73], v[176:179], v[212:215], v[70:73]
	s_barrier
	s_add_i32 s20, s33, s24
	s_add_i32 m0, s20, 0xffffff80
	ds_read_b128 v[180:183], v185 offset:49152
	ds_read_b128 v[188:191], v185 offset:50176
	ds_read_b128 v[192:195], v185 offset:51200
	ds_read_b128 v[196:199], v185 offset:52224
	ds_read_b128 v[200:203], v185 offset:53248
	ds_read_b128 v[204:207], v185 offset:54272
	ds_read_b128 v[208:211], v185 offset:55296
	ds_read_b128 v[212:215], v185 offset:56320
	global_load_lds_dwordx4 v156, s[16:17] offset:128
	s_add_i32 m0, s20, 0x1f80
	s_add_i32 s20, s42, s24
	global_load_lds_dwordx4 v160, s[16:17] offset:128
	s_add_u32 s16, s16, 0x2b0080
	s_addc_u32 s17, s17, 0
	s_mov_b32 m0, s20
	s_nop 0
	global_load_lds_dwordx4 v156, s[16:17]
	s_add_i32 m0, s20, 0x2000
	s_nop 0
	global_load_lds_dwordx4 v160, s[16:17]
	s_mov_b32 m0, s34
	s_nop 0
	global_load_lds_dwordx4 v154, s[100:101]
	s_mov_b32 m0, s35
	s_nop 0
	global_load_lds_dwordx4 v158, s[100:101]
	s_waitcnt vmcnt(8)
	s_waitcnt lgkmcnt(0)
	s_barrier
	s_waitcnt lgkmcnt(0)
	v_mfma_f32_16x16x32_bf16 v[58:61], v[130:133], v[180:183], v[58:61]
	v_mfma_f32_16x16x32_bf16 v[58:61], v[134:137], v[188:191], v[58:61]
	v_mfma_f32_16x16x32_bf16 v[54:57], v[138:141], v[180:183], v[54:57]
	v_mfma_f32_16x16x32_bf16 v[54:57], v[142:145], v[188:191], v[54:57]
	v_mfma_f32_16x16x32_bf16 v[42:45], v[130:133], v[192:195], v[42:45]
	v_mfma_f32_16x16x32_bf16 v[42:45], v[134:137], v[196:199], v[42:45]
	v_mfma_f32_16x16x32_bf16 v[34:37], v[138:141], v[192:195], v[34:37]
	v_mfma_f32_16x16x32_bf16 v[34:37], v[142:145], v[196:199], v[34:37]
	v_mfma_f32_16x16x32_bf16 v[26:29], v[130:133], v[200:203], v[26:29]
	v_mfma_f32_16x16x32_bf16 v[26:29], v[134:137], v[204:207], v[26:29]
	v_mfma_f32_16x16x32_bf16 v[18:21], v[138:141], v[200:203], v[18:21]
	v_mfma_f32_16x16x32_bf16 v[18:21], v[142:145], v[204:207], v[18:21]
	v_mfma_f32_16x16x32_bf16 v[6:9], v[130:133], v[208:211], v[6:9]
	v_mfma_f32_16x16x32_bf16 v[6:9], v[134:137], v[212:215], v[6:9]
	v_mfma_f32_16x16x32_bf16 v[2:5], v[138:141], v[208:211], v[2:5]
	v_mfma_f32_16x16x32_bf16 v[2:5], v[142:145], v[212:215], v[2:5]
	v_mfma_f32_16x16x32_bf16 v[62:65], v[146:149], v[180:183], v[62:65]
	v_mfma_f32_16x16x32_bf16 v[62:65], v[150:153], v[188:191], v[62:65]
	v_mfma_f32_16x16x32_bf16 v[50:53], v[172:175], v[180:183], v[50:53]
	v_mfma_f32_16x16x32_bf16 v[50:53], v[176:179], v[188:191], v[50:53]
	v_mfma_f32_16x16x32_bf16 v[46:49], v[146:149], v[192:195], v[46:49]
	v_mfma_f32_16x16x32_bf16 v[46:49], v[150:153], v[196:199], v[46:49]
	v_mfma_f32_16x16x32_bf16 v[38:41], v[172:175], v[192:195], v[38:41]
	v_mfma_f32_16x16x32_bf16 v[38:41], v[176:179], v[196:199], v[38:41]
	v_mfma_f32_16x16x32_bf16 v[30:33], v[146:149], v[200:203], v[30:33]
	v_mfma_f32_16x16x32_bf16 v[30:33], v[150:153], v[204:207], v[30:33]
	v_mfma_f32_16x16x32_bf16 v[22:25], v[172:175], v[200:203], v[22:25]
	v_mfma_f32_16x16x32_bf16 v[22:25], v[176:179], v[204:207], v[22:25]
	v_mfma_f32_16x16x32_bf16 v[10:13], v[146:149], v[208:211], v[10:13]
	v_mfma_f32_16x16x32_bf16 v[10:13], v[150:153], v[212:215], v[10:13]
	v_mfma_f32_16x16x32_bf16 v[14:17], v[172:175], v[208:211], v[14:17]
	v_mfma_f32_16x16x32_bf16 v[14:17], v[176:179], v[212:215], v[14:17]
	s_barrier
	s_add_i32 s64, s64, 2
	s_add_u32 s18, s18, 0x100
	s_addc_u32 s19, s19, 0
	s_add_u32 s62, s62, 0x100
	s_addc_u32 s63, s63, 0
	s_cmpk_gt_u32 s64, 0xa9
	s_cbranch_scc0 .LBB0_1245
	s_and_b64 vcc, exec, s[12:13]
	s_cbranch_vccz .LBB0_1248
	s_barrier

; #define PG8_STAGE(bufoff, gbase, voff) do { _Pragma("unroll") for (int _i = 0; _i < 2; ++_i) \
;         __builtin_amdgcn_global_load_lds((const unsigned*)((const char*)(gbase) + (voff)[_i]), (PG8_LAS unsigned*)(lds + (bufoff) + ldsw + _i * 8192), 16, 0, 0); } while (0)
; #define PG8_LDA(dst, b, h) do { _Pragma("unroll") for (int m = 0; m < 4; ++m) _Pragma("unroll") for (int k = 0; k < 2; ++k) dst[m][k] = *(const PG8_LAS bf16x8*)(lds + PG8_SA(b, h) + aoff + m * 2048 + k * 1024); } while (0)
; #define PG8_LDB(dst, b, h) do { _Pragma("unroll") for (int n = 0; n < 2; ++n) _Pragma("unroll") for (int k = 0; k < 2; ++k) dst[n][k] = *(const PG8_LAS bf16x8*)(lds + PG8_SB(b, h) + boff + n * 2048 + k * 1024); } while (0)
; #define PG8_MMA(ai, bj, At, Bt) do { __builtin_amdgcn_s_setprio(1); _Pragma("unroll") for (int m = 0; m < 4; ++m) _Pragma("unroll") for (int n = 0; n < 2; ++n) _Pragma("unroll") for (int k = 0; k < 2; ++k) \
;         acc[ai][bj][m][n] = __builtin_amdgcn_mfma_f32_16x16x32_bf16(Bt[n][k], At[m][k], acc[ai][bj][m][n], 0, 0, 0); __builtin_amdgcn_s_setprio(0); } while (0)
; #define PG8_WAIT_V(n) asm volatile("s_waitcnt vmcnt(" #n ")" ::: "memory")
; #define PG8_BAR __builtin_amdgcn_s_barrier()
; template <class Epi, class Sched, bool ALIGN_EPI = false, bool SP2 = false>
; __device__ __forceinline__ void gemm_phase(PG8_LAS unsigned char* lds, const Gemm g, const Sched& S, const Epi& E) {
;     ...
;         for (int t = 0; t < nt; t += 2) {
;             const bool last = (t == nt - 2);
;             const char* a1 = cA + (size_t)(t + 1) * kstep;
;             const char* a2 = last ? nA : cA + (size_t)(t + 2) * kstep; const char* b2 = last ? nB : cB + (size_t)(t + 2) * kstep;
;             const char* a3 = a2 + kstep; const char* b3 = b2 + kstep;
;             if (last && has_next) S.a_ready(nxt);
;             if constexpr (SP2) {
;             PG8_LDB(B0, 0, 0); PG8_LDB(B1, 0, 1); PG8_SCHED; PG8_LDA(At, 0, 0); PG8_STAGE(PG8_SA(1, 1), a1 + hstep, voffA);
;             PG8_WAIT_V(8); PG8_WAIT_L(0); PG8_BAR; PG8_MMA(0, 0, At, B0); PG8_MMA(0, 1, At, B1); PG8_BAR; PG8_SCHED;
;             PG8_LDA(At, 0, 1); PG8_STAGE(PG8_SB(0, 0), b2, voffB); PG8_STAGE(PG8_SB(0, 1), b2 + hstep, voffB); PG8_STAGE(PG8_SA(0, 0), a2, voffA);
;             PG8_WAIT_V(8); PG8_WAIT_L(0); PG8_BAR; PG8_MMA(1, 0, At, B0); PG8_MMA(1, 1, At, B1); PG8_BAR; PG8_SCHED;
.LBB0_1332:
	ds_read_b128 v[148:151], v241 offset:0
	ds_read_b128 v[156:159], v241 offset:1024
	ds_read_b128 v[166:169], v241 offset:2048
	ds_read_b128 v[170:173], v241 offset:3072
	ds_read_b128 v[174:177], v241 offset:16384
	ds_read_b128 v[178:181], v241 offset:17408
	ds_read_b128 v[182:185], v241 offset:18432
	ds_read_b128 v[186:189], v241 offset:19456
	s_add_u32 s20, s22, 0xfff00080
	s_addc_u32 s21, s23, -1
	s_cmp_eq_u32 s67, 60
	s_cselect_b32 s25, s13, s21
	s_cselect_b32 s24, s63, s20
	s_cselect_b32 s21, s11, s66
	s_cselect_b32 s20, s64, s65
	s_add_i32 m0, s19, 0xc000
	ds_read_b128 v[190:193], v155
	ds_read_b128 v[194:197], v155 offset:1024
	ds_read_b128 v[198:201], v155 offset:2048
	ds_read_b128 v[202:205], v155 offset:3072
	ds_read_b128 v[206:209], v155 offset:4096
	ds_read_b128 v[210:213], v155 offset:5120
	ds_read_b128 v[214:217], v155 offset:6144
	ds_read_b128 v[218:221], v155 offset:7168
	global_load_lds_dwordx4 v138, s[22:23]
	s_add_i32 m0, s19, 0xe000
	s_nop 0
	global_load_lds_dwordx4 v140, s[22:23]
	s_waitcnt vmcnt(8)
	s_waitcnt lgkmcnt(0)
	s_barrier
	s_waitcnt lgkmcnt(0)
	v_mfma_f32_16x16x32_bf16 v[118:121], v[148:151], v[190:193], v[118:121]
	v_mfma_f32_16x16x32_bf16 v[118:121], v[156:159], v[194:197], v[118:121]
	v_mfma_f32_16x16x32_bf16 v[114:117], v[166:169], v[190:193], v[114:117]
	v_mfma_f32_16x16x32_bf16 v[114:117], v[170:173], v[194:197], v[114:117]
	v_mfma_f32_16x16x32_bf16 v[102:105], v[148:151], v[198:201], v[102:105]
	v_mfma_f32_16x16x32_bf16 v[102:105], v[156:159], v[202:205], v[102:105]
	v_mfma_f32_16x16x32_bf16 v[98:101], v[166:169], v[198:201], v[98:101]
	v_mfma_f32_16x16x32_bf16 v[98:101], v[170:173], v[202:205], v[98:101]
	v_mfma_f32_16x16x32_bf16 v[86:89], v[148:151], v[206:209], v[86:89]
	v_mfma_f32_16x16x32_bf16 v[86:89], v[156:159], v[210:213], v[86:89]
	v_mfma_f32_16x16x32_bf16 v[82:85], v[166:169], v[206:209], v[82:85]
	v_mfma_f32_16x16x32_bf16 v[82:85], v[170:173], v[210:213], v[82:85]
	v_mfma_f32_16x16x32_bf16 v[70:73], v[148:151], v[214:217], v[70:73]
	v_mfma_f32_16x16x32_bf16 v[70:73], v[156:159], v[218:221], v[70:73]
	v_mfma_f32_16x16x32_bf16 v[66:69], v[166:169], v[214:217], v[66:69]
	v_mfma_f32_16x16x32_bf16 v[66:69], v[170:173], v[218:221], v[66:69]
	v_mfma_f32_16x16x32_bf16 v[126:129], v[174:177], v[190:193], v[126:129]
	v_mfma_f32_16x16x32_bf16 v[126:129], v[178:181], v[194:197], v[126:129]
	v_mfma_f32_16x16x32_bf16 v[122:125], v[182:185], v[190:193], v[122:125]
	v_mfma_f32_16x16x32_bf16 v[122:125], v[186:189], v[194:197], v[122:125]
	v_mfma_f32_16x16x32_bf16 v[110:113], v[174:177], v[198:201], v[110:113]
	v_mfma_f32_16x16x32_bf16 v[110:113], v[178:181], v[202:205], v[110:113]
	v_mfma_f32_16x16x32_bf16 v[106:109], v[182:185], v[198:201], v[106:109]
	v_mfma_f32_16x16x32_bf16 v[106:109], v[186:189], v[202:205], v[106:109]
	v_mfma_f32_16x16x32_bf16 v[94:97], v[174:177], v[206:209], v[94:97]
	v_mfma_f32_16x16x32_bf16 v[94:97], v[178:181], v[210:213], v[94:97]
	v_mfma_f32_16x16x32_bf16 v[90:93], v[182:185], v[206:209], v[90:93]
	v_mfma_f32_16x16x32_bf16 v[90:93], v[186:189], v[210:213], v[90:93]
	v_mfma_f32_16x16x32_bf16 v[78:81], v[174:177], v[214:217], v[78:81]
	v_mfma_f32_16x16x32_bf16 v[78:81], v[178:181], v[218:221], v[78:81]
	v_mfma_f32_16x16x32_bf16 v[74:77], v[182:185], v[214:217], v[74:77]
	v_mfma_f32_16x16x32_bf16 v[74:77], v[186:189], v[218:221], v[74:77]
	s_barrier
	s_add_i32 s33, s47, s28
	s_mov_b32 m0, s33
	ds_read_b128 v[190:193], v155 offset:16384
	ds_read_b128 v[194:197], v155 offset:17408
	ds_read_b128 v[198:201], v155 offset:18432
	ds_read_b128 v[202:205], v155 offset:19456
	ds_read_b128 v[206:209], v155 offset:20480
	ds_read_b128 v[210:213], v155 offset:21504
	ds_read_b128 v[214:217], v155 offset:22528
	ds_read_b128 v[218:221], v155 offset:23552
	global_load_lds_dwordx4 v132, s[20:21]
	s_add_i32 m0, s33, 0x2000
	s_add_u32 s68, s20, 0x100000
	s_addc_u32 s69, s21, 0
	s_add_i32 s33, s52, s28
	global_load_lds_dwordx4 v136, s[20:21]
	s_mov_b32 m0, s33
	s_add_u32 s100, s24, 0x80
	s_addc_u32 s101, s25, 0
	global_load_lds_dwordx4 v132, s[68:69]
	s_add_i32 m0, s33, 0x2000
	s_nop 0
	global_load_lds_dwordx4 v136, s[68:69]
	s_mov_b32 m0, s19
	s_nop 0
	global_load_lds_dwordx4 v130, s[24:25]
	s_mov_b32 m0, s35
	s_nop 0
	global_load_lds_dwordx4 v134, s[24:25]
	s_waitcnt vmcnt(8)
	s_waitcnt lgkmcnt(0)
	s_barrier
	s_waitcnt lgkmcnt(0)
	v_mfma_f32_16x16x32_bf16 v[54:57], v[148:151], v[190:193], v[54:57]
	v_mfma_f32_16x16x32_bf16 v[54:57], v[156:159], v[194:197], v[54:57]
	v_mfma_f32_16x16x32_bf16 v[50:53], v[166:169], v[190:193], v[50:53]
	v_mfma_f32_16x16x32_bf16 v[50:53], v[170:173], v[194:197], v[50:53]
	v_mfma_f32_16x16x32_bf16 v[38:41], v[148:151], v[198:201], v[38:41]
	v_mfma_f32_16x16x32_bf16 v[38:41], v[156:159], v[202:205], v[38:41]
	v_mfma_f32_16x16x32_bf16 v[34:37], v[166:169], v[198:201], v[34:37]
	v_mfma_f32_16x16x32_bf16 v[34:37], v[170:173], v[202:205], v[34:37]
	v_mfma_f32_16x16x32_bf16 v[22:25], v[148:151], v[206:209], v[22:25]
	v_mfma_f32_16x16x32_bf16 v[22:25], v[156:159], v[210:213], v[22:25]
	v_mfma_f32_16x16x32_bf16 v[18:21], v[166:169], v[206:209], v[18:21]
	v_mfma_f32_16x16x32_bf16 v[18:21], v[170:173], v[210:213], v[18:21]
	v_mfma_f32_16x16x32_bf16 v[6:9], v[148:151], v[214:217], v[6:9]
	v_mfma_f32_16x16x32_bf16 v[6:9], v[156:159], v[218:221], v[6:9]
	v_mfma_f32_16x16x32_bf16 v[2:5], v[166:169], v[214:217], v[2:5]
	v_mfma_f32_16x16x32_bf16 v[2:5], v[170:173], v[218:221], v[2:5]
	v_mfma_f32_16x16x32_bf16 v[62:65], v[174:177], v[190:193], v[62:65]
	v_mfma_f32_16x16x32_bf16 v[62:65], v[178:181], v[194:197], v[62:65]
	v_mfma_f32_16x16x32_bf16 v[58:61], v[182:185], v[190:193], v[58:61]
	v_mfma_f32_16x16x32_bf16 v[58:61], v[186:189], v[194:197], v[58:61]
	v_mfma_f32_16x16x32_bf16 v[46:49], v[174:177], v[198:201], v[46:49]
	v_mfma_f32_16x16x32_bf16 v[46:49], v[178:181], v[202:205], v[46:49]
	v_mfma_f32_16x16x32_bf16 v[42:45], v[182:185], v[198:201], v[42:45]
	v_mfma_f32_16x16x32_bf16 v[42:45], v[186:189], v[202:205], v[42:45]
	v_mfma_f32_16x16x32_bf16 v[30:33], v[174:177], v[206:209], v[30:33]
	v_mfma_f32_16x16x32_bf16 v[30:33], v[178:181], v[210:213], v[30:33]
	v_mfma_f32_16x16x32_bf16 v[26:29], v[182:185], v[206:209], v[26:29]
	v_mfma_f32_16x16x32_bf16 v[26:29], v[186:189], v[210:213], v[26:29]
	v_mfma_f32_16x16x32_bf16 v[10:13], v[174:177], v[214:217], v[10:13]
	v_mfma_f32_16x16x32_bf16 v[10:13], v[178:181], v[218:221], v[10:13]
	v_mfma_f32_16x16x32_bf16 v[14:17], v[182:185], v[214:217], v[14:17]
	v_mfma_f32_16x16x32_bf16 v[14:17], v[186:189], v[218:221], v[14:17]
	s_barrier
; #define PG8_STAGE(bufoff, gbase, voff) do { _Pragma("unroll") for (int _i = 0; _i < 2; ++_i) \
;         __builtin_amdgcn_global_load_lds((const unsigned*)((const char*)(gbase) + (voff)[_i]), (PG8_LAS unsigned*)(lds + (bufoff) + ldsw + _i * 8192), 16, 0, 0); } while (0)
; #define PG8_LDA(dst, b, h) do { _Pragma("unroll") for (int m = 0; m < 4; ++m) _Pragma("unroll") for (int k = 0; k < 2; ++k) dst[m][k] = *(const PG8_LAS bf16x8*)(lds + PG8_SA(b, h) + aoff + m * 2048 + k * 1024); } while (0)
; #define PG8_LDB(dst, b, h) do { _Pragma("unroll") for (int n = 0; n < 2; ++n) _Pragma("unroll") for (int k = 0; k < 2; ++k) dst[n][k] = *(const PG8_LAS bf16x8*)(lds + PG8_SB(b, h) + boff + n * 2048 + k * 1024); } while (0)
; #define PG8_MMA(ai, bj, At, Bt) do { __builtin_amdgcn_s_setprio(1); _Pragma("unroll") for (int m = 0; m < 4; ++m) _Pragma("unroll") for (int n = 0; n < 2; ++n) _Pragma("unroll") for (int k = 0; k < 2; ++k) \
;         acc[ai][bj][m][n] = __builtin_amdgcn_mfma_f32_16x16x32_bf16(Bt[n][k], At[m][k], acc[ai][bj][m][n], 0, 0, 0); __builtin_amdgcn_s_setprio(0); } while (0)
; #define PG8_WAIT_V(n) asm volatile("s_waitcnt vmcnt(" #n ")" ::: "memory")
; #define PG8_WAIT_L(n) asm volatile("s_waitcnt lgkmcnt(" #n ")" ::: "memory")
; #define PG8_BAR __builtin_amdgcn_s_barrier()
; #define PG8_SCHED __builtin_amdgcn_sched_barrier(0)
; template <class Epi, class Sched, bool ALIGN_EPI = false, bool SP2 = false>
; __device__ __forceinline__ void gemm_phase(PG8_LAS unsigned char* lds, const Gemm g, const Sched& S, const Epi& E) {
;     ...
;             PG8_LDB(B0, 1, 0); PG8_LDB(B1, 1, 1); PG8_SCHED; PG8_LDA(At, 1, 0); PG8_STAGE(PG8_SA(0, 1), a2 + hstep, voffA);
;             PG8_WAIT_V(8); PG8_WAIT_L(0); PG8_BAR; PG8_MMA(0, 0, At, B0); PG8_MMA(0, 1, At, B1); PG8_BAR; PG8_SCHED;
;             PG8_LDA(At, 1, 1); PG8_STAGE(PG8_SB(1, 0), b3, voffB); PG8_STAGE(PG8_SB(1, 1), b3 + hstep, voffB); PG8_STAGE(PG8_SA(1, 0), a3, voffA);
;             PG8_WAIT_V(8); PG8_WAIT_L(0); PG8_BAR; PG8_MMA(1, 0, At, B0); PG8_MMA(1, 1, At, B1); PG8_BAR; PG8_SCHED;
	s_add_i32 s33, 0, 0x18000
	s_add_i32 s42, 0, 0x1c000
	ds_read_b128 v[148:151], v241 offset:32768
	ds_read_b128 v[156:159], v241 offset:33792
	ds_read_b128 v[166:169], v241 offset:34816
	ds_read_b128 v[170:173], v241 offset:35840
	ds_read_b128 v[174:177], v241 offset:49152
	ds_read_b128 v[178:181], v241 offset:50176
	ds_read_b128 v[182:185], v241 offset:51200
	ds_read_b128 v[186:189], v241 offset:52224
	s_add_u32 s24, s24, 0x100000
	s_addc_u32 s25, s25, 0
	s_mov_b32 m0, s36
	ds_read_b128 v[190:193], v155 offset:32768
	ds_read_b128 v[194:197], v155 offset:33792
	ds_read_b128 v[198:201], v155 offset:34816
	ds_read_b128 v[202:205], v155 offset:35840
	ds_read_b128 v[206:209], v155 offset:36864
	ds_read_b128 v[210:213], v155 offset:37888
	ds_read_b128 v[214:217], v155 offset:38912
	ds_read_b128 v[218:221], v155 offset:39936
	global_load_lds_dwordx4 v130, s[24:25]
	s_mov_b32 m0, s37
	s_nop 0
	global_load_lds_dwordx4 v134, s[24:25]
	s_waitcnt vmcnt(8)
	s_waitcnt lgkmcnt(0)
	s_barrier
	s_waitcnt lgkmcnt(0)
	v_mfma_f32_16x16x32_bf16 v[118:121], v[148:151], v[190:193], v[118:121]
	v_mfma_f32_16x16x32_bf16 v[118:121], v[156:159], v[194:197], v[118:121]
	v_mfma_f32_16x16x32_bf16 v[114:117], v[166:169], v[190:193], v[114:117]
	v_mfma_f32_16x16x32_bf16 v[114:117], v[170:173], v[194:197], v[114:117]
	v_mfma_f32_16x16x32_bf16 v[102:105], v[148:151], v[198:201], v[102:105]
	v_mfma_f32_16x16x32_bf16 v[102:105], v[156:159], v[202:205], v[102:105]
	v_mfma_f32_16x16x32_bf16 v[98:101], v[166:169], v[198:201], v[98:101]
	v_mfma_f32_16x16x32_bf16 v[98:101], v[170:173], v[202:205], v[98:101]
	v_mfma_f32_16x16x32_bf16 v[86:89], v[148:151], v[206:209], v[86:89]
	v_mfma_f32_16x16x32_bf16 v[86:89], v[156:159], v[210:213], v[86:89]
	v_mfma_f32_16x16x32_bf16 v[82:85], v[166:169], v[206:209], v[82:85]
	v_mfma_f32_16x16x32_bf16 v[82:85], v[170:173], v[210:213], v[82:85]
	v_mfma_f32_16x16x32_bf16 v[70:73], v[148:151], v[214:217], v[70:73]
	v_mfma_f32_16x16x32_bf16 v[70:73], v[156:159], v[218:221], v[70:73]
	v_mfma_f32_16x16x32_bf16 v[66:69], v[166:169], v[214:217], v[66:69]
	v_mfma_f32_16x16x32_bf16 v[66:69], v[170:173], v[218:221], v[66:69]
	v_mfma_f32_16x16x32_bf16 v[126:129], v[174:177], v[190:193], v[126:129]
	v_mfma_f32_16x16x32_bf16 v[126:129], v[178:181], v[194:197], v[126:129]
	v_mfma_f32_16x16x32_bf16 v[122:125], v[182:185], v[190:193], v[122:125]
	v_mfma_f32_16x16x32_bf16 v[122:125], v[186:189], v[194:197], v[122:125]
	v_mfma_f32_16x16x32_bf16 v[110:113], v[174:177], v[198:201], v[110:113]
	v_mfma_f32_16x16x32_bf16 v[110:113], v[178:181], v[202:205], v[110:113]
	v_mfma_f32_16x16x32_bf16 v[106:109], v[182:185], v[198:201], v[106:109]
	v_mfma_f32_16x16x32_bf16 v[106:109], v[186:189], v[202:205], v[106:109]
	v_mfma_f32_16x16x32_bf16 v[94:97], v[174:177], v[206:209], v[94:97]
	v_mfma_f32_16x16x32_bf16 v[94:97], v[178:181], v[210:213], v[94:97]
	v_mfma_f32_16x16x32_bf16 v[90:93], v[182:185], v[206:209], v[90:93]
	v_mfma_f32_16x16x32_bf16 v[90:93], v[186:189], v[210:213], v[90:93]
	v_mfma_f32_16x16x32_bf16 v[78:81], v[174:177], v[214:217], v[78:81]
	v_mfma_f32_16x16x32_bf16 v[78:81], v[178:181], v[218:221], v[78:81]
	v_mfma_f32_16x16x32_bf16 v[74:77], v[182:185], v[214:217], v[74:77]
	v_mfma_f32_16x16x32_bf16 v[74:77], v[186:189], v[218:221], v[74:77]
	s_barrier
	s_add_i32 s24, s33, s28
	s_add_i32 m0, s24, 0xffffff80
	ds_read_b128 v[190:193], v155 offset:49152
	ds_read_b128 v[194:197], v155 offset:50176
	ds_read_b128 v[198:201], v155 offset:51200
	ds_read_b128 v[202:205], v155 offset:52224
	ds_read_b128 v[206:209], v155 offset:53248
	ds_read_b128 v[210:213], v155 offset:54272
	ds_read_b128 v[214:217], v155 offset:55296
	ds_read_b128 v[218:221], v155 offset:56320
	global_load_lds_dwordx4 v132, s[20:21] offset:128
	s_add_i32 m0, s24, 0x1f80
	s_add_i32 s24, s42, s28
	global_load_lds_dwordx4 v136, s[20:21] offset:128
	s_add_u32 s20, s20, 0x100080
	s_addc_u32 s21, s21, 0
	s_mov_b32 m0, s24
	s_nop 0
	global_load_lds_dwordx4 v132, s[20:21]
	s_add_i32 m0, s24, 0x2000
	s_nop 0
	global_load_lds_dwordx4 v136, s[20:21]
	s_mov_b32 m0, s43
	s_nop 0
	global_load_lds_dwordx4 v130, s[100:101]
	s_mov_b32 m0, s46
	s_nop 0
	global_load_lds_dwordx4 v134, s[100:101]
	s_waitcnt vmcnt(8)
	s_waitcnt lgkmcnt(0)
	s_barrier
	s_waitcnt lgkmcnt(0)
	v_mfma_f32_16x16x32_bf16 v[54:57], v[148:151], v[190:193], v[54:57]
	v_mfma_f32_16x16x32_bf16 v[54:57], v[156:159], v[194:197], v[54:57]
	v_mfma_f32_16x16x32_bf16 v[50:53], v[166:169], v[190:193], v[50:53]
	v_mfma_f32_16x16x32_bf16 v[50:53], v[170:173], v[194:197], v[50:53]
	v_mfma_f32_16x16x32_bf16 v[38:41], v[148:151], v[198:201], v[38:41]
	v_mfma_f32_16x16x32_bf16 v[38:41], v[156:159], v[202:205], v[38:41]
	v_mfma_f32_16x16x32_bf16 v[34:37], v[166:169], v[198:201], v[34:37]
	v_mfma_f32_16x16x32_bf16 v[34:37], v[170:173], v[202:205], v[34:37]
	v_mfma_f32_16x16x32_bf16 v[22:25], v[148:151], v[206:209], v[22:25]
	v_mfma_f32_16x16x32_bf16 v[22:25], v[156:159], v[210:213], v[22:25]
	v_mfma_f32_16x16x32_bf16 v[18:21], v[166:169], v[206:209], v[18:21]
	v_mfma_f32_16x16x32_bf16 v[18:21], v[170:173], v[210:213], v[18:21]
	v_mfma_f32_16x16x32_bf16 v[6:9], v[148:151], v[214:217], v[6:9]
	v_mfma_f32_16x16x32_bf16 v[6:9], v[156:159], v[218:221], v[6:9]
	v_mfma_f32_16x16x32_bf16 v[2:5], v[166:169], v[214:217], v[2:5]
	v_mfma_f32_16x16x32_bf16 v[2:5], v[170:173], v[218:221], v[2:5]
	v_mfma_f32_16x16x32_bf16 v[62:65], v[174:177], v[190:193], v[62:65]
	v_mfma_f32_16x16x32_bf16 v[62:65], v[178:181], v[194:197], v[62:65]
	v_mfma_f32_16x16x32_bf16 v[58:61], v[182:185], v[190:193], v[58:61]
	v_mfma_f32_16x16x32_bf16 v[58:61], v[186:189], v[194:197], v[58:61]
	v_mfma_f32_16x16x32_bf16 v[46:49], v[174:177], v[198:201], v[46:49]
	v_mfma_f32_16x16x32_bf16 v[46:49], v[178:181], v[202:205], v[46:49]
	v_mfma_f32_16x16x32_bf16 v[42:45], v[182:185], v[198:201], v[42:45]
	v_mfma_f32_16x16x32_bf16 v[42:45], v[186:189], v[202:205], v[42:45]
	v_mfma_f32_16x16x32_bf16 v[30:33], v[174:177], v[206:209], v[30:33]
	v_mfma_f32_16x16x32_bf16 v[30:33], v[178:181], v[210:213], v[30:33]
	v_mfma_f32_16x16x32_bf16 v[26:29], v[182:185], v[206:209], v[26:29]
	v_mfma_f32_16x16x32_bf16 v[26:29], v[186:189], v[210:213], v[26:29]
	v_mfma_f32_16x16x32_bf16 v[10:13], v[174:177], v[214:217], v[10:13]
	v_mfma_f32_16x16x32_bf16 v[10:13], v[178:181], v[218:221], v[10:13]
	v_mfma_f32_16x16x32_bf16 v[14:17], v[182:185], v[214:217], v[14:17]
	v_mfma_f32_16x16x32_bf16 v[14:17], v[186:189], v[218:221], v[14:17]
	s_barrier
	s_add_i32 s67, s67, 2
	s_add_u32 s22, s22, 0x100
	s_addc_u32 s23, s23, 0
	s_add_u32 s65, s65, 0x100
	s_addc_u32 s66, s66, 0
	s_cmp_gt_u32 s67, 61
	s_cbranch_scc0 .LBB0_1332
	s_and_b64 vcc, exec, s[8:9]
	s_cbranch_vccz .LBB0_1335
	s_barrier

; #define PG8_STAGE(bufoff, gbase, voff) do { _Pragma("unroll") for (int _i = 0; _i < 2; ++_i) \
;         __builtin_amdgcn_global_load_lds((const unsigned*)((const char*)(gbase) + (voff)[_i]), (PG8_LAS unsigned*)(lds + (bufoff) + ldsw + _i * 8192), 16, 0, 0); } while (0)
; #define PG8_LDA(dst, b, h) do { _Pragma("unroll") for (int m = 0; m < 4; ++m) _Pragma("unroll") for (int k = 0; k < 2; ++k) dst[m][k] = *(const PG8_LAS bf16x8*)(lds + PG8_SA(b, h) + aoff + m * 2048 + k * 1024); } while (0)
; #define PG8_LDB(dst, b, h) do { _Pragma("unroll") for (int n = 0; n < 2; ++n) _Pragma("unroll") for (int k = 0; k < 2; ++k) dst[n][k] = *(const PG8_LAS bf16x8*)(lds + PG8_SB(b, h) + boff + n * 2048 + k * 1024); } while (0)
; #define PG8_MMA(ai, bj, At, Bt) do { __builtin_amdgcn_s_setprio(1); _Pragma("unroll") for (int m = 0; m < 4; ++m) _Pragma("unroll") for (int n = 0; n < 2; ++n) _Pragma("unroll") for (int k = 0; k < 2; ++k) \
;         acc[ai][bj][m][n] = __builtin_amdgcn_mfma_f32_16x16x32_bf16(Bt[n][k], At[m][k], acc[ai][bj][m][n], 0, 0, 0); __builtin_amdgcn_s_setprio(0); } while (0)
; #define PG8_WAIT_V(n) asm volatile("s_waitcnt vmcnt(" #n ")" ::: "memory")
; #define PG8_BAR __builtin_amdgcn_s_barrier()
; template <class Epi, class Sched, bool ALIGN_EPI = false, bool SP2 = false>
; __device__ __forceinline__ void gemm_phase(PG8_LAS unsigned char* lds, const Gemm g, const Sched& S, const Epi& E) {
;     ...
;         for (int t = 0; t < nt; t += 2) {
;             const bool last = (t == nt - 2);
;             const char* a1 = cA + (size_t)(t + 1) * kstep;
;             const char* a2 = last ? nA : cA + (size_t)(t + 2) * kstep; const char* b2 = last ? nB : cB + (size_t)(t + 2) * kstep;
;             const char* a3 = a2 + kstep; const char* b3 = b2 + kstep;
;             if (last && has_next) S.a_ready(nxt);
;             if constexpr (SP2) {
;             PG8_LDB(B0, 0, 0); PG8_LDB(B1, 0, 1); PG8_SCHED; PG8_LDA(At, 0, 0); PG8_STAGE(PG8_SA(1, 1), a1 + hstep, voffA);
;             PG8_WAIT_V(8); PG8_WAIT_L(0); PG8_BAR; PG8_MMA(0, 0, At, B0); PG8_MMA(0, 1, At, B1); PG8_BAR; PG8_SCHED;
;             PG8_LDA(At, 0, 1); PG8_STAGE(PG8_SB(0, 0), b2, voffB); PG8_STAGE(PG8_SB(0, 1), b2 + hstep, voffB); PG8_STAGE(PG8_SA(0, 0), a2, voffA);
;             PG8_WAIT_V(8); PG8_WAIT_L(0); PG8_BAR; PG8_MMA(1, 0, At, B0); PG8_MMA(1, 1, At, B1); PG8_BAR; PG8_SCHED;
.LBB0_1595:
	ds_read_b128 v[130:133], v241 offset:0
	ds_read_b128 v[134:137], v241 offset:1024
	ds_read_b128 v[138:141], v241 offset:2048
	ds_read_b128 v[142:145], v241 offset:3072
	ds_read_b128 v[146:149], v241 offset:16384
	ds_read_b128 v[150:153], v241 offset:17408
	ds_read_b128 v[172:175], v241 offset:18432
	ds_read_b128 v[176:179], v241 offset:19456
	s_add_u32 s24, s26, 0xfff00080
	s_addc_u32 s25, s27, -1
	s_cmp_eq_u32 s62, 60
	s_cselect_b32 s29, s15, s25
	s_cselect_b32 s28, s21, s24
	s_cselect_b32 s25, s13, s53
	s_cselect_b32 s24, s51, s52
	s_add_i32 m0, s23, 0xc000
	ds_read_b128 v[180:183], v185
	ds_read_b128 v[188:191], v185 offset:1024
	ds_read_b128 v[192:195], v185 offset:2048
	ds_read_b128 v[196:199], v185 offset:3072
	ds_read_b128 v[200:203], v185 offset:4096
	ds_read_b128 v[204:207], v185 offset:5120
	ds_read_b128 v[208:211], v185 offset:6144
	ds_read_b128 v[212:215], v185 offset:7168
	global_load_lds_dwordx4 v162, s[26:27]
	s_add_i32 m0, s23, 0xe000
	s_nop 0
	global_load_lds_dwordx4 v166, s[26:27]
	s_waitcnt vmcnt(8)
	s_waitcnt lgkmcnt(0)
	s_barrier
	s_waitcnt lgkmcnt(0)
	v_mfma_f32_16x16x32_bf16 v[114:117], v[130:133], v[180:183], v[114:117]
	v_mfma_f32_16x16x32_bf16 v[114:117], v[134:137], v[188:191], v[114:117]
	v_mfma_f32_16x16x32_bf16 v[118:121], v[138:141], v[180:183], v[118:121]
	v_mfma_f32_16x16x32_bf16 v[118:121], v[142:145], v[188:191], v[118:121]
	v_mfma_f32_16x16x32_bf16 v[106:109], v[130:133], v[192:195], v[106:109]
	v_mfma_f32_16x16x32_bf16 v[106:109], v[134:137], v[196:199], v[106:109]
	v_mfma_f32_16x16x32_bf16 v[98:101], v[138:141], v[192:195], v[98:101]
	v_mfma_f32_16x16x32_bf16 v[98:101], v[142:145], v[196:199], v[98:101]
	v_mfma_f32_16x16x32_bf16 v[90:93], v[130:133], v[200:203], v[90:93]
	v_mfma_f32_16x16x32_bf16 v[90:93], v[134:137], v[204:207], v[90:93]
	v_mfma_f32_16x16x32_bf16 v[82:85], v[138:141], v[200:203], v[82:85]
	v_mfma_f32_16x16x32_bf16 v[82:85], v[142:145], v[204:207], v[82:85]
	v_mfma_f32_16x16x32_bf16 v[74:77], v[130:133], v[208:211], v[74:77]
	v_mfma_f32_16x16x32_bf16 v[74:77], v[134:137], v[212:215], v[74:77]
	v_mfma_f32_16x16x32_bf16 v[66:69], v[138:141], v[208:211], v[66:69]
	v_mfma_f32_16x16x32_bf16 v[66:69], v[142:145], v[212:215], v[66:69]
	v_mfma_f32_16x16x32_bf16 v[122:125], v[146:149], v[180:183], v[122:125]
	v_mfma_f32_16x16x32_bf16 v[122:125], v[150:153], v[188:191], v[122:125]
	v_mfma_f32_16x16x32_bf16 v[126:129], v[172:175], v[180:183], v[126:129]
	v_mfma_f32_16x16x32_bf16 v[126:129], v[176:179], v[188:191], v[126:129]
	v_mfma_f32_16x16x32_bf16 v[110:113], v[146:149], v[192:195], v[110:113]
	v_mfma_f32_16x16x32_bf16 v[110:113], v[150:153], v[196:199], v[110:113]
	v_mfma_f32_16x16x32_bf16 v[102:105], v[172:175], v[192:195], v[102:105]
	v_mfma_f32_16x16x32_bf16 v[102:105], v[176:179], v[196:199], v[102:105]
	v_mfma_f32_16x16x32_bf16 v[94:97], v[146:149], v[200:203], v[94:97]
	v_mfma_f32_16x16x32_bf16 v[94:97], v[150:153], v[204:207], v[94:97]
	v_mfma_f32_16x16x32_bf16 v[86:89], v[172:175], v[200:203], v[86:89]
	v_mfma_f32_16x16x32_bf16 v[86:89], v[176:179], v[204:207], v[86:89]
	v_mfma_f32_16x16x32_bf16 v[78:81], v[146:149], v[208:211], v[78:81]
	v_mfma_f32_16x16x32_bf16 v[78:81], v[150:153], v[212:215], v[78:81]
	v_mfma_f32_16x16x32_bf16 v[70:73], v[172:175], v[208:211], v[70:73]
	v_mfma_f32_16x16x32_bf16 v[70:73], v[176:179], v[212:215], v[70:73]
	s_barrier
	s_add_i32 s33, s48, s36
	s_mov_b32 m0, s33
	ds_read_b128 v[180:183], v185 offset:16384
	ds_read_b128 v[188:191], v185 offset:17408
	ds_read_b128 v[192:195], v185 offset:18432
	ds_read_b128 v[196:199], v185 offset:19456
	ds_read_b128 v[200:203], v185 offset:20480
	ds_read_b128 v[204:207], v185 offset:21504
	ds_read_b128 v[208:211], v185 offset:22528
	ds_read_b128 v[212:215], v185 offset:23552
	global_load_lds_dwordx4 v156, s[24:25]
	s_add_i32 m0, s33, 0x2000
	s_add_u32 s64, s24, 0x100000
	s_addc_u32 s65, s25, 0
	s_add_i32 s33, s49, s36
	global_load_lds_dwordx4 v160, s[24:25]
	s_mov_b32 m0, s33
	s_add_u32 s100, s28, 0x80
	s_addc_u32 s101, s29, 0
	global_load_lds_dwordx4 v156, s[64:65]
	s_add_i32 m0, s33, 0x2000
	s_nop 0
	global_load_lds_dwordx4 v160, s[64:65]
	s_mov_b32 m0, s23
	s_nop 0
	global_load_lds_dwordx4 v154, s[28:29]
	s_mov_b32 m0, s37
	s_nop 0
	global_load_lds_dwordx4 v158, s[28:29]
	s_waitcnt vmcnt(8)
	s_waitcnt lgkmcnt(0)
	s_barrier
	s_waitcnt lgkmcnt(0)
	v_mfma_f32_16x16x32_bf16 v[58:61], v[130:133], v[180:183], v[58:61]
	v_mfma_f32_16x16x32_bf16 v[58:61], v[134:137], v[188:191], v[58:61]
	v_mfma_f32_16x16x32_bf16 v[54:57], v[138:141], v[180:183], v[54:57]
	v_mfma_f32_16x16x32_bf16 v[54:57], v[142:145], v[188:191], v[54:57]
	v_mfma_f32_16x16x32_bf16 v[42:45], v[130:133], v[192:195], v[42:45]
	v_mfma_f32_16x16x32_bf16 v[42:45], v[134:137], v[196:199], v[42:45]
	v_mfma_f32_16x16x32_bf16 v[34:37], v[138:141], v[192:195], v[34:37]
	v_mfma_f32_16x16x32_bf16 v[34:37], v[142:145], v[196:199], v[34:37]
	v_mfma_f32_16x16x32_bf16 v[26:29], v[130:133], v[200:203], v[26:29]
	v_mfma_f32_16x16x32_bf16 v[26:29], v[134:137], v[204:207], v[26:29]
	v_mfma_f32_16x16x32_bf16 v[18:21], v[138:141], v[200:203], v[18:21]
	v_mfma_f32_16x16x32_bf16 v[18:21], v[142:145], v[204:207], v[18:21]
	v_mfma_f32_16x16x32_bf16 v[6:9], v[130:133], v[208:211], v[6:9]
	v_mfma_f32_16x16x32_bf16 v[6:9], v[134:137], v[212:215], v[6:9]
	v_mfma_f32_16x16x32_bf16 v[2:5], v[138:141], v[208:211], v[2:5]
	v_mfma_f32_16x16x32_bf16 v[2:5], v[142:145], v[212:215], v[2:5]
	v_mfma_f32_16x16x32_bf16 v[62:65], v[146:149], v[180:183], v[62:65]
	v_mfma_f32_16x16x32_bf16 v[62:65], v[150:153], v[188:191], v[62:65]
	v_mfma_f32_16x16x32_bf16 v[50:53], v[172:175], v[180:183], v[50:53]
	v_mfma_f32_16x16x32_bf16 v[50:53], v[176:179], v[188:191], v[50:53]
	v_mfma_f32_16x16x32_bf16 v[46:49], v[146:149], v[192:195], v[46:49]
	v_mfma_f32_16x16x32_bf16 v[46:49], v[150:153], v[196:199], v[46:49]
	v_mfma_f32_16x16x32_bf16 v[38:41], v[172:175], v[192:195], v[38:41]
	v_mfma_f32_16x16x32_bf16 v[38:41], v[176:179], v[196:199], v[38:41]
	v_mfma_f32_16x16x32_bf16 v[30:33], v[146:149], v[200:203], v[30:33]
	v_mfma_f32_16x16x32_bf16 v[30:33], v[150:153], v[204:207], v[30:33]
	v_mfma_f32_16x16x32_bf16 v[22:25], v[172:175], v[200:203], v[22:25]
	v_mfma_f32_16x16x32_bf16 v[22:25], v[176:179], v[204:207], v[22:25]
	v_mfma_f32_16x16x32_bf16 v[10:13], v[146:149], v[208:211], v[10:13]
	v_mfma_f32_16x16x32_bf16 v[10:13], v[150:153], v[212:215], v[10:13]
	v_mfma_f32_16x16x32_bf16 v[14:17], v[172:175], v[208:211], v[14:17]
	v_mfma_f32_16x16x32_bf16 v[14:17], v[176:179], v[212:215], v[14:17]
	s_barrier
; #define PG8_STAGE(bufoff, gbase, voff) do { _Pragma("unroll") for (int _i = 0; _i < 2; ++_i) \
;         __builtin_amdgcn_global_load_lds((const unsigned*)((const char*)(gbase) + (voff)[_i]), (PG8_LAS unsigned*)(lds + (bufoff) + ldsw + _i * 8192), 16, 0, 0); } while (0)
; #define PG8_LDA(dst, b, h) do { _Pragma("unroll") for (int m = 0; m < 4; ++m) _Pragma("unroll") for (int k = 0; k < 2; ++k) dst[m][k] = *(const PG8_LAS bf16x8*)(lds + PG8_SA(b, h) + aoff + m * 2048 + k * 1024); } while (0)
; #define PG8_LDB(dst, b, h) do { _Pragma("unroll") for (int n = 0; n < 2; ++n) _Pragma("unroll") for (int k = 0; k < 2; ++k) dst[n][k] = *(const PG8_LAS bf16x8*)(lds + PG8_SB(b, h) + boff + n * 2048 + k * 1024); } while (0)
; #define PG8_MMA(ai, bj, At, Bt) do { __builtin_amdgcn_s_setprio(1); _Pragma("unroll") for (int m = 0; m < 4; ++m) _Pragma("unroll") for (int n = 0; n < 2; ++n) _Pragma("unroll") for (int k = 0; k < 2; ++k) \
;         acc[ai][bj][m][n] = __builtin_amdgcn_mfma_f32_16x16x32_bf16(Bt[n][k], At[m][k], acc[ai][bj][m][n], 0, 0, 0); __builtin_amdgcn_s_setprio(0); } while (0)
; #define PG8_WAIT_V(n) asm volatile("s_waitcnt vmcnt(" #n ")" ::: "memory")
; #define PG8_WAIT_L(n) asm volatile("s_waitcnt lgkmcnt(" #n ")" ::: "memory")
; #define PG8_BAR __builtin_amdgcn_s_barrier()
; #define PG8_SCHED __builtin_amdgcn_sched_barrier(0)
; template <class Epi, class Sched, bool ALIGN_EPI = false, bool SP2 = false>
; __device__ __forceinline__ void gemm_phase(PG8_LAS unsigned char* lds, const Gemm g, const Sched& S, const Epi& E) {
;     ...
;             PG8_LDB(B0, 1, 0); PG8_LDB(B1, 1, 1); PG8_SCHED; PG8_LDA(At, 1, 0); PG8_STAGE(PG8_SA(0, 1), a2 + hstep, voffA);
;             PG8_WAIT_V(8); PG8_WAIT_L(0); PG8_BAR; PG8_MMA(0, 0, At, B0); PG8_MMA(0, 1, At, B1); PG8_BAR; PG8_SCHED;
;             PG8_LDA(At, 1, 1); PG8_STAGE(PG8_SB(1, 0), b3, voffB); PG8_STAGE(PG8_SB(1, 1), b3 + hstep, voffB); PG8_STAGE(PG8_SA(1, 0), a3, voffA);
;             PG8_WAIT_V(8); PG8_WAIT_L(0); PG8_BAR; PG8_MMA(1, 0, At, B0); PG8_MMA(1, 1, At, B1); PG8_BAR; PG8_SCHED;
	s_add_i32 s33, 0, 0x18000
	s_add_i32 s42, 0, 0x1c000
	ds_read_b128 v[130:133], v241 offset:32768
	ds_read_b128 v[134:137], v241 offset:33792
	ds_read_b128 v[138:141], v241 offset:34816
	ds_read_b128 v[142:145], v241 offset:35840
	ds_read_b128 v[146:149], v241 offset:49152
	ds_read_b128 v[150:153], v241 offset:50176
	ds_read_b128 v[172:175], v241 offset:51200
	ds_read_b128 v[176:179], v241 offset:52224
	s_add_u32 s28, s28, 0x100000
	s_addc_u32 s29, s29, 0
	s_mov_b32 m0, s40
	ds_read_b128 v[180:183], v185 offset:32768
	ds_read_b128 v[188:191], v185 offset:33792
	ds_read_b128 v[192:195], v185 offset:34816
	ds_read_b128 v[196:199], v185 offset:35840
	ds_read_b128 v[200:203], v185 offset:36864
	ds_read_b128 v[204:207], v185 offset:37888
	ds_read_b128 v[208:211], v185 offset:38912
	ds_read_b128 v[212:215], v185 offset:39936
	global_load_lds_dwordx4 v154, s[28:29]
	s_mov_b32 m0, s41
	s_nop 0
	global_load_lds_dwordx4 v158, s[28:29]
	s_waitcnt vmcnt(8)
	s_waitcnt lgkmcnt(0)
	s_barrier
	s_waitcnt lgkmcnt(0)
	v_mfma_f32_16x16x32_bf16 v[114:117], v[130:133], v[180:183], v[114:117]
	v_mfma_f32_16x16x32_bf16 v[114:117], v[134:137], v[188:191], v[114:117]
	v_mfma_f32_16x16x32_bf16 v[118:121], v[138:141], v[180:183], v[118:121]
	v_mfma_f32_16x16x32_bf16 v[118:121], v[142:145], v[188:191], v[118:121]
	v_mfma_f32_16x16x32_bf16 v[106:109], v[130:133], v[192:195], v[106:109]
	v_mfma_f32_16x16x32_bf16 v[106:109], v[134:137], v[196:199], v[106:109]
	v_mfma_f32_16x16x32_bf16 v[98:101], v[138:141], v[192:195], v[98:101]
	v_mfma_f32_16x16x32_bf16 v[98:101], v[142:145], v[196:199], v[98:101]
	v_mfma_f32_16x16x32_bf16 v[90:93], v[130:133], v[200:203], v[90:93]
	v_mfma_f32_16x16x32_bf16 v[90:93], v[134:137], v[204:207], v[90:93]
	v_mfma_f32_16x16x32_bf16 v[82:85], v[138:141], v[200:203], v[82:85]
	v_mfma_f32_16x16x32_bf16 v[82:85], v[142:145], v[204:207], v[82:85]
	v_mfma_f32_16x16x32_bf16 v[74:77], v[130:133], v[208:211], v[74:77]
	v_mfma_f32_16x16x32_bf16 v[74:77], v[134:137], v[212:215], v[74:77]
	v_mfma_f32_16x16x32_bf16 v[66:69], v[138:141], v[208:211], v[66:69]
	v_mfma_f32_16x16x32_bf16 v[66:69], v[142:145], v[212:215], v[66:69]
	v_mfma_f32_16x16x32_bf16 v[122:125], v[146:149], v[180:183], v[122:125]
	v_mfma_f32_16x16x32_bf16 v[122:125], v[150:153], v[188:191], v[122:125]
	v_mfma_f32_16x16x32_bf16 v[126:129], v[172:175], v[180:183], v[126:129]
	v_mfma_f32_16x16x32_bf16 v[126:129], v[176:179], v[188:191], v[126:129]
	v_mfma_f32_16x16x32_bf16 v[110:113], v[146:149], v[192:195], v[110:113]
	v_mfma_f32_16x16x32_bf16 v[110:113], v[150:153], v[196:199], v[110:113]
	v_mfma_f32_16x16x32_bf16 v[102:105], v[172:175], v[192:195], v[102:105]
	v_mfma_f32_16x16x32_bf16 v[102:105], v[176:179], v[196:199], v[102:105]
	v_mfma_f32_16x16x32_bf16 v[94:97], v[146:149], v[200:203], v[94:97]
	v_mfma_f32_16x16x32_bf16 v[94:97], v[150:153], v[204:207], v[94:97]
	v_mfma_f32_16x16x32_bf16 v[86:89], v[172:175], v[200:203], v[86:89]
	v_mfma_f32_16x16x32_bf16 v[86:89], v[176:179], v[204:207], v[86:89]
	v_mfma_f32_16x16x32_bf16 v[78:81], v[146:149], v[208:211], v[78:81]
	v_mfma_f32_16x16x32_bf16 v[78:81], v[150:153], v[212:215], v[78:81]
	v_mfma_f32_16x16x32_bf16 v[70:73], v[172:175], v[208:211], v[70:73]
	v_mfma_f32_16x16x32_bf16 v[70:73], v[176:179], v[212:215], v[70:73]
	s_barrier
	s_add_i32 s28, s33, s36
	s_add_i32 m0, s28, 0xffffff80
	ds_read_b128 v[180:183], v185 offset:49152
	ds_read_b128 v[188:191], v185 offset:50176
	ds_read_b128 v[192:195], v185 offset:51200
	ds_read_b128 v[196:199], v185 offset:52224
	ds_read_b128 v[200:203], v185 offset:53248
	ds_read_b128 v[204:207], v185 offset:54272
	ds_read_b128 v[208:211], v185 offset:55296
	ds_read_b128 v[212:215], v185 offset:56320
	global_load_lds_dwordx4 v156, s[24:25] offset:128
	s_add_i32 m0, s28, 0x1f80
	s_add_i32 s28, s42, s36
	global_load_lds_dwordx4 v160, s[24:25] offset:128
	s_add_u32 s24, s24, 0x100080
	s_addc_u32 s25, s25, 0
	s_mov_b32 m0, s28
	s_nop 0
	global_load_lds_dwordx4 v156, s[24:25]
	s_add_i32 m0, s28, 0x2000
	s_nop 0
	global_load_lds_dwordx4 v160, s[24:25]
	s_mov_b32 m0, s44
	s_nop 0
	global_load_lds_dwordx4 v154, s[100:101]
	s_mov_b32 m0, s45
	s_nop 0
	global_load_lds_dwordx4 v158, s[100:101]
	s_waitcnt vmcnt(8)
	s_waitcnt lgkmcnt(0)
	s_barrier
	s_waitcnt lgkmcnt(0)
	v_mfma_f32_16x16x32_bf16 v[58:61], v[130:133], v[180:183], v[58:61]
	v_mfma_f32_16x16x32_bf16 v[58:61], v[134:137], v[188:191], v[58:61]
	v_mfma_f32_16x16x32_bf16 v[54:57], v[138:141], v[180:183], v[54:57]
	v_mfma_f32_16x16x32_bf16 v[54:57], v[142:145], v[188:191], v[54:57]
	v_mfma_f32_16x16x32_bf16 v[42:45], v[130:133], v[192:195], v[42:45]
	v_mfma_f32_16x16x32_bf16 v[42:45], v[134:137], v[196:199], v[42:45]
	v_mfma_f32_16x16x32_bf16 v[34:37], v[138:141], v[192:195], v[34:37]
	v_mfma_f32_16x16x32_bf16 v[34:37], v[142:145], v[196:199], v[34:37]
	v_mfma_f32_16x16x32_bf16 v[26:29], v[130:133], v[200:203], v[26:29]
	v_mfma_f32_16x16x32_bf16 v[26:29], v[134:137], v[204:207], v[26:29]
	v_mfma_f32_16x16x32_bf16 v[18:21], v[138:141], v[200:203], v[18:21]
	v_mfma_f32_16x16x32_bf16 v[18:21], v[142:145], v[204:207], v[18:21]
	v_mfma_f32_16x16x32_bf16 v[6:9], v[130:133], v[208:211], v[6:9]
	v_mfma_f32_16x16x32_bf16 v[6:9], v[134:137], v[212:215], v[6:9]
	v_mfma_f32_16x16x32_bf16 v[2:5], v[138:141], v[208:211], v[2:5]
	v_mfma_f32_16x16x32_bf16 v[2:5], v[142:145], v[212:215], v[2:5]
	v_mfma_f32_16x16x32_bf16 v[62:65], v[146:149], v[180:183], v[62:65]
	v_mfma_f32_16x16x32_bf16 v[62:65], v[150:153], v[188:191], v[62:65]
	v_mfma_f32_16x16x32_bf16 v[50:53], v[172:175], v[180:183], v[50:53]
	v_mfma_f32_16x16x32_bf16 v[50:53], v[176:179], v[188:191], v[50:53]
	v_mfma_f32_16x16x32_bf16 v[46:49], v[146:149], v[192:195], v[46:49]
	v_mfma_f32_16x16x32_bf16 v[46:49], v[150:153], v[196:199], v[46:49]
	v_mfma_f32_16x16x32_bf16 v[38:41], v[172:175], v[192:195], v[38:41]
	v_mfma_f32_16x16x32_bf16 v[38:41], v[176:179], v[196:199], v[38:41]
	v_mfma_f32_16x16x32_bf16 v[30:33], v[146:149], v[200:203], v[30:33]
	v_mfma_f32_16x16x32_bf16 v[30:33], v[150:153], v[204:207], v[30:33]
	v_mfma_f32_16x16x32_bf16 v[22:25], v[172:175], v[200:203], v[22:25]
	v_mfma_f32_16x16x32_bf16 v[22:25], v[176:179], v[204:207], v[22:25]
	v_mfma_f32_16x16x32_bf16 v[10:13], v[146:149], v[208:211], v[10:13]
	v_mfma_f32_16x16x32_bf16 v[10:13], v[150:153], v[212:215], v[10:13]
	v_mfma_f32_16x16x32_bf16 v[14:17], v[172:175], v[208:211], v[14:17]
	v_mfma_f32_16x16x32_bf16 v[14:17], v[176:179], v[212:215], v[14:17]
	s_barrier
	s_add_i32 s62, s62, 2
	s_add_u32 s26, s26, 0x100
	s_addc_u32 s27, s27, 0
	s_add_u32 s52, s52, 0x100
	s_addc_u32 s53, s53, 0
	s_cmp_gt_u32 s62, 61
	s_cbranch_scc0 .LBB0_1595
	s_and_b64 vcc, exec, s[10:11]
	s_cbranch_vccz .LBB0_1598
	s_barrier

; #define PG8_STAGE(bufoff, gbase, voff) do { _Pragma("unroll") for (int _i = 0; _i < 2; ++_i) \
;         __builtin_amdgcn_global_load_lds((const unsigned*)((const char*)(gbase) + (voff)[_i]), (PG8_LAS unsigned*)(lds + (bufoff) + ldsw + _i * 8192), 16, 0, 0); } while (0)
; #define PG8_LDA(dst, b, h) do { _Pragma("unroll") for (int m = 0; m < 4; ++m) _Pragma("unroll") for (int k = 0; k < 2; ++k) dst[m][k] = *(const PG8_LAS bf16x8*)(lds + PG8_SA(b, h) + aoff + m * 2048 + k * 1024); } while (0)
; #define PG8_LDB(dst, b, h) do { _Pragma("unroll") for (int n = 0; n < 2; ++n) _Pragma("unroll") for (int k = 0; k < 2; ++k) dst[n][k] = *(const PG8_LAS bf16x8*)(lds + PG8_SB(b, h) + boff + n * 2048 + k * 1024); } while (0)
; #define PG8_MMA(ai, bj, At, Bt) do { __builtin_amdgcn_s_setprio(1); _Pragma("unroll") for (int m = 0; m < 4; ++m) _Pragma("unroll") for (int n = 0; n < 2; ++n) _Pragma("unroll") for (int k = 0; k < 2; ++k) \
;         acc[ai][bj][m][n] = __builtin_amdgcn_mfma_f32_16x16x32_bf16(Bt[n][k], At[m][k], acc[ai][bj][m][n], 0, 0, 0); __builtin_amdgcn_s_setprio(0); } while (0)
; #define PG8_WAIT_V(n) asm volatile("s_waitcnt vmcnt(" #n ")" ::: "memory")
; #define PG8_BAR __builtin_amdgcn_s_barrier()
; template <class Epi, class Sched, bool ALIGN_EPI = false, bool SP2 = false>
; __device__ __forceinline__ void gemm_phase(PG8_LAS unsigned char* lds, const Gemm g, const Sched& S, const Epi& E) {
;     ...
;         for (int t = 0; t < nt; t += 2) {
;             const bool last = (t == nt - 2);
;             const char* a1 = cA + (size_t)(t + 1) * kstep;
;             const char* a2 = last ? nA : cA + (size_t)(t + 2) * kstep; const char* b2 = last ? nB : cB + (size_t)(t + 2) * kstep;
;             const char* a3 = a2 + kstep; const char* b3 = b2 + kstep;
;             if (last && has_next) S.a_ready(nxt);
;             if constexpr (SP2) {
;             PG8_LDB(B0, 0, 0); PG8_LDB(B1, 0, 1); PG8_SCHED; PG8_LDA(At, 0, 0); PG8_STAGE(PG8_SA(1, 1), a1 + hstep, voffA);
;             PG8_WAIT_V(8); PG8_WAIT_L(0); PG8_BAR; PG8_MMA(0, 0, At, B0); PG8_MMA(0, 1, At, B1); PG8_BAR; PG8_SCHED;
;             PG8_LDA(At, 0, 1); PG8_STAGE(PG8_SB(0, 0), b2, voffB); PG8_STAGE(PG8_SB(0, 1), b2 + hstep, voffB); PG8_STAGE(PG8_SA(0, 0), a2, voffA);
;             PG8_WAIT_V(8); PG8_WAIT_L(0); PG8_BAR; PG8_MMA(1, 0, At, B0); PG8_MMA(1, 1, At, B1); PG8_BAR; PG8_SCHED;
.LBB0_1681:
	ds_read_b128 v[160:163], v241 offset:0
	ds_read_b128 v[166:169], v241 offset:1024
	ds_read_b128 v[170:173], v241 offset:2048
	ds_read_b128 v[174:177], v241 offset:3072
	ds_read_b128 v[178:181], v241 offset:16384
	ds_read_b128 v[182:185], v241 offset:17408
	ds_read_b128 v[186:189], v241 offset:18432
	ds_read_b128 v[190:193], v241 offset:19456
	s_add_u32 s22, s24, 0xfff00080
	s_addc_u32 s23, s25, -1
	s_cmp_eq_u32 s52, 60
	s_cselect_b32 s27, s15, s23
	s_cselect_b32 s26, s48, s22
	s_cselect_b32 s23, s13, s51
	s_cselect_b32 s22, s49, s50
	s_add_i32 m0, s21, 0xc000
	ds_read_b128 v[194:197], v155
	ds_read_b128 v[198:201], v155 offset:1024
	ds_read_b128 v[202:205], v155 offset:2048
	ds_read_b128 v[206:209], v155 offset:3072
	ds_read_b128 v[210:213], v155 offset:4096
	ds_read_b128 v[214:217], v155 offset:5120
	ds_read_b128 v[218:221], v155 offset:6144
	ds_read_b128 v[222:225], v155 offset:7168
	global_load_lds_dwordx4 v138, s[24:25]
	s_add_i32 m0, s21, 0xe000
	s_nop 0
	global_load_lds_dwordx4 v140, s[24:25]
	s_waitcnt vmcnt(8)
	s_waitcnt lgkmcnt(0)
	s_barrier
	s_waitcnt lgkmcnt(0)
	v_mfma_f32_16x16x32_bf16 v[122:125], v[160:163], v[194:197], v[122:125]
	v_mfma_f32_16x16x32_bf16 v[122:125], v[166:169], v[198:201], v[122:125]
	v_mfma_f32_16x16x32_bf16 v[114:117], v[170:173], v[194:197], v[114:117]
	v_mfma_f32_16x16x32_bf16 v[114:117], v[174:177], v[198:201], v[114:117]
	v_mfma_f32_16x16x32_bf16 v[106:109], v[160:163], v[202:205], v[106:109]
	v_mfma_f32_16x16x32_bf16 v[106:109], v[166:169], v[206:209], v[106:109]
	v_mfma_f32_16x16x32_bf16 v[98:101], v[170:173], v[202:205], v[98:101]
	v_mfma_f32_16x16x32_bf16 v[98:101], v[174:177], v[206:209], v[98:101]
	v_mfma_f32_16x16x32_bf16 v[90:93], v[160:163], v[210:213], v[90:93]
	v_mfma_f32_16x16x32_bf16 v[90:93], v[166:169], v[214:217], v[90:93]
	v_mfma_f32_16x16x32_bf16 v[82:85], v[170:173], v[210:213], v[82:85]
	v_mfma_f32_16x16x32_bf16 v[82:85], v[174:177], v[214:217], v[82:85]
	v_mfma_f32_16x16x32_bf16 v[74:77], v[160:163], v[218:221], v[74:77]
	v_mfma_f32_16x16x32_bf16 v[74:77], v[166:169], v[222:225], v[74:77]
	v_mfma_f32_16x16x32_bf16 v[62:65], v[170:173], v[218:221], v[62:65]
	v_mfma_f32_16x16x32_bf16 v[62:65], v[174:177], v[222:225], v[62:65]
	v_mfma_f32_16x16x32_bf16 v[126:129], v[178:181], v[194:197], v[126:129]
	v_mfma_f32_16x16x32_bf16 v[126:129], v[182:185], v[198:201], v[126:129]
	v_mfma_f32_16x16x32_bf16 v[118:121], v[186:189], v[194:197], v[118:121]
	v_mfma_f32_16x16x32_bf16 v[118:121], v[190:193], v[198:201], v[118:121]
	v_mfma_f32_16x16x32_bf16 v[110:113], v[178:181], v[202:205], v[110:113]
	v_mfma_f32_16x16x32_bf16 v[110:113], v[182:185], v[206:209], v[110:113]
	v_mfma_f32_16x16x32_bf16 v[102:105], v[186:189], v[202:205], v[102:105]
	v_mfma_f32_16x16x32_bf16 v[102:105], v[190:193], v[206:209], v[102:105]
	v_mfma_f32_16x16x32_bf16 v[94:97], v[178:181], v[210:213], v[94:97]
	v_mfma_f32_16x16x32_bf16 v[94:97], v[182:185], v[214:217], v[94:97]
	v_mfma_f32_16x16x32_bf16 v[86:89], v[186:189], v[210:213], v[86:89]
	v_mfma_f32_16x16x32_bf16 v[86:89], v[190:193], v[214:217], v[86:89]
	v_mfma_f32_16x16x32_bf16 v[78:81], v[178:181], v[218:221], v[78:81]
	v_mfma_f32_16x16x32_bf16 v[78:81], v[182:185], v[222:225], v[78:81]
	v_mfma_f32_16x16x32_bf16 v[70:73], v[186:189], v[218:221], v[70:73]
	v_mfma_f32_16x16x32_bf16 v[70:73], v[190:193], v[222:225], v[70:73]
	s_barrier
	s_add_i32 s33, s44, s29
	s_mov_b32 m0, s33
	ds_read_b128 v[194:197], v155 offset:16384
	ds_read_b128 v[198:201], v155 offset:17408
	ds_read_b128 v[202:205], v155 offset:18432
	ds_read_b128 v[206:209], v155 offset:19456
	ds_read_b128 v[210:213], v155 offset:20480
	ds_read_b128 v[214:217], v155 offset:21504
	ds_read_b128 v[218:221], v155 offset:22528
	ds_read_b128 v[222:225], v155 offset:23552
	global_load_lds_dwordx4 v132, s[22:23]
	s_add_i32 m0, s33, 0x2000
	s_add_u32 s62, s22, 0x100000
	s_addc_u32 s63, s23, 0
	s_add_i32 s33, s45, s29
	global_load_lds_dwordx4 v136, s[22:23]
	s_mov_b32 m0, s33
	s_add_u32 s100, s26, 0x80
	s_addc_u32 s101, s27, 0
	global_load_lds_dwordx4 v132, s[62:63]
	s_add_i32 m0, s33, 0x2000
	s_nop 0
	global_load_lds_dwordx4 v136, s[62:63]
	s_mov_b32 m0, s21
	s_nop 0
	global_load_lds_dwordx4 v130, s[26:27]
	s_mov_b32 m0, s34
	s_nop 0
	global_load_lds_dwordx4 v134, s[26:27]
	s_waitcnt vmcnt(8)
	s_waitcnt lgkmcnt(0)
	s_barrier
	s_waitcnt lgkmcnt(0)
	v_mfma_f32_16x16x32_bf16 v[58:61], v[160:163], v[194:197], v[58:61]
	v_mfma_f32_16x16x32_bf16 v[58:61], v[166:169], v[198:201], v[58:61]
	v_mfma_f32_16x16x32_bf16 v[50:53], v[170:173], v[194:197], v[50:53]
	v_mfma_f32_16x16x32_bf16 v[50:53], v[174:177], v[198:201], v[50:53]
	v_mfma_f32_16x16x32_bf16 v[42:45], v[160:163], v[202:205], v[42:45]
	v_mfma_f32_16x16x32_bf16 v[42:45], v[166:169], v[206:209], v[42:45]
	v_mfma_f32_16x16x32_bf16 v[34:37], v[170:173], v[202:205], v[34:37]
	v_mfma_f32_16x16x32_bf16 v[34:37], v[174:177], v[206:209], v[34:37]
	v_mfma_f32_16x16x32_bf16 v[26:29], v[160:163], v[210:213], v[26:29]
	v_mfma_f32_16x16x32_bf16 v[26:29], v[166:169], v[214:217], v[26:29]
	v_mfma_f32_16x16x32_bf16 v[18:21], v[170:173], v[210:213], v[18:21]
	v_mfma_f32_16x16x32_bf16 v[18:21], v[174:177], v[214:217], v[18:21]
	v_mfma_f32_16x16x32_bf16 v[10:13], v[160:163], v[218:221], v[10:13]
	v_mfma_f32_16x16x32_bf16 v[10:13], v[166:169], v[222:225], v[10:13]
	v_mfma_f32_16x16x32_bf16 v[2:5], v[170:173], v[218:221], v[2:5]
	v_mfma_f32_16x16x32_bf16 v[2:5], v[174:177], v[222:225], v[2:5]
	v_mfma_f32_16x16x32_bf16 v[66:69], v[178:181], v[194:197], v[66:69]
	v_mfma_f32_16x16x32_bf16 v[66:69], v[182:185], v[198:201], v[66:69]
	v_mfma_f32_16x16x32_bf16 v[54:57], v[186:189], v[194:197], v[54:57]
	v_mfma_f32_16x16x32_bf16 v[54:57], v[190:193], v[198:201], v[54:57]
	v_mfma_f32_16x16x32_bf16 v[46:49], v[178:181], v[202:205], v[46:49]
	v_mfma_f32_16x16x32_bf16 v[46:49], v[182:185], v[206:209], v[46:49]
	v_mfma_f32_16x16x32_bf16 v[38:41], v[186:189], v[202:205], v[38:41]
	v_mfma_f32_16x16x32_bf16 v[38:41], v[190:193], v[206:209], v[38:41]
	v_mfma_f32_16x16x32_bf16 v[30:33], v[178:181], v[210:213], v[30:33]
	v_mfma_f32_16x16x32_bf16 v[30:33], v[182:185], v[214:217], v[30:33]
	v_mfma_f32_16x16x32_bf16 v[22:25], v[186:189], v[210:213], v[22:25]
	v_mfma_f32_16x16x32_bf16 v[22:25], v[190:193], v[214:217], v[22:25]
	v_mfma_f32_16x16x32_bf16 v[14:17], v[178:181], v[218:221], v[14:17]
	v_mfma_f32_16x16x32_bf16 v[14:17], v[182:185], v[222:225], v[14:17]
	v_mfma_f32_16x16x32_bf16 v[6:9], v[186:189], v[218:221], v[6:9]
	v_mfma_f32_16x16x32_bf16 v[6:9], v[190:193], v[222:225], v[6:9]
	s_barrier
; #define PG8_STAGE(bufoff, gbase, voff) do { _Pragma("unroll") for (int _i = 0; _i < 2; ++_i) \
;         __builtin_amdgcn_global_load_lds((const unsigned*)((const char*)(gbase) + (voff)[_i]), (PG8_LAS unsigned*)(lds + (bufoff) + ldsw + _i * 8192), 16, 0, 0); } while (0)
; #define PG8_LDA(dst, b, h) do { _Pragma("unroll") for (int m = 0; m < 4; ++m) _Pragma("unroll") for (int k = 0; k < 2; ++k) dst[m][k] = *(const PG8_LAS bf16x8*)(lds + PG8_SA(b, h) + aoff + m * 2048 + k * 1024); } while (0)
; #define PG8_LDB(dst, b, h) do { _Pragma("unroll") for (int n = 0; n < 2; ++n) _Pragma("unroll") for (int k = 0; k < 2; ++k) dst[n][k] = *(const PG8_LAS bf16x8*)(lds + PG8_SB(b, h) + boff + n * 2048 + k * 1024); } while (0)
; #define PG8_MMA(ai, bj, At, Bt) do { __builtin_amdgcn_s_setprio(1); _Pragma("unroll") for (int m = 0; m < 4; ++m) _Pragma("unroll") for (int n = 0; n < 2; ++n) _Pragma("unroll") for (int k = 0; k < 2; ++k) \
;         acc[ai][bj][m][n] = __builtin_amdgcn_mfma_f32_16x16x32_bf16(Bt[n][k], At[m][k], acc[ai][bj][m][n], 0, 0, 0); __builtin_amdgcn_s_setprio(0); } while (0)
; #define PG8_WAIT_V(n) asm volatile("s_waitcnt vmcnt(" #n ")" ::: "memory")
; #define PG8_WAIT_L(n) asm volatile("s_waitcnt lgkmcnt(" #n ")" ::: "memory")
; #define PG8_BAR __builtin_amdgcn_s_barrier()
; #define PG8_SCHED __builtin_amdgcn_sched_barrier(0)
; template <class Epi, class Sched, bool ALIGN_EPI = false, bool SP2 = false>
; __device__ __forceinline__ void gemm_phase(PG8_LAS unsigned char* lds, const Gemm g, const Sched& S, const Epi& E) {
;     ...
;             PG8_LDB(B0, 1, 0); PG8_LDB(B1, 1, 1); PG8_SCHED; PG8_LDA(At, 1, 0); PG8_STAGE(PG8_SA(0, 1), a2 + hstep, voffA);
;             PG8_WAIT_V(8); PG8_WAIT_L(0); PG8_BAR; PG8_MMA(0, 0, At, B0); PG8_MMA(0, 1, At, B1); PG8_BAR; PG8_SCHED;
;             PG8_LDA(At, 1, 1); PG8_STAGE(PG8_SB(1, 0), b3, voffB); PG8_STAGE(PG8_SB(1, 1), b3 + hstep, voffB); PG8_STAGE(PG8_SA(1, 0), a3, voffA);
;             PG8_WAIT_V(8); PG8_WAIT_L(0); PG8_BAR; PG8_MMA(1, 0, At, B0); PG8_MMA(1, 1, At, B1); PG8_BAR; PG8_SCHED;
	s_add_i32 s33, 0, 0x18000
	s_add_i32 s42, 0, 0x1c000
	ds_read_b128 v[160:163], v241 offset:32768
	ds_read_b128 v[166:169], v241 offset:33792
	ds_read_b128 v[170:173], v241 offset:34816
	ds_read_b128 v[174:177], v241 offset:35840
	ds_read_b128 v[178:181], v241 offset:49152
	ds_read_b128 v[182:185], v241 offset:50176
	ds_read_b128 v[186:189], v241 offset:51200
	ds_read_b128 v[190:193], v241 offset:52224
	s_add_u32 s26, s26, 0x100000
	s_addc_u32 s27, s27, 0
	s_mov_b32 m0, s35
	ds_read_b128 v[194:197], v155 offset:32768
	ds_read_b128 v[198:201], v155 offset:33792
	ds_read_b128 v[202:205], v155 offset:34816
	ds_read_b128 v[206:209], v155 offset:35840
	ds_read_b128 v[210:213], v155 offset:36864
	ds_read_b128 v[214:217], v155 offset:37888
	ds_read_b128 v[218:221], v155 offset:38912
	ds_read_b128 v[222:225], v155 offset:39936
	global_load_lds_dwordx4 v130, s[26:27]
	s_mov_b32 m0, s36
	s_nop 0
	global_load_lds_dwordx4 v134, s[26:27]
	s_waitcnt vmcnt(8)
	s_waitcnt lgkmcnt(0)
	s_barrier
	s_waitcnt lgkmcnt(0)
	v_mfma_f32_16x16x32_bf16 v[122:125], v[160:163], v[194:197], v[122:125]
	v_mfma_f32_16x16x32_bf16 v[122:125], v[166:169], v[198:201], v[122:125]
	v_mfma_f32_16x16x32_bf16 v[114:117], v[170:173], v[194:197], v[114:117]
	v_mfma_f32_16x16x32_bf16 v[114:117], v[174:177], v[198:201], v[114:117]
	v_mfma_f32_16x16x32_bf16 v[106:109], v[160:163], v[202:205], v[106:109]
	v_mfma_f32_16x16x32_bf16 v[106:109], v[166:169], v[206:209], v[106:109]
	v_mfma_f32_16x16x32_bf16 v[98:101], v[170:173], v[202:205], v[98:101]
	v_mfma_f32_16x16x32_bf16 v[98:101], v[174:177], v[206:209], v[98:101]
	v_mfma_f32_16x16x32_bf16 v[90:93], v[160:163], v[210:213], v[90:93]
	v_mfma_f32_16x16x32_bf16 v[90:93], v[166:169], v[214:217], v[90:93]
	v_mfma_f32_16x16x32_bf16 v[82:85], v[170:173], v[210:213], v[82:85]
	v_mfma_f32_16x16x32_bf16 v[82:85], v[174:177], v[214:217], v[82:85]
	v_mfma_f32_16x16x32_bf16 v[74:77], v[160:163], v[218:221], v[74:77]
	v_mfma_f32_16x16x32_bf16 v[74:77], v[166:169], v[222:225], v[74:77]
	v_mfma_f32_16x16x32_bf16 v[62:65], v[170:173], v[218:221], v[62:65]
	v_mfma_f32_16x16x32_bf16 v[62:65], v[174:177], v[222:225], v[62:65]
	v_mfma_f32_16x16x32_bf16 v[126:129], v[178:181], v[194:197], v[126:129]
	v_mfma_f32_16x16x32_bf16 v[126:129], v[182:185], v[198:201], v[126:129]
	v_mfma_f32_16x16x32_bf16 v[118:121], v[186:189], v[194:197], v[118:121]
	v_mfma_f32_16x16x32_bf16 v[118:121], v[190:193], v[198:201], v[118:121]
	v_mfma_f32_16x16x32_bf16 v[110:113], v[178:181], v[202:205], v[110:113]
	v_mfma_f32_16x16x32_bf16 v[110:113], v[182:185], v[206:209], v[110:113]
	v_mfma_f32_16x16x32_bf16 v[102:105], v[186:189], v[202:205], v[102:105]
	v_mfma_f32_16x16x32_bf16 v[102:105], v[190:193], v[206:209], v[102:105]
	v_mfma_f32_16x16x32_bf16 v[94:97], v[178:181], v[210:213], v[94:97]
	v_mfma_f32_16x16x32_bf16 v[94:97], v[182:185], v[214:217], v[94:97]
	v_mfma_f32_16x16x32_bf16 v[86:89], v[186:189], v[210:213], v[86:89]
	v_mfma_f32_16x16x32_bf16 v[86:89], v[190:193], v[214:217], v[86:89]
	v_mfma_f32_16x16x32_bf16 v[78:81], v[178:181], v[218:221], v[78:81]
	v_mfma_f32_16x16x32_bf16 v[78:81], v[182:185], v[222:225], v[78:81]
	v_mfma_f32_16x16x32_bf16 v[70:73], v[186:189], v[218:221], v[70:73]
	v_mfma_f32_16x16x32_bf16 v[70:73], v[190:193], v[222:225], v[70:73]
	s_barrier
	s_add_i32 s26, s33, s29
	s_add_i32 m0, s26, 0xffffff80
	ds_read_b128 v[194:197], v155 offset:49152
	ds_read_b128 v[198:201], v155 offset:50176
	ds_read_b128 v[202:205], v155 offset:51200
	ds_read_b128 v[206:209], v155 offset:52224
	ds_read_b128 v[210:213], v155 offset:53248
	ds_read_b128 v[214:217], v155 offset:54272
	ds_read_b128 v[218:221], v155 offset:55296
	ds_read_b128 v[222:225], v155 offset:56320
	global_load_lds_dwordx4 v132, s[22:23] offset:128
	s_add_i32 m0, s26, 0x1f80
	s_add_i32 s26, s42, s29
	global_load_lds_dwordx4 v136, s[22:23] offset:128
	s_add_u32 s22, s22, 0x100080
	s_addc_u32 s23, s23, 0
	s_mov_b32 m0, s26
	s_nop 0
	global_load_lds_dwordx4 v132, s[22:23]
	s_add_i32 m0, s26, 0x2000
	s_nop 0
	global_load_lds_dwordx4 v136, s[22:23]
	s_mov_b32 m0, s41
	s_nop 0
	global_load_lds_dwordx4 v130, s[100:101]
	s_mov_b32 m0, s43
	s_nop 0
	global_load_lds_dwordx4 v134, s[100:101]
	s_waitcnt vmcnt(8)
	s_waitcnt lgkmcnt(0)
	s_barrier
	s_waitcnt lgkmcnt(0)
	v_mfma_f32_16x16x32_bf16 v[58:61], v[160:163], v[194:197], v[58:61]
	v_mfma_f32_16x16x32_bf16 v[58:61], v[166:169], v[198:201], v[58:61]
	v_mfma_f32_16x16x32_bf16 v[50:53], v[170:173], v[194:197], v[50:53]
	v_mfma_f32_16x16x32_bf16 v[50:53], v[174:177], v[198:201], v[50:53]
	v_mfma_f32_16x16x32_bf16 v[42:45], v[160:163], v[202:205], v[42:45]
	v_mfma_f32_16x16x32_bf16 v[42:45], v[166:169], v[206:209], v[42:45]
	v_mfma_f32_16x16x32_bf16 v[34:37], v[170:173], v[202:205], v[34:37]
	v_mfma_f32_16x16x32_bf16 v[34:37], v[174:177], v[206:209], v[34:37]
	v_mfma_f32_16x16x32_bf16 v[26:29], v[160:163], v[210:213], v[26:29]
	v_mfma_f32_16x16x32_bf16 v[26:29], v[166:169], v[214:217], v[26:29]
	v_mfma_f32_16x16x32_bf16 v[18:21], v[170:173], v[210:213], v[18:21]
	v_mfma_f32_16x16x32_bf16 v[18:21], v[174:177], v[214:217], v[18:21]
	v_mfma_f32_16x16x32_bf16 v[10:13], v[160:163], v[218:221], v[10:13]
	v_mfma_f32_16x16x32_bf16 v[10:13], v[166:169], v[222:225], v[10:13]
	v_mfma_f32_16x16x32_bf16 v[2:5], v[170:173], v[218:221], v[2:5]
	v_mfma_f32_16x16x32_bf16 v[2:5], v[174:177], v[222:225], v[2:5]
	v_mfma_f32_16x16x32_bf16 v[66:69], v[178:181], v[194:197], v[66:69]
	v_mfma_f32_16x16x32_bf16 v[66:69], v[182:185], v[198:201], v[66:69]
	v_mfma_f32_16x16x32_bf16 v[54:57], v[186:189], v[194:197], v[54:57]
	v_mfma_f32_16x16x32_bf16 v[54:57], v[190:193], v[198:201], v[54:57]
	v_mfma_f32_16x16x32_bf16 v[46:49], v[178:181], v[202:205], v[46:49]
	v_mfma_f32_16x16x32_bf16 v[46:49], v[182:185], v[206:209], v[46:49]
	v_mfma_f32_16x16x32_bf16 v[38:41], v[186:189], v[202:205], v[38:41]
	v_mfma_f32_16x16x32_bf16 v[38:41], v[190:193], v[206:209], v[38:41]
	v_mfma_f32_16x16x32_bf16 v[30:33], v[178:181], v[210:213], v[30:33]
	v_mfma_f32_16x16x32_bf16 v[30:33], v[182:185], v[214:217], v[30:33]
	v_mfma_f32_16x16x32_bf16 v[22:25], v[186:189], v[210:213], v[22:25]
	v_mfma_f32_16x16x32_bf16 v[22:25], v[190:193], v[214:217], v[22:25]
	v_mfma_f32_16x16x32_bf16 v[14:17], v[178:181], v[218:221], v[14:17]
	v_mfma_f32_16x16x32_bf16 v[14:17], v[182:185], v[222:225], v[14:17]
	v_mfma_f32_16x16x32_bf16 v[6:9], v[186:189], v[218:221], v[6:9]
	v_mfma_f32_16x16x32_bf16 v[6:9], v[190:193], v[222:225], v[6:9]
	s_barrier
	s_add_i32 s52, s52, 2
	s_add_u32 s24, s24, 0x100
	s_addc_u32 s25, s25, 0
	s_add_u32 s50, s50, 0x100
	s_addc_u32 s51, s51, 0
	s_cmp_gt_u32 s52, 61
	s_cbranch_scc0 .LBB0_1681
	s_and_b64 vcc, exec, s[8:9]
	s_cbranch_vccz .LBB0_1684
	s_barrier

; #define PG8_STAGE(bufoff, gbase, voff) do { _Pragma("unroll") for (int _i = 0; _i < 2; ++_i) \
;         __builtin_amdgcn_global_load_lds((const unsigned*)((const char*)(gbase) + (voff)[_i]), (PG8_LAS unsigned*)(lds + (bufoff) + ldsw + _i * 8192), 16, 0, 0); } while (0)
; #define PG8_LDA(dst, b, h) do { _Pragma("unroll") for (int m = 0; m < 4; ++m) _Pragma("unroll") for (int k = 0; k < 2; ++k) dst[m][k] = *(const PG8_LAS bf16x8*)(lds + PG8_SA(b, h) + aoff + m * 2048 + k * 1024); } while (0)
; #define PG8_LDB(dst, b, h) do { _Pragma("unroll") for (int n = 0; n < 2; ++n) _Pragma("unroll") for (int k = 0; k < 2; ++k) dst[n][k] = *(const PG8_LAS bf16x8*)(lds + PG8_SB(b, h) + boff + n * 2048 + k * 1024); } while (0)
; #define PG8_MMA(ai, bj, At, Bt) do { __builtin_amdgcn_s_setprio(1); _Pragma("unroll") for (int m = 0; m < 4; ++m) _Pragma("unroll") for (int n = 0; n < 2; ++n) _Pragma("unroll") for (int k = 0; k < 2; ++k) \
;         acc[ai][bj][m][n] = __builtin_amdgcn_mfma_f32_16x16x32_bf16(Bt[n][k], At[m][k], acc[ai][bj][m][n], 0, 0, 0); __builtin_amdgcn_s_setprio(0); } while (0)
; #define PG8_WAIT_V(n) asm volatile("s_waitcnt vmcnt(" #n ")" ::: "memory")
; #define PG8_BAR __builtin_amdgcn_s_barrier()
; template <class Epi, class Sched, bool ALIGN_EPI = false, bool SP2 = false>
; __device__ __forceinline__ void gemm_phase(PG8_LAS unsigned char* lds, const Gemm g, const Sched& S, const Epi& E) {
;     ...
;         for (int t = 0; t < nt; t += 2) {
;             const bool last = (t == nt - 2);
;             const char* a1 = cA + (size_t)(t + 1) * kstep;
;             const char* a2 = last ? nA : cA + (size_t)(t + 2) * kstep; const char* b2 = last ? nB : cB + (size_t)(t + 2) * kstep;
;             const char* a3 = a2 + kstep; const char* b3 = b2 + kstep;
;             if (last && has_next) S.a_ready(nxt);
;             if constexpr (SP2) {
;             PG8_LDB(B0, 0, 0); PG8_LDB(B1, 0, 1); PG8_SCHED; PG8_LDA(At, 0, 0); PG8_STAGE(PG8_SA(1, 1), a1 + hstep, voffA);
;             PG8_WAIT_V(8); PG8_WAIT_L(0); PG8_BAR; PG8_MMA(0, 0, At, B0); PG8_MMA(0, 1, At, B1); PG8_BAR; PG8_SCHED;
;             PG8_LDA(At, 0, 1); PG8_STAGE(PG8_SB(0, 0), b2, voffB); PG8_STAGE(PG8_SB(0, 1), b2 + hstep, voffB); PG8_STAGE(PG8_SA(0, 0), a2, voffA);
;             PG8_WAIT_V(8); PG8_WAIT_L(0); PG8_BAR; PG8_MMA(1, 0, At, B0); PG8_MMA(1, 1, At, B1); PG8_BAR; PG8_SCHED;
.LBB0_1801:
	ds_read_b128 v[130:133], v241 offset:0
	ds_read_b128 v[134:137], v241 offset:1024
	ds_read_b128 v[138:141], v241 offset:2048
	ds_read_b128 v[142:145], v241 offset:3072
	ds_read_b128 v[146:149], v241 offset:16384
	ds_read_b128 v[150:153], v241 offset:17408
	ds_read_b128 v[170:173], v241 offset:18432
	ds_read_b128 v[174:177], v241 offset:19456
	s_add_u32 s16, s18, 0xffd50080
	s_addc_u32 s17, s19, -1
	s_cmpk_eq_i32 s48, 0xa8
	s_cselect_b32 s21, s5, s17
	s_cselect_b32 s20, s4, s16
	s_cselect_b32 s17, s15, s47
	s_cselect_b32 s16, s14, s46
	s_add_i32 m0, s25, 0xc000
	ds_read_b128 v[178:181], v184
	ds_read_b128 v[186:189], v184 offset:1024
	ds_read_b128 v[190:193], v184 offset:2048
	ds_read_b128 v[194:197], v184 offset:3072
	ds_read_b128 v[198:201], v184 offset:4096
	ds_read_b128 v[202:205], v184 offset:5120
	ds_read_b128 v[206:209], v184 offset:6144
	ds_read_b128 v[210:213], v184 offset:7168
	global_load_lds_dwordx4 v0, s[18:19]
	s_add_i32 m0, s25, 0xe000
	s_nop 0
	global_load_lds_dwordx4 v162, s[18:19]
	s_waitcnt vmcnt(8)
	s_waitcnt lgkmcnt(0)
	s_barrier
	s_waitcnt lgkmcnt(0)
	v_mfma_f32_16x16x32_bf16 v[114:117], v[130:133], v[178:181], v[114:117]
	v_mfma_f32_16x16x32_bf16 v[114:117], v[134:137], v[186:189], v[114:117]
	v_mfma_f32_16x16x32_bf16 v[118:121], v[138:141], v[178:181], v[118:121]
	v_mfma_f32_16x16x32_bf16 v[118:121], v[142:145], v[186:189], v[118:121]
	v_mfma_f32_16x16x32_bf16 v[106:109], v[130:133], v[190:193], v[106:109]
	v_mfma_f32_16x16x32_bf16 v[106:109], v[134:137], v[194:197], v[106:109]
	v_mfma_f32_16x16x32_bf16 v[98:101], v[138:141], v[190:193], v[98:101]
	v_mfma_f32_16x16x32_bf16 v[98:101], v[142:145], v[194:197], v[98:101]
	v_mfma_f32_16x16x32_bf16 v[90:93], v[130:133], v[198:201], v[90:93]
	v_mfma_f32_16x16x32_bf16 v[90:93], v[134:137], v[202:205], v[90:93]
	v_mfma_f32_16x16x32_bf16 v[82:85], v[138:141], v[198:201], v[82:85]
	v_mfma_f32_16x16x32_bf16 v[82:85], v[142:145], v[202:205], v[82:85]
	v_mfma_f32_16x16x32_bf16 v[74:77], v[130:133], v[206:209], v[74:77]
	v_mfma_f32_16x16x32_bf16 v[74:77], v[134:137], v[210:213], v[74:77]
	v_mfma_f32_16x16x32_bf16 v[66:69], v[138:141], v[206:209], v[66:69]
	v_mfma_f32_16x16x32_bf16 v[66:69], v[142:145], v[210:213], v[66:69]
	v_mfma_f32_16x16x32_bf16 v[122:125], v[146:149], v[178:181], v[122:125]
	v_mfma_f32_16x16x32_bf16 v[122:125], v[150:153], v[186:189], v[122:125]
	v_mfma_f32_16x16x32_bf16 v[126:129], v[170:173], v[178:181], v[126:129]
	v_mfma_f32_16x16x32_bf16 v[126:129], v[174:177], v[186:189], v[126:129]
	v_mfma_f32_16x16x32_bf16 v[110:113], v[146:149], v[190:193], v[110:113]
	v_mfma_f32_16x16x32_bf16 v[110:113], v[150:153], v[194:197], v[110:113]
	v_mfma_f32_16x16x32_bf16 v[102:105], v[170:173], v[190:193], v[102:105]
	v_mfma_f32_16x16x32_bf16 v[102:105], v[174:177], v[194:197], v[102:105]
	v_mfma_f32_16x16x32_bf16 v[94:97], v[146:149], v[198:201], v[94:97]
	v_mfma_f32_16x16x32_bf16 v[94:97], v[150:153], v[202:205], v[94:97]
	v_mfma_f32_16x16x32_bf16 v[86:89], v[170:173], v[198:201], v[86:89]
	v_mfma_f32_16x16x32_bf16 v[86:89], v[174:177], v[202:205], v[86:89]
	v_mfma_f32_16x16x32_bf16 v[78:81], v[146:149], v[206:209], v[78:81]
	v_mfma_f32_16x16x32_bf16 v[78:81], v[150:153], v[210:213], v[78:81]
	v_mfma_f32_16x16x32_bf16 v[70:73], v[170:173], v[206:209], v[70:73]
	v_mfma_f32_16x16x32_bf16 v[70:73], v[174:177], v[210:213], v[70:73]
	s_barrier
	s_add_i32 s33, s36, s24
	s_mov_b32 m0, s33
	ds_read_b128 v[178:181], v184 offset:16384
	ds_read_b128 v[186:189], v184 offset:17408
	ds_read_b128 v[190:193], v184 offset:18432
	ds_read_b128 v[194:197], v184 offset:19456
	ds_read_b128 v[198:201], v184 offset:20480
	ds_read_b128 v[202:205], v184 offset:21504
	ds_read_b128 v[206:209], v184 offset:22528
	ds_read_b128 v[210:213], v184 offset:23552
	global_load_lds_dwordx4 v156, s[16:17]
	s_add_i32 m0, s33, 0x2000
	s_add_u32 s50, s16, 0x2b0000
	s_addc_u32 s51, s17, 0
	s_add_i32 s33, s37, s24
	global_load_lds_dwordx4 v160, s[16:17]
	s_mov_b32 m0, s33
	s_add_u32 s100, s20, 0x80
	s_addc_u32 s101, s21, 0
	global_load_lds_dwordx4 v156, s[50:51]
	s_add_i32 m0, s33, 0x2000
	s_nop 0
	global_load_lds_dwordx4 v160, s[50:51]
	s_mov_b32 m0, s25
	s_nop 0
	global_load_lds_dwordx4 v154, s[20:21]
	s_mov_b32 m0, s26
	s_nop 0
	global_load_lds_dwordx4 v158, s[20:21]
	s_waitcnt vmcnt(8)
	s_waitcnt lgkmcnt(0)
	s_barrier
	s_waitcnt lgkmcnt(0)
	v_mfma_f32_16x16x32_bf16 v[58:61], v[130:133], v[178:181], v[58:61]
	v_mfma_f32_16x16x32_bf16 v[58:61], v[134:137], v[186:189], v[58:61]
	v_mfma_f32_16x16x32_bf16 v[54:57], v[138:141], v[178:181], v[54:57]
	v_mfma_f32_16x16x32_bf16 v[54:57], v[142:145], v[186:189], v[54:57]
	v_mfma_f32_16x16x32_bf16 v[42:45], v[130:133], v[190:193], v[42:45]
	v_mfma_f32_16x16x32_bf16 v[42:45], v[134:137], v[194:197], v[42:45]
	v_mfma_f32_16x16x32_bf16 v[34:37], v[138:141], v[190:193], v[34:37]
	v_mfma_f32_16x16x32_bf16 v[34:37], v[142:145], v[194:197], v[34:37]
	v_mfma_f32_16x16x32_bf16 v[26:29], v[130:133], v[198:201], v[26:29]
	v_mfma_f32_16x16x32_bf16 v[26:29], v[134:137], v[202:205], v[26:29]
	v_mfma_f32_16x16x32_bf16 v[18:21], v[138:141], v[198:201], v[18:21]
	v_mfma_f32_16x16x32_bf16 v[18:21], v[142:145], v[202:205], v[18:21]
	v_mfma_f32_16x16x32_bf16 v[6:9], v[130:133], v[206:209], v[6:9]
	v_mfma_f32_16x16x32_bf16 v[6:9], v[134:137], v[210:213], v[6:9]
	v_mfma_f32_16x16x32_bf16 v[2:5], v[138:141], v[206:209], v[2:5]
	v_mfma_f32_16x16x32_bf16 v[2:5], v[142:145], v[210:213], v[2:5]
	v_mfma_f32_16x16x32_bf16 v[62:65], v[146:149], v[178:181], v[62:65]
	v_mfma_f32_16x16x32_bf16 v[62:65], v[150:153], v[186:189], v[62:65]
	v_mfma_f32_16x16x32_bf16 v[50:53], v[170:173], v[178:181], v[50:53]
	v_mfma_f32_16x16x32_bf16 v[50:53], v[174:177], v[186:189], v[50:53]
	v_mfma_f32_16x16x32_bf16 v[46:49], v[146:149], v[190:193], v[46:49]
	v_mfma_f32_16x16x32_bf16 v[46:49], v[150:153], v[194:197], v[46:49]
	v_mfma_f32_16x16x32_bf16 v[38:41], v[170:173], v[190:193], v[38:41]
	v_mfma_f32_16x16x32_bf16 v[38:41], v[174:177], v[194:197], v[38:41]
	v_mfma_f32_16x16x32_bf16 v[30:33], v[146:149], v[198:201], v[30:33]
	v_mfma_f32_16x16x32_bf16 v[30:33], v[150:153], v[202:205], v[30:33]
	v_mfma_f32_16x16x32_bf16 v[22:25], v[170:173], v[198:201], v[22:25]
	v_mfma_f32_16x16x32_bf16 v[22:25], v[174:177], v[202:205], v[22:25]
	v_mfma_f32_16x16x32_bf16 v[10:13], v[146:149], v[206:209], v[10:13]
	v_mfma_f32_16x16x32_bf16 v[10:13], v[150:153], v[210:213], v[10:13]
	v_mfma_f32_16x16x32_bf16 v[14:17], v[170:173], v[206:209], v[14:17]
	v_mfma_f32_16x16x32_bf16 v[14:17], v[174:177], v[210:213], v[14:17]
	s_barrier
; #define PG8_STAGE(bufoff, gbase, voff) do { _Pragma("unroll") for (int _i = 0; _i < 2; ++_i) \
;         __builtin_amdgcn_global_load_lds((const unsigned*)((const char*)(gbase) + (voff)[_i]), (PG8_LAS unsigned*)(lds + (bufoff) + ldsw + _i * 8192), 16, 0, 0); } while (0)
; #define PG8_LDA(dst, b, h) do { _Pragma("unroll") for (int m = 0; m < 4; ++m) _Pragma("unroll") for (int k = 0; k < 2; ++k) dst[m][k] = *(const PG8_LAS bf16x8*)(lds + PG8_SA(b, h) + aoff + m * 2048 + k * 1024); } while (0)
; #define PG8_LDB(dst, b, h) do { _Pragma("unroll") for (int n = 0; n < 2; ++n) _Pragma("unroll") for (int k = 0; k < 2; ++k) dst[n][k] = *(const PG8_LAS bf16x8*)(lds + PG8_SB(b, h) + boff + n * 2048 + k * 1024); } while (0)
; #define PG8_MMA(ai, bj, At, Bt) do { __builtin_amdgcn_s_setprio(1); _Pragma("unroll") for (int m = 0; m < 4; ++m) _Pragma("unroll") for (int n = 0; n < 2; ++n) _Pragma("unroll") for (int k = 0; k < 2; ++k) \
;         acc[ai][bj][m][n] = __builtin_amdgcn_mfma_f32_16x16x32_bf16(Bt[n][k], At[m][k], acc[ai][bj][m][n], 0, 0, 0); __builtin_amdgcn_s_setprio(0); } while (0)
; #define PG8_WAIT_V(n) asm volatile("s_waitcnt vmcnt(" #n ")" ::: "memory")
; #define PG8_WAIT_L(n) asm volatile("s_waitcnt lgkmcnt(" #n ")" ::: "memory")
; #define PG8_BAR __builtin_amdgcn_s_barrier()
; #define PG8_SCHED __builtin_amdgcn_sched_barrier(0)
; template <class Epi, class Sched, bool ALIGN_EPI = false, bool SP2 = false>
; __device__ __forceinline__ void gemm_phase(PG8_LAS unsigned char* lds, const Gemm g, const Sched& S, const Epi& E) {
;     ...
;             PG8_LDB(B0, 1, 0); PG8_LDB(B1, 1, 1); PG8_SCHED; PG8_LDA(At, 1, 0); PG8_STAGE(PG8_SA(0, 1), a2 + hstep, voffA);
;             PG8_WAIT_V(8); PG8_WAIT_L(0); PG8_BAR; PG8_MMA(0, 0, At, B0); PG8_MMA(0, 1, At, B1); PG8_BAR; PG8_SCHED;
;             PG8_LDA(At, 1, 1); PG8_STAGE(PG8_SB(1, 0), b3, voffB); PG8_STAGE(PG8_SB(1, 1), b3 + hstep, voffB); PG8_STAGE(PG8_SA(1, 0), a3, voffA);
;             PG8_WAIT_V(8); PG8_WAIT_L(0); PG8_BAR; PG8_MMA(1, 0, At, B0); PG8_MMA(1, 1, At, B1); PG8_BAR; PG8_SCHED;
	s_add_i32 s33, 0, 0x18000
	s_add_i32 s42, 0, 0x1c000
	ds_read_b128 v[130:133], v241 offset:32768
	ds_read_b128 v[134:137], v241 offset:33792
	ds_read_b128 v[138:141], v241 offset:34816
	ds_read_b128 v[142:145], v241 offset:35840
	ds_read_b128 v[146:149], v241 offset:49152
	ds_read_b128 v[150:153], v241 offset:50176
	ds_read_b128 v[170:173], v241 offset:51200
	ds_read_b128 v[174:177], v241 offset:52224
	s_add_u32 s20, s20, 0x2b0000
	s_addc_u32 s21, s21, 0
	s_mov_b32 m0, s27
	ds_read_b128 v[178:181], v184 offset:32768
	ds_read_b128 v[186:189], v184 offset:33792
	ds_read_b128 v[190:193], v184 offset:34816
	ds_read_b128 v[194:197], v184 offset:35840
	ds_read_b128 v[198:201], v184 offset:36864
	ds_read_b128 v[202:205], v184 offset:37888
	ds_read_b128 v[206:209], v184 offset:38912
	ds_read_b128 v[210:213], v184 offset:39936
	global_load_lds_dwordx4 v154, s[20:21]
	s_mov_b32 m0, s28
	s_nop 0
	global_load_lds_dwordx4 v158, s[20:21]
	s_waitcnt vmcnt(8)
	s_waitcnt lgkmcnt(0)
	s_barrier
	s_waitcnt lgkmcnt(0)
	v_mfma_f32_16x16x32_bf16 v[114:117], v[130:133], v[178:181], v[114:117]
	v_mfma_f32_16x16x32_bf16 v[114:117], v[134:137], v[186:189], v[114:117]
	v_mfma_f32_16x16x32_bf16 v[118:121], v[138:141], v[178:181], v[118:121]
	v_mfma_f32_16x16x32_bf16 v[118:121], v[142:145], v[186:189], v[118:121]
	v_mfma_f32_16x16x32_bf16 v[106:109], v[130:133], v[190:193], v[106:109]
	v_mfma_f32_16x16x32_bf16 v[106:109], v[134:137], v[194:197], v[106:109]
	v_mfma_f32_16x16x32_bf16 v[98:101], v[138:141], v[190:193], v[98:101]
	v_mfma_f32_16x16x32_bf16 v[98:101], v[142:145], v[194:197], v[98:101]
	v_mfma_f32_16x16x32_bf16 v[90:93], v[130:133], v[198:201], v[90:93]
	v_mfma_f32_16x16x32_bf16 v[90:93], v[134:137], v[202:205], v[90:93]
	v_mfma_f32_16x16x32_bf16 v[82:85], v[138:141], v[198:201], v[82:85]
	v_mfma_f32_16x16x32_bf16 v[82:85], v[142:145], v[202:205], v[82:85]
	v_mfma_f32_16x16x32_bf16 v[74:77], v[130:133], v[206:209], v[74:77]
	v_mfma_f32_16x16x32_bf16 v[74:77], v[134:137], v[210:213], v[74:77]
	v_mfma_f32_16x16x32_bf16 v[66:69], v[138:141], v[206:209], v[66:69]
	v_mfma_f32_16x16x32_bf16 v[66:69], v[142:145], v[210:213], v[66:69]
	v_mfma_f32_16x16x32_bf16 v[122:125], v[146:149], v[178:181], v[122:125]
	v_mfma_f32_16x16x32_bf16 v[122:125], v[150:153], v[186:189], v[122:125]
	v_mfma_f32_16x16x32_bf16 v[126:129], v[170:173], v[178:181], v[126:129]
	v_mfma_f32_16x16x32_bf16 v[126:129], v[174:177], v[186:189], v[126:129]
	v_mfma_f32_16x16x32_bf16 v[110:113], v[146:149], v[190:193], v[110:113]
	v_mfma_f32_16x16x32_bf16 v[110:113], v[150:153], v[194:197], v[110:113]
	v_mfma_f32_16x16x32_bf16 v[102:105], v[170:173], v[190:193], v[102:105]
	v_mfma_f32_16x16x32_bf16 v[102:105], v[174:177], v[194:197], v[102:105]
	v_mfma_f32_16x16x32_bf16 v[94:97], v[146:149], v[198:201], v[94:97]
	v_mfma_f32_16x16x32_bf16 v[94:97], v[150:153], v[202:205], v[94:97]
	v_mfma_f32_16x16x32_bf16 v[86:89], v[170:173], v[198:201], v[86:89]
	v_mfma_f32_16x16x32_bf16 v[86:89], v[174:177], v[202:205], v[86:89]
	v_mfma_f32_16x16x32_bf16 v[78:81], v[146:149], v[206:209], v[78:81]
	v_mfma_f32_16x16x32_bf16 v[78:81], v[150:153], v[210:213], v[78:81]
	v_mfma_f32_16x16x32_bf16 v[70:73], v[170:173], v[206:209], v[70:73]
	v_mfma_f32_16x16x32_bf16 v[70:73], v[174:177], v[210:213], v[70:73]
	s_barrier
	s_add_i32 s20, s33, s24
	s_add_i32 m0, s20, 0xffffff80
	ds_read_b128 v[178:181], v184 offset:49152
	ds_read_b128 v[186:189], v184 offset:50176
	ds_read_b128 v[190:193], v184 offset:51200
	ds_read_b128 v[194:197], v184 offset:52224
	ds_read_b128 v[198:201], v184 offset:53248
	ds_read_b128 v[202:205], v184 offset:54272
	ds_read_b128 v[206:209], v184 offset:55296
	ds_read_b128 v[210:213], v184 offset:56320
	global_load_lds_dwordx4 v156, s[16:17] offset:128
	s_add_i32 m0, s20, 0x1f80
	s_add_i32 s20, s42, s24
	global_load_lds_dwordx4 v160, s[16:17] offset:128
	s_add_u32 s16, s16, 0x2b0080
	s_addc_u32 s17, s17, 0
	s_mov_b32 m0, s20
	s_nop 0
	global_load_lds_dwordx4 v156, s[16:17]
	s_add_i32 m0, s20, 0x2000
	s_nop 0
	global_load_lds_dwordx4 v160, s[16:17]
	s_mov_b32 m0, s30
	s_nop 0
	global_load_lds_dwordx4 v154, s[100:101]
	s_mov_b32 m0, s31
	s_nop 0
	global_load_lds_dwordx4 v158, s[100:101]
	s_waitcnt vmcnt(8)
	s_waitcnt lgkmcnt(0)
	s_barrier
	s_waitcnt lgkmcnt(0)
	v_mfma_f32_16x16x32_bf16 v[58:61], v[130:133], v[178:181], v[58:61]
	v_mfma_f32_16x16x32_bf16 v[58:61], v[134:137], v[186:189], v[58:61]
	v_mfma_f32_16x16x32_bf16 v[54:57], v[138:141], v[178:181], v[54:57]
	v_mfma_f32_16x16x32_bf16 v[54:57], v[142:145], v[186:189], v[54:57]
	v_mfma_f32_16x16x32_bf16 v[42:45], v[130:133], v[190:193], v[42:45]
	v_mfma_f32_16x16x32_bf16 v[42:45], v[134:137], v[194:197], v[42:45]
	v_mfma_f32_16x16x32_bf16 v[34:37], v[138:141], v[190:193], v[34:37]
	v_mfma_f32_16x16x32_bf16 v[34:37], v[142:145], v[194:197], v[34:37]
	v_mfma_f32_16x16x32_bf16 v[26:29], v[130:133], v[198:201], v[26:29]
	v_mfma_f32_16x16x32_bf16 v[26:29], v[134:137], v[202:205], v[26:29]
	v_mfma_f32_16x16x32_bf16 v[18:21], v[138:141], v[198:201], v[18:21]
	v_mfma_f32_16x16x32_bf16 v[18:21], v[142:145], v[202:205], v[18:21]
	v_mfma_f32_16x16x32_bf16 v[6:9], v[130:133], v[206:209], v[6:9]
	v_mfma_f32_16x16x32_bf16 v[6:9], v[134:137], v[210:213], v[6:9]
	v_mfma_f32_16x16x32_bf16 v[2:5], v[138:141], v[206:209], v[2:5]
	v_mfma_f32_16x16x32_bf16 v[2:5], v[142:145], v[210:213], v[2:5]
	v_mfma_f32_16x16x32_bf16 v[62:65], v[146:149], v[178:181], v[62:65]
	v_mfma_f32_16x16x32_bf16 v[62:65], v[150:153], v[186:189], v[62:65]
	v_mfma_f32_16x16x32_bf16 v[50:53], v[170:173], v[178:181], v[50:53]
	v_mfma_f32_16x16x32_bf16 v[50:53], v[174:177], v[186:189], v[50:53]
	v_mfma_f32_16x16x32_bf16 v[46:49], v[146:149], v[190:193], v[46:49]
	v_mfma_f32_16x16x32_bf16 v[46:49], v[150:153], v[194:197], v[46:49]
	v_mfma_f32_16x16x32_bf16 v[38:41], v[170:173], v[190:193], v[38:41]
	v_mfma_f32_16x16x32_bf16 v[38:41], v[174:177], v[194:197], v[38:41]
	v_mfma_f32_16x16x32_bf16 v[30:33], v[146:149], v[198:201], v[30:33]
	v_mfma_f32_16x16x32_bf16 v[30:33], v[150:153], v[202:205], v[30:33]
	v_mfma_f32_16x16x32_bf16 v[22:25], v[170:173], v[198:201], v[22:25]
	v_mfma_f32_16x16x32_bf16 v[22:25], v[174:177], v[202:205], v[22:25]
	v_mfma_f32_16x16x32_bf16 v[10:13], v[146:149], v[206:209], v[10:13]
	v_mfma_f32_16x16x32_bf16 v[10:13], v[150:153], v[210:213], v[10:13]
	v_mfma_f32_16x16x32_bf16 v[14:17], v[170:173], v[206:209], v[14:17]
	v_mfma_f32_16x16x32_bf16 v[14:17], v[174:177], v[210:213], v[14:17]
	s_barrier
	s_add_i32 s48, s48, 2
	s_add_u32 s18, s18, 0x100
	s_addc_u32 s19, s19, 0
	s_add_u32 s46, s46, 0x100
	s_addc_u32 s47, s47, 0
	s_cmpk_gt_u32 s48, 0xa9
	s_cbranch_scc0 .LBB0_1801
	s_and_b64 vcc, exec, s[12:13]
	s_cbranch_vccz .LBB0_1804
	s_barrier
